# indexer scoring software-pipelined: MFMA of tile t issued before VALU of tile t-1 on alternating accumulators, exit blocks + zero-fill ladder instead of per-tile skip checks, WG-shared DMA ring
# speedup vs baseline: 1.0105x; 1.0105x over previous
.LBB0_401:
	s_or_b64 exec, exec, s[80:81]
	v_lshlrev_b32_e32 v174, 16, v2
	s_waitcnt vmcnt(0)
	v_lshlrev_b32_e32 v166, 16, v10
	v_and_b32_e32 v173, 0xffff0000, v2
	v_and_b32_e32 v165, 0xffff0000, v10
	v_lshlrev_b32_e32 v172, 16, v3
	v_lshlrev_b32_e32 v164, 16, v11
	v_and_b32_e32 v171, 0xffff0000, v3
	v_and_b32_e32 v163, 0xffff0000, v11
	v_lshlrev_b32_e32 v170, 16, v4
	v_lshlrev_b32_e32 v162, 16, v12
	v_and_b32_e32 v169, 0xffff0000, v4
	v_and_b32_e32 v161, 0xffff0000, v12
	v_lshlrev_b32_e32 v168, 16, v5
	v_lshlrev_b32_e32 v160, 16, v13
	v_and_b32_e32 v167, 0xffff0000, v5
	v_and_b32_e32 v89, 0xffff0000, v13
	v_mfma_f32_32x32x16_bf16 v[2:17], v[38:41], v[6:9], 0
	v_or_b32_e32 v87, v177, v94
	v_mov_b32_e32 v175, 0
	v_mfma_f32_32x32x16_bf16 v[2:17], v[46:49], v[26:29], v[2:17]
	v_mfma_f32_32x32x16_bf16 v[2:17], v[34:37], v[18:21], v[2:17]
	v_mfma_f32_32x32x16_bf16 v[2:17], v[42:45], v[22:25], v[2:17]
	s_and_saveexec_b64 s[80:81], s[74:75]
	s_cbranch_execz .Lidxp_e1
	s_waitcnt lgkmcnt(0)
	s_waitcnt vmcnt(0)
	s_barrier
	v_mfma_f32_32x32x16_bf16 v[18:33], v[38:41], v[58:61], 0
	v_mfma_f32_32x32x16_bf16 v[18:33], v[46:49], v[54:57], v[18:33]
	v_mfma_f32_32x32x16_bf16 v[18:33], v[34:37], v[50:53], v[18:33]
	v_mfma_f32_32x32x16_bf16 v[18:33], v[42:45], v[62:65], v[18:33]
	ds_read_b128 v[58:61], v74 offset:0
	ds_read_b128 v[54:57], v75 offset:0
	ds_read_b128 v[50:53], v76 offset:0
	ds_read_b128 v[62:65], v77 offset:0
	v_max_f32_e32 v2, 0, v2
	v_fma_f32 v2, v174, v2, 0
	v_max_f32_e32 v3, 0, v3
	v_fmac_f32_e32 v2, v173, v3
	v_max_f32_e32 v3, 0, v4
	v_fmac_f32_e32 v2, v172, v3
	v_max_f32_e32 v3, 0, v5
	v_fmac_f32_e32 v2, v171, v3
	v_max_f32_e32 v3, 0, v6
	v_fmac_f32_e32 v2, v170, v3
	v_max_f32_e32 v3, 0, v7
	v_fmac_f32_e32 v2, v169, v3
	v_max_f32_e32 v3, 0, v8
	v_fmac_f32_e32 v2, v168, v3
	v_max_f32_e32 v3, 0, v9
	v_fmac_f32_e32 v2, v167, v3
	v_max_f32_e32 v3, 0, v10
	v_fmac_f32_e32 v2, v166, v3
	v_max_f32_e32 v3, 0, v11
	v_fmac_f32_e32 v2, v165, v3
	v_max_f32_e32 v3, 0, v12
	v_fmac_f32_e32 v2, v164, v3
	v_max_f32_e32 v3, 0, v13
	v_fmac_f32_e32 v2, v163, v3
	v_max_f32_e32 v3, 0, v14
	v_fmac_f32_e32 v2, v162, v3
	v_max_f32_e32 v3, 0, v15
	v_fmac_f32_e32 v2, v161, v3
	v_max_f32_e32 v3, 0, v16
	v_fmac_f32_e32 v2, v160, v3
	v_max_f32_e32 v3, 0, v17
	v_fmac_f32_e32 v2, v89, v3
	v_not_b32_e32 v3, v2
	v_or_b32_e32 v4, 0x80000000, v2
	v_cmp_gt_i32_e32 vcc, 0, v2
	s_nop 1
	v_cndmask_b32_e32 v2, v4, v3, vcc
	v_cmp_le_u32_e32 vcc, v93, v87
	s_nop 1
	v_cndmask_b32_e32 v81, 0, v2, vcc
.LBB0_405:
	s_or_b64 exec, exec, s[80:81]
	s_xor_b64 s[80:81], s[82:83], -1
	v_cmp_lt_u32_e32 vcc, 63, v177
	v_mov_b32_e32 v176, 0
	s_and_saveexec_b64 s[74:75], vcc
	s_cbranch_execz .Lidxp_e2
	s_waitcnt lgkmcnt(0)
	v_mfma_f32_32x32x16_bf16 v[2:17], v[38:41], v[58:61], 0
	v_max_f32_e32 v18, 0, v18
	v_max_f32_e32 v19, 0, v19
	v_fma_f32 v18, v174, v18, 0
	v_max_f32_e32 v20, 0, v20
	v_fmac_f32_e32 v18, v173, v19
	v_max_f32_e32 v21, 0, v21
	v_fmac_f32_e32 v18, v172, v20
	v_max_f32_e32 v22, 0, v22
	v_fmac_f32_e32 v18, v171, v21
	v_max_f32_e32 v23, 0, v23
	v_mfma_f32_32x32x16_bf16 v[2:17], v[46:49], v[54:57], v[2:17]
	v_fmac_f32_e32 v18, v170, v22
	v_max_f32_e32 v24, 0, v24
	v_fmac_f32_e32 v18, v169, v23
	v_max_f32_e32 v25, 0, v25
	v_fmac_f32_e32 v18, v168, v24
	v_max_f32_e32 v26, 0, v26
	v_fmac_f32_e32 v18, v167, v25
	v_max_f32_e32 v27, 0, v27
	v_fmac_f32_e32 v18, v166, v26
	v_max_f32_e32 v28, 0, v28
	v_mfma_f32_32x32x16_bf16 v[2:17], v[34:37], v[50:53], v[2:17]
	v_fmac_f32_e32 v18, v165, v27
	v_max_f32_e32 v29, 0, v29
	v_fmac_f32_e32 v18, v164, v28
	v_max_f32_e32 v30, 0, v30
	v_fmac_f32_e32 v18, v163, v29
	v_fmac_f32_e32 v18, v162, v30
	v_max_f32_e32 v19, 0, v31
	v_fmac_f32_e32 v18, v161, v19
	v_max_f32_e32 v19, 0, v32
	v_fmac_f32_e32 v18, v160, v19
	v_mfma_f32_32x32x16_bf16 v[2:17], v[42:45], v[62:65], v[2:17]
	ds_read_b128 v[58:61], v74 offset:4096
	ds_read_b128 v[54:57], v75 offset:4096
	ds_read_b128 v[50:53], v76 offset:4096
	ds_read_b128 v[62:65], v77 offset:4096
	v_max_f32_e32 v19, 0, v33
	v_fmac_f32_e32 v18, v89, v19
	v_not_b32_e32 v19, v18
	v_or_b32_e32 v20, 0x80000000, v18
	v_cmp_gt_i32_e32 vcc, 0, v18
	s_nop 1
	v_cndmask_b32_e32 v18, v20, v19, vcc
	v_cmp_le_u32_e32 vcc, v96, v87
	s_nop 1
	v_cndmask_b32_e32 v175, 0, v18, vcc
.LBB0_409:
	s_or_b64 exec, exec, s[74:75]
	s_movk_i32 s2, 0x5f
	v_cmp_lt_u32_e32 vcc, s2, v177
	v_mov_b32_e32 v179, 0
	s_and_saveexec_b64 s[74:75], vcc
	s_cbranch_execz .Lidxp_e3
	s_waitcnt lgkmcnt(0)
	v_mfma_f32_32x32x16_bf16 v[18:33], v[38:41], v[58:61], 0
	v_max_f32_e32 v2, 0, v2
	v_max_f32_e32 v3, 0, v3
	v_fma_f32 v2, v174, v2, 0
	v_max_f32_e32 v4, 0, v4
	v_fmac_f32_e32 v2, v173, v3
	v_max_f32_e32 v5, 0, v5
	v_fmac_f32_e32 v2, v172, v4
	v_max_f32_e32 v6, 0, v6
	v_fmac_f32_e32 v2, v171, v5
	v_max_f32_e32 v7, 0, v7
	v_mfma_f32_32x32x16_bf16 v[18:33], v[46:49], v[54:57], v[18:33]
	v_fmac_f32_e32 v2, v170, v6
	v_max_f32_e32 v8, 0, v8
	v_fmac_f32_e32 v2, v169, v7
	v_max_f32_e32 v9, 0, v9
	v_fmac_f32_e32 v2, v168, v8
	v_max_f32_e32 v10, 0, v10
	v_fmac_f32_e32 v2, v167, v9
	v_max_f32_e32 v11, 0, v11
	v_fmac_f32_e32 v2, v166, v10
	v_max_f32_e32 v12, 0, v12
	v_mfma_f32_32x32x16_bf16 v[18:33], v[34:37], v[50:53], v[18:33]
	v_fmac_f32_e32 v2, v165, v11
	v_max_f32_e32 v13, 0, v13
	v_fmac_f32_e32 v2, v164, v12
	v_max_f32_e32 v14, 0, v14
	v_fmac_f32_e32 v2, v163, v13
	v_fmac_f32_e32 v2, v162, v14
	v_max_f32_e32 v3, 0, v15
	v_fmac_f32_e32 v2, v161, v3
	v_max_f32_e32 v3, 0, v16
	v_fmac_f32_e32 v2, v160, v3
	v_mfma_f32_32x32x16_bf16 v[18:33], v[42:45], v[62:65], v[18:33]
	ds_read_b128 v[58:61], v74 offset:8192
	ds_read_b128 v[54:57], v75 offset:8192
	ds_read_b128 v[50:53], v76 offset:8192
	ds_read_b128 v[62:65], v77 offset:8192
	v_max_f32_e32 v3, 0, v17
	v_fmac_f32_e32 v2, v89, v3
	v_not_b32_e32 v3, v2
	v_or_b32_e32 v4, 0x80000000, v2
	v_cmp_gt_i32_e32 vcc, 0, v2
	s_nop 1
	v_cndmask_b32_e32 v2, v4, v3, vcc
	v_cmp_le_u32_e32 vcc, v97, v87
	s_nop 1
	v_cndmask_b32_e32 v176, 0, v2, vcc
.LBB0_413:
	s_or_b64 exec, exec, s[74:75]
	s_movk_i32 s2, 0x7f
	v_cmp_lt_u32_e32 vcc, s2, v177
	v_mov_b32_e32 v180, 0
	s_and_saveexec_b64 s[74:75], vcc
	s_cbranch_execz .Lidxp_e4
	s_waitcnt lgkmcnt(0)
	v_mfma_f32_32x32x16_bf16 v[2:17], v[38:41], v[58:61], 0
	v_max_f32_e32 v18, 0, v18
	v_max_f32_e32 v19, 0, v19
	v_fma_f32 v18, v174, v18, 0
	v_max_f32_e32 v20, 0, v20
	v_fmac_f32_e32 v18, v173, v19
	v_max_f32_e32 v21, 0, v21
	v_fmac_f32_e32 v18, v172, v20
	v_max_f32_e32 v22, 0, v22
	v_fmac_f32_e32 v18, v171, v21
	v_max_f32_e32 v23, 0, v23
	v_mfma_f32_32x32x16_bf16 v[2:17], v[46:49], v[54:57], v[2:17]
	v_fmac_f32_e32 v18, v170, v22
	v_max_f32_e32 v24, 0, v24
	v_fmac_f32_e32 v18, v169, v23
	v_max_f32_e32 v25, 0, v25
	v_fmac_f32_e32 v18, v168, v24
	v_max_f32_e32 v26, 0, v26
	v_fmac_f32_e32 v18, v167, v25
	v_max_f32_e32 v27, 0, v27
	v_fmac_f32_e32 v18, v166, v26
	v_max_f32_e32 v28, 0, v28
	v_mfma_f32_32x32x16_bf16 v[2:17], v[34:37], v[50:53], v[2:17]
	v_fmac_f32_e32 v18, v165, v27
	v_max_f32_e32 v29, 0, v29
	v_fmac_f32_e32 v18, v164, v28
	v_max_f32_e32 v30, 0, v30
	v_fmac_f32_e32 v18, v163, v29
	v_fmac_f32_e32 v18, v162, v30
	v_max_f32_e32 v19, 0, v31
	v_fmac_f32_e32 v18, v161, v19
	v_max_f32_e32 v19, 0, v32
	v_fmac_f32_e32 v18, v160, v19
	v_mfma_f32_32x32x16_bf16 v[2:17], v[42:45], v[62:65], v[2:17]
	ds_read_b128 v[58:61], v74 offset:12288
	ds_read_b128 v[54:57], v75 offset:12288
	ds_read_b128 v[50:53], v76 offset:12288
	ds_read_b128 v[62:65], v77 offset:12288
	v_max_f32_e32 v19, 0, v33
	v_fmac_f32_e32 v18, v89, v19
	v_not_b32_e32 v19, v18
	v_or_b32_e32 v20, 0x80000000, v18
	v_cmp_gt_i32_e32 vcc, 0, v18
	s_nop 1
	v_cndmask_b32_e32 v18, v20, v19, vcc
	v_cmp_le_u32_e32 vcc, v98, v87
	s_nop 1
	v_cndmask_b32_e32 v179, 0, v18, vcc
.LBB0_417:
	s_or_b64 exec, exec, s[74:75]
	s_movk_i32 s2, 0x9f
	v_cmp_lt_u32_e32 vcc, s2, v177
	v_mov_b32_e32 v181, 0
	s_and_saveexec_b64 s[74:75], vcc
	s_cbranch_execz .Lidxp_e5
	s_waitcnt lgkmcnt(0)
	v_mfma_f32_32x32x16_bf16 v[18:33], v[38:41], v[58:61], 0
	v_max_f32_e32 v2, 0, v2
	v_max_f32_e32 v3, 0, v3
	v_fma_f32 v2, v174, v2, 0
	v_max_f32_e32 v4, 0, v4
	v_fmac_f32_e32 v2, v173, v3
	v_max_f32_e32 v5, 0, v5
	v_fmac_f32_e32 v2, v172, v4
	v_max_f32_e32 v6, 0, v6
	v_fmac_f32_e32 v2, v171, v5
	v_max_f32_e32 v7, 0, v7
	v_mfma_f32_32x32x16_bf16 v[18:33], v[46:49], v[54:57], v[18:33]
	v_fmac_f32_e32 v2, v170, v6
	v_max_f32_e32 v8, 0, v8
	v_fmac_f32_e32 v2, v169, v7
	v_max_f32_e32 v9, 0, v9
	v_fmac_f32_e32 v2, v168, v8
	v_max_f32_e32 v10, 0, v10
	v_fmac_f32_e32 v2, v167, v9
	v_max_f32_e32 v11, 0, v11
	v_fmac_f32_e32 v2, v166, v10
	v_max_f32_e32 v12, 0, v12
	v_mfma_f32_32x32x16_bf16 v[18:33], v[34:37], v[50:53], v[18:33]
	v_fmac_f32_e32 v2, v165, v11
	v_max_f32_e32 v13, 0, v13
	v_fmac_f32_e32 v2, v164, v12
	v_max_f32_e32 v14, 0, v14
	v_fmac_f32_e32 v2, v163, v13
	v_fmac_f32_e32 v2, v162, v14
	v_max_f32_e32 v3, 0, v15
	v_fmac_f32_e32 v2, v161, v3
	v_max_f32_e32 v3, 0, v16
	v_fmac_f32_e32 v2, v160, v3
	v_mfma_f32_32x32x16_bf16 v[18:33], v[42:45], v[62:65], v[18:33]
	ds_read_b128 v[58:61], v74 offset:16384
	ds_read_b128 v[54:57], v75 offset:16384
	ds_read_b128 v[50:53], v76 offset:16384
	ds_read_b128 v[62:65], v77 offset:16384
	v_max_f32_e32 v3, 0, v17
	v_fmac_f32_e32 v2, v89, v3
	v_not_b32_e32 v3, v2
	v_or_b32_e32 v4, 0x80000000, v2
	v_cmp_gt_i32_e32 vcc, 0, v2
	s_nop 1
	v_cndmask_b32_e32 v2, v4, v3, vcc
	v_cmp_le_u32_e32 vcc, v99, v87
	s_nop 1
	v_cndmask_b32_e32 v180, 0, v2, vcc
.LBB0_421:
	s_or_b64 exec, exec, s[74:75]
	s_movk_i32 s2, 0xbf
	v_cmp_lt_u32_e32 vcc, s2, v177
	v_mov_b32_e32 v182, 0
	s_and_saveexec_b64 s[74:75], vcc
	s_cbranch_execz .Lidxp_e6
	s_waitcnt lgkmcnt(0)
	v_mfma_f32_32x32x16_bf16 v[2:17], v[38:41], v[58:61], 0
	v_max_f32_e32 v18, 0, v18
	v_max_f32_e32 v19, 0, v19
	v_fma_f32 v18, v174, v18, 0
	v_max_f32_e32 v20, 0, v20
	v_fmac_f32_e32 v18, v173, v19
	v_max_f32_e32 v21, 0, v21
	v_fmac_f32_e32 v18, v172, v20
	v_max_f32_e32 v22, 0, v22
	v_fmac_f32_e32 v18, v171, v21
	v_max_f32_e32 v23, 0, v23
	v_mfma_f32_32x32x16_bf16 v[2:17], v[46:49], v[54:57], v[2:17]
	v_fmac_f32_e32 v18, v170, v22
	v_max_f32_e32 v24, 0, v24
	v_fmac_f32_e32 v18, v169, v23
	v_max_f32_e32 v25, 0, v25
	v_fmac_f32_e32 v18, v168, v24
	v_max_f32_e32 v26, 0, v26
	v_fmac_f32_e32 v18, v167, v25
	v_max_f32_e32 v27, 0, v27
	v_fmac_f32_e32 v18, v166, v26
	v_max_f32_e32 v28, 0, v28
	v_mfma_f32_32x32x16_bf16 v[2:17], v[34:37], v[50:53], v[2:17]
	v_fmac_f32_e32 v18, v165, v27
	v_max_f32_e32 v29, 0, v29
	v_fmac_f32_e32 v18, v164, v28
	v_max_f32_e32 v30, 0, v30
	v_fmac_f32_e32 v18, v163, v29
	v_fmac_f32_e32 v18, v162, v30
	v_max_f32_e32 v19, 0, v31
	v_fmac_f32_e32 v18, v161, v19
	v_max_f32_e32 v19, 0, v32
	v_fmac_f32_e32 v18, v160, v19
	v_mfma_f32_32x32x16_bf16 v[2:17], v[42:45], v[62:65], v[2:17]
	ds_read_b128 v[58:61], v74 offset:20480
	ds_read_b128 v[54:57], v75 offset:20480
	ds_read_b128 v[50:53], v76 offset:20480
	ds_read_b128 v[62:65], v77 offset:20480
	v_max_f32_e32 v19, 0, v33
	v_fmac_f32_e32 v18, v89, v19
	v_not_b32_e32 v19, v18
	v_or_b32_e32 v20, 0x80000000, v18
	v_cmp_gt_i32_e32 vcc, 0, v18
	s_nop 1
	v_cndmask_b32_e32 v18, v20, v19, vcc
	v_cmp_le_u32_e32 vcc, v100, v87
	s_nop 1
	v_cndmask_b32_e32 v181, 0, v18, vcc
.LBB0_425:
	s_or_b64 exec, exec, s[74:75]
	s_movk_i32 s2, 0xdf
	v_cmp_lt_u32_e32 vcc, s2, v177
	v_mov_b32_e32 v183, 0
	s_and_saveexec_b64 s[74:75], vcc
	s_cbranch_execz .Lidxp_e7
	s_waitcnt lgkmcnt(0)
	v_mfma_f32_32x32x16_bf16 v[18:33], v[38:41], v[58:61], 0
	v_max_f32_e32 v2, 0, v2
	v_max_f32_e32 v3, 0, v3
	v_fma_f32 v2, v174, v2, 0
	v_max_f32_e32 v4, 0, v4
	v_fmac_f32_e32 v2, v173, v3
	v_max_f32_e32 v5, 0, v5
	v_fmac_f32_e32 v2, v172, v4
	v_max_f32_e32 v6, 0, v6
	v_fmac_f32_e32 v2, v171, v5
	v_max_f32_e32 v7, 0, v7
	v_mfma_f32_32x32x16_bf16 v[18:33], v[46:49], v[54:57], v[18:33]
	v_fmac_f32_e32 v2, v170, v6
	v_max_f32_e32 v8, 0, v8
	v_fmac_f32_e32 v2, v169, v7
	v_max_f32_e32 v9, 0, v9
	v_fmac_f32_e32 v2, v168, v8
	v_max_f32_e32 v10, 0, v10
	v_fmac_f32_e32 v2, v167, v9
	v_max_f32_e32 v11, 0, v11
	v_fmac_f32_e32 v2, v166, v10
	v_max_f32_e32 v12, 0, v12
	v_mfma_f32_32x32x16_bf16 v[18:33], v[34:37], v[50:53], v[18:33]
	v_fmac_f32_e32 v2, v165, v11
	v_max_f32_e32 v13, 0, v13
	v_fmac_f32_e32 v2, v164, v12
	v_max_f32_e32 v14, 0, v14
	v_fmac_f32_e32 v2, v163, v13
	v_fmac_f32_e32 v2, v162, v14
	v_max_f32_e32 v3, 0, v15
	v_fmac_f32_e32 v2, v161, v3
	v_max_f32_e32 v3, 0, v16
	v_fmac_f32_e32 v2, v160, v3
	v_mfma_f32_32x32x16_bf16 v[18:33], v[42:45], v[62:65], v[18:33]
	ds_read_b128 v[58:61], v74 offset:24576
	ds_read_b128 v[54:57], v75 offset:24576
	ds_read_b128 v[50:53], v76 offset:24576
	ds_read_b128 v[62:65], v77 offset:24576
	v_max_f32_e32 v3, 0, v17
	v_fmac_f32_e32 v2, v89, v3
	v_not_b32_e32 v3, v2
	v_or_b32_e32 v4, 0x80000000, v2
	v_cmp_gt_i32_e32 vcc, 0, v2
	s_nop 1
	v_cndmask_b32_e32 v2, v4, v3, vcc
	v_cmp_le_u32_e32 vcc, v101, v87
	s_nop 1
	v_cndmask_b32_e32 v182, 0, v2, vcc
.LBB0_429:
	s_or_b64 exec, exec, s[74:75]
	s_movk_i32 s2, 0xff
	v_cmp_gt_u32_e64 s[74:75], s33, v177
	v_cmp_lt_u32_e32 vcc, s2, v177
	v_mov_b32_e32 v184, 0
	s_and_saveexec_b64 s[82:83], vcc
	s_cbranch_execz .Lidxp_e8
	s_waitcnt lgkmcnt(0)
	v_mfma_f32_32x32x16_bf16 v[2:17], v[38:41], v[58:61], 0
	v_max_f32_e32 v18, 0, v18
	v_max_f32_e32 v19, 0, v19
	v_fma_f32 v18, v174, v18, 0
	v_max_f32_e32 v20, 0, v20
	v_fmac_f32_e32 v18, v173, v19
	v_max_f32_e32 v21, 0, v21
	v_fmac_f32_e32 v18, v172, v20
	v_max_f32_e32 v22, 0, v22
	v_fmac_f32_e32 v18, v171, v21
	v_max_f32_e32 v23, 0, v23
	v_mfma_f32_32x32x16_bf16 v[2:17], v[46:49], v[54:57], v[2:17]
	v_fmac_f32_e32 v18, v170, v22
	v_max_f32_e32 v24, 0, v24
	v_fmac_f32_e32 v18, v169, v23
	v_max_f32_e32 v25, 0, v25
	v_fmac_f32_e32 v18, v168, v24
	v_max_f32_e32 v26, 0, v26
	v_fmac_f32_e32 v18, v167, v25
	v_max_f32_e32 v27, 0, v27
	v_fmac_f32_e32 v18, v166, v26
	v_max_f32_e32 v28, 0, v28
	v_mfma_f32_32x32x16_bf16 v[2:17], v[34:37], v[50:53], v[2:17]
	v_fmac_f32_e32 v18, v165, v27
	v_max_f32_e32 v29, 0, v29
	v_fmac_f32_e32 v18, v164, v28
	v_max_f32_e32 v30, 0, v30
	v_fmac_f32_e32 v18, v163, v29
	v_fmac_f32_e32 v18, v162, v30
	v_max_f32_e32 v19, 0, v31
	v_fmac_f32_e32 v18, v161, v19
	v_max_f32_e32 v19, 0, v32
	v_fmac_f32_e32 v18, v160, v19
	v_mfma_f32_32x32x16_bf16 v[2:17], v[42:45], v[62:65], v[2:17]
	ds_read_b128 v[58:61], v74 offset:28672
	ds_read_b128 v[54:57], v75 offset:28672
	ds_read_b128 v[50:53], v76 offset:28672
	ds_read_b128 v[62:65], v77 offset:28672
	v_max_f32_e32 v19, 0, v33
	v_fmac_f32_e32 v18, v89, v19
	v_not_b32_e32 v19, v18
	v_or_b32_e32 v20, 0x80000000, v18
	v_cmp_gt_i32_e32 vcc, 0, v18
	s_nop 1
	v_cndmask_b32_e32 v18, v20, v19, vcc
	v_cmp_le_u32_e32 vcc, v102, v87
	s_nop 1
	v_cndmask_b32_e32 v183, 0, v18, vcc
.LBB0_433:
	s_or_b64 exec, exec, s[82:83]
	s_movk_i32 s2, 0x11f
	v_cmp_lt_u32_e32 vcc, s2, v177
	v_mov_b32_e32 v185, 0
	s_and_saveexec_b64 s[82:83], vcc
	s_cbranch_execz .Lidxp_e9
	s_waitcnt lgkmcnt(0)
	s_waitcnt vmcnt(0)
	s_barrier
	v_cmp_le_u32_e32 vcc, v79, v80
	s_and_b64 vcc, exec, vcc
	s_cbranch_vccz .Lidxd_s1
	s_nop 0
	global_load_lds_dwordx4 v72, s[100:101]
	s_add_u32 m0, m0, 0x400
	s_add_u32 s100, s100, 0x1a000
	s_addc_u32 s101, s101, 0
	s_nop 0
	global_load_lds_dwordx4 v73, s[100:101]
	s_add_u32 m0, m0, 0x400
	s_add_u32 s100, s100, 0x1a000
	s_addc_u32 s101, s101, 0
	s_nop 0
	global_load_lds_dwordx4 v72, s[100:101]
	s_add_u32 m0, m0, 0x400
	s_add_u32 s100, s100, 0x1a000
	s_addc_u32 s101, s101, 0
	s_nop 0
	global_load_lds_dwordx4 v73, s[100:101]
	s_add_u32 m0, m0, 0x400
	s_add_u32 s100, s100, 0x1a000
	s_addc_u32 s101, s101, 0
	s_add_u32 m0, m0, 0x7000
	s_add_u32 s100, s100, 0x2d8000
	s_addc_u32 s101, s101, 0
	v_add_u32_e32 v79, 8, v79
.Lidxd_s1:
	v_mfma_f32_32x32x16_bf16 v[18:33], v[38:41], v[58:61], 0
	v_max_f32_e32 v2, 0, v2
	v_max_f32_e32 v3, 0, v3
	v_fma_f32 v2, v174, v2, 0
	v_max_f32_e32 v4, 0, v4
	v_fmac_f32_e32 v2, v173, v3
	v_max_f32_e32 v5, 0, v5
	v_fmac_f32_e32 v2, v172, v4
	v_max_f32_e32 v6, 0, v6
	v_fmac_f32_e32 v2, v171, v5
	v_max_f32_e32 v7, 0, v7
	v_mfma_f32_32x32x16_bf16 v[18:33], v[46:49], v[54:57], v[18:33]
	v_fmac_f32_e32 v2, v170, v6
	v_max_f32_e32 v8, 0, v8
	v_fmac_f32_e32 v2, v169, v7
	v_max_f32_e32 v9, 0, v9
	v_fmac_f32_e32 v2, v168, v8
	v_max_f32_e32 v10, 0, v10
	v_fmac_f32_e32 v2, v167, v9
	v_max_f32_e32 v11, 0, v11
	v_fmac_f32_e32 v2, v166, v10
	v_max_f32_e32 v12, 0, v12
	v_mfma_f32_32x32x16_bf16 v[18:33], v[34:37], v[50:53], v[18:33]
	v_fmac_f32_e32 v2, v165, v11
	v_max_f32_e32 v13, 0, v13
	v_fmac_f32_e32 v2, v164, v12
	v_max_f32_e32 v14, 0, v14
	v_fmac_f32_e32 v2, v163, v13
	v_fmac_f32_e32 v2, v162, v14
	v_max_f32_e32 v3, 0, v15
	v_fmac_f32_e32 v2, v161, v3
	v_max_f32_e32 v3, 0, v16
	v_fmac_f32_e32 v2, v160, v3
	v_mfma_f32_32x32x16_bf16 v[18:33], v[42:45], v[62:65], v[18:33]
	ds_read_b128 v[58:61], v74 offset:32768
	ds_read_b128 v[54:57], v75 offset:32768
	ds_read_b128 v[50:53], v76 offset:32768
	ds_read_b128 v[62:65], v77 offset:32768
	v_max_f32_e32 v3, 0, v17
	v_fmac_f32_e32 v2, v89, v3
	v_not_b32_e32 v3, v2
	v_or_b32_e32 v4, 0x80000000, v2
	v_cmp_gt_i32_e32 vcc, 0, v2
	s_nop 1
	v_cndmask_b32_e32 v2, v4, v3, vcc
	v_cmp_le_u32_e32 vcc, v103, v87
	s_nop 1
	v_cndmask_b32_e32 v184, 0, v2, vcc
.LBB0_437:
	s_or_b64 exec, exec, s[82:83]
	s_movk_i32 s2, 0x13f
	v_cmp_lt_u32_e32 vcc, s2, v177
	v_mov_b32_e32 v186, 0
	s_and_saveexec_b64 s[82:83], vcc
	s_cbranch_execz .Lidxp_e10
	s_waitcnt lgkmcnt(0)
	v_mfma_f32_32x32x16_bf16 v[2:17], v[38:41], v[58:61], 0
	v_max_f32_e32 v18, 0, v18
	v_max_f32_e32 v19, 0, v19
	v_fma_f32 v18, v174, v18, 0
	v_max_f32_e32 v20, 0, v20
	v_fmac_f32_e32 v18, v173, v19
	v_max_f32_e32 v21, 0, v21
	v_fmac_f32_e32 v18, v172, v20
	v_max_f32_e32 v22, 0, v22
	v_fmac_f32_e32 v18, v171, v21
	v_max_f32_e32 v23, 0, v23
	v_mfma_f32_32x32x16_bf16 v[2:17], v[46:49], v[54:57], v[2:17]
	v_fmac_f32_e32 v18, v170, v22
	v_max_f32_e32 v24, 0, v24
	v_fmac_f32_e32 v18, v169, v23
	v_max_f32_e32 v25, 0, v25
	v_fmac_f32_e32 v18, v168, v24
	v_max_f32_e32 v26, 0, v26
	v_fmac_f32_e32 v18, v167, v25
	v_max_f32_e32 v27, 0, v27
	v_fmac_f32_e32 v18, v166, v26
	v_max_f32_e32 v28, 0, v28
	v_mfma_f32_32x32x16_bf16 v[2:17], v[34:37], v[50:53], v[2:17]
	v_fmac_f32_e32 v18, v165, v27
	v_max_f32_e32 v29, 0, v29
	v_fmac_f32_e32 v18, v164, v28
	v_max_f32_e32 v30, 0, v30
	v_fmac_f32_e32 v18, v163, v29
	v_fmac_f32_e32 v18, v162, v30
	v_max_f32_e32 v19, 0, v31
	v_fmac_f32_e32 v18, v161, v19
	v_max_f32_e32 v19, 0, v32
	v_fmac_f32_e32 v18, v160, v19
	v_mfma_f32_32x32x16_bf16 v[2:17], v[42:45], v[62:65], v[2:17]
	ds_read_b128 v[58:61], v74 offset:36864
	ds_read_b128 v[54:57], v75 offset:36864
	ds_read_b128 v[50:53], v76 offset:36864
	ds_read_b128 v[62:65], v77 offset:36864
	v_max_f32_e32 v19, 0, v33
	v_fmac_f32_e32 v18, v89, v19
	v_not_b32_e32 v19, v18
	v_or_b32_e32 v20, 0x80000000, v18
	v_cmp_gt_i32_e32 vcc, 0, v18
	s_nop 1
	v_cndmask_b32_e32 v18, v20, v19, vcc
	v_cmp_le_u32_e32 vcc, v104, v87
	s_nop 1
	v_cndmask_b32_e32 v185, 0, v18, vcc
.LBB0_441:
	s_or_b64 exec, exec, s[82:83]
	s_movk_i32 s2, 0x15f
	v_cmp_lt_u32_e32 vcc, s2, v177
	v_mov_b32_e32 v187, 0
	s_and_saveexec_b64 s[82:83], vcc
	s_cbranch_execz .Lidxp_e11
	s_waitcnt lgkmcnt(0)
	v_mfma_f32_32x32x16_bf16 v[18:33], v[38:41], v[58:61], 0
	v_max_f32_e32 v2, 0, v2
	v_max_f32_e32 v3, 0, v3
	v_fma_f32 v2, v174, v2, 0
	v_max_f32_e32 v4, 0, v4
	v_fmac_f32_e32 v2, v173, v3
	v_max_f32_e32 v5, 0, v5
	v_fmac_f32_e32 v2, v172, v4
	v_max_f32_e32 v6, 0, v6
	v_fmac_f32_e32 v2, v171, v5
	v_max_f32_e32 v7, 0, v7
	v_mfma_f32_32x32x16_bf16 v[18:33], v[46:49], v[54:57], v[18:33]
	v_fmac_f32_e32 v2, v170, v6
	v_max_f32_e32 v8, 0, v8
	v_fmac_f32_e32 v2, v169, v7
	v_max_f32_e32 v9, 0, v9
	v_fmac_f32_e32 v2, v168, v8
	v_max_f32_e32 v10, 0, v10
	v_fmac_f32_e32 v2, v167, v9
	v_max_f32_e32 v11, 0, v11
	v_fmac_f32_e32 v2, v166, v10
	v_max_f32_e32 v12, 0, v12
	v_mfma_f32_32x32x16_bf16 v[18:33], v[34:37], v[50:53], v[18:33]
	v_fmac_f32_e32 v2, v165, v11
	v_max_f32_e32 v13, 0, v13
	v_fmac_f32_e32 v2, v164, v12
	v_max_f32_e32 v14, 0, v14
	v_fmac_f32_e32 v2, v163, v13
	v_fmac_f32_e32 v2, v162, v14
	v_max_f32_e32 v3, 0, v15
	v_fmac_f32_e32 v2, v161, v3
	v_max_f32_e32 v3, 0, v16
	v_fmac_f32_e32 v2, v160, v3
	v_mfma_f32_32x32x16_bf16 v[18:33], v[42:45], v[62:65], v[18:33]
	ds_read_b128 v[58:61], v74 offset:40960
	ds_read_b128 v[54:57], v75 offset:40960
	ds_read_b128 v[50:53], v76 offset:40960
	ds_read_b128 v[62:65], v77 offset:40960
	v_max_f32_e32 v3, 0, v17
	v_fmac_f32_e32 v2, v89, v3
	v_not_b32_e32 v3, v2
	v_or_b32_e32 v4, 0x80000000, v2
	v_cmp_gt_i32_e32 vcc, 0, v2
	s_nop 1
	v_cndmask_b32_e32 v2, v4, v3, vcc
	v_cmp_le_u32_e32 vcc, v105, v87
	s_nop 1
	v_cndmask_b32_e32 v186, 0, v2, vcc
.LBB0_445:
	s_or_b64 exec, exec, s[82:83]
	s_movk_i32 s2, 0x17f
	v_cmp_lt_u32_e32 vcc, s2, v177
	v_mov_b32_e32 v188, 0
	s_and_saveexec_b64 s[82:83], vcc
	s_cbranch_execz .Lidxp_e12
	s_waitcnt lgkmcnt(0)
	v_mfma_f32_32x32x16_bf16 v[2:17], v[38:41], v[58:61], 0
	v_max_f32_e32 v18, 0, v18
	v_max_f32_e32 v19, 0, v19
	v_fma_f32 v18, v174, v18, 0
	v_max_f32_e32 v20, 0, v20
	v_fmac_f32_e32 v18, v173, v19
	v_max_f32_e32 v21, 0, v21
	v_fmac_f32_e32 v18, v172, v20
	v_max_f32_e32 v22, 0, v22
	v_fmac_f32_e32 v18, v171, v21
	v_max_f32_e32 v23, 0, v23
	v_mfma_f32_32x32x16_bf16 v[2:17], v[46:49], v[54:57], v[2:17]
	v_fmac_f32_e32 v18, v170, v22
	v_max_f32_e32 v24, 0, v24
	v_fmac_f32_e32 v18, v169, v23
	v_max_f32_e32 v25, 0, v25
	v_fmac_f32_e32 v18, v168, v24
	v_max_f32_e32 v26, 0, v26
	v_fmac_f32_e32 v18, v167, v25
	v_max_f32_e32 v27, 0, v27
	v_fmac_f32_e32 v18, v166, v26
	v_max_f32_e32 v28, 0, v28
	v_mfma_f32_32x32x16_bf16 v[2:17], v[34:37], v[50:53], v[2:17]
	v_fmac_f32_e32 v18, v165, v27
	v_max_f32_e32 v29, 0, v29
	v_fmac_f32_e32 v18, v164, v28
	v_max_f32_e32 v30, 0, v30
	v_fmac_f32_e32 v18, v163, v29
	v_fmac_f32_e32 v18, v162, v30
	v_max_f32_e32 v19, 0, v31
	v_fmac_f32_e32 v18, v161, v19
	v_max_f32_e32 v19, 0, v32
	v_fmac_f32_e32 v18, v160, v19
	v_mfma_f32_32x32x16_bf16 v[2:17], v[42:45], v[62:65], v[2:17]
	ds_read_b128 v[58:61], v74 offset:45056
	ds_read_b128 v[54:57], v75 offset:45056
	ds_read_b128 v[50:53], v76 offset:45056
	ds_read_b128 v[62:65], v77 offset:45056
	v_max_f32_e32 v19, 0, v33
	v_fmac_f32_e32 v18, v89, v19
	v_not_b32_e32 v19, v18
	v_or_b32_e32 v20, 0x80000000, v18
	v_cmp_gt_i32_e32 vcc, 0, v18
	s_nop 1
	v_cndmask_b32_e32 v18, v20, v19, vcc
	v_cmp_le_u32_e32 vcc, v106, v87
	s_nop 1
	v_cndmask_b32_e32 v187, 0, v18, vcc
.LBB0_449:
	s_or_b64 exec, exec, s[82:83]
	s_movk_i32 s2, 0x19f
	v_cmp_lt_u32_e32 vcc, s2, v177
	v_mov_b32_e32 v189, 0
	s_and_saveexec_b64 s[82:83], vcc
	s_cbranch_execz .Lidxp_e13
	s_waitcnt lgkmcnt(0)
	v_mfma_f32_32x32x16_bf16 v[18:33], v[38:41], v[58:61], 0
	v_max_f32_e32 v2, 0, v2
	v_max_f32_e32 v3, 0, v3
	v_fma_f32 v2, v174, v2, 0
	v_max_f32_e32 v4, 0, v4
	v_fmac_f32_e32 v2, v173, v3
	v_max_f32_e32 v5, 0, v5
	v_fmac_f32_e32 v2, v172, v4
	v_max_f32_e32 v6, 0, v6
	v_fmac_f32_e32 v2, v171, v5
	v_max_f32_e32 v7, 0, v7
	v_mfma_f32_32x32x16_bf16 v[18:33], v[46:49], v[54:57], v[18:33]
	v_fmac_f32_e32 v2, v170, v6
	v_max_f32_e32 v8, 0, v8
	v_fmac_f32_e32 v2, v169, v7
	v_max_f32_e32 v9, 0, v9
	v_fmac_f32_e32 v2, v168, v8
	v_max_f32_e32 v10, 0, v10
	v_fmac_f32_e32 v2, v167, v9
	v_max_f32_e32 v11, 0, v11
	v_fmac_f32_e32 v2, v166, v10
	v_max_f32_e32 v12, 0, v12
	v_mfma_f32_32x32x16_bf16 v[18:33], v[34:37], v[50:53], v[18:33]
	v_fmac_f32_e32 v2, v165, v11
	v_max_f32_e32 v13, 0, v13
	v_fmac_f32_e32 v2, v164, v12
	v_max_f32_e32 v14, 0, v14
	v_fmac_f32_e32 v2, v163, v13
	v_fmac_f32_e32 v2, v162, v14
	v_max_f32_e32 v3, 0, v15
	v_fmac_f32_e32 v2, v161, v3
	v_max_f32_e32 v3, 0, v16
	v_fmac_f32_e32 v2, v160, v3
	v_mfma_f32_32x32x16_bf16 v[18:33], v[42:45], v[62:65], v[18:33]
	ds_read_b128 v[58:61], v74 offset:49152
	ds_read_b128 v[54:57], v75 offset:49152
	ds_read_b128 v[50:53], v76 offset:49152
	ds_read_b128 v[62:65], v77 offset:49152
	v_max_f32_e32 v3, 0, v17
	v_fmac_f32_e32 v2, v89, v3
	v_not_b32_e32 v3, v2
	v_or_b32_e32 v4, 0x80000000, v2
	v_cmp_gt_i32_e32 vcc, 0, v2
	s_nop 1
	v_cndmask_b32_e32 v2, v4, v3, vcc
	v_cmp_le_u32_e32 vcc, v107, v87
	s_nop 1
	v_cndmask_b32_e32 v188, 0, v2, vcc
.LBB0_453:
	s_or_b64 exec, exec, s[82:83]
	s_movk_i32 s2, 0x1bf
	v_cmp_lt_u32_e32 vcc, s2, v177
	v_mov_b32_e32 v190, 0
	s_and_saveexec_b64 s[82:83], vcc
	s_cbranch_execz .Lidxp_e14
	s_waitcnt lgkmcnt(0)
	v_mfma_f32_32x32x16_bf16 v[2:17], v[38:41], v[58:61], 0
	v_max_f32_e32 v18, 0, v18
	v_max_f32_e32 v19, 0, v19
	v_fma_f32 v18, v174, v18, 0
	v_max_f32_e32 v20, 0, v20
	v_fmac_f32_e32 v18, v173, v19
	v_max_f32_e32 v21, 0, v21
	v_fmac_f32_e32 v18, v172, v20
	v_max_f32_e32 v22, 0, v22
	v_fmac_f32_e32 v18, v171, v21
	v_max_f32_e32 v23, 0, v23
	v_mfma_f32_32x32x16_bf16 v[2:17], v[46:49], v[54:57], v[2:17]
	v_fmac_f32_e32 v18, v170, v22
	v_max_f32_e32 v24, 0, v24
	v_fmac_f32_e32 v18, v169, v23
	v_max_f32_e32 v25, 0, v25
	v_fmac_f32_e32 v18, v168, v24
	v_max_f32_e32 v26, 0, v26
	v_fmac_f32_e32 v18, v167, v25
	v_max_f32_e32 v27, 0, v27
	v_fmac_f32_e32 v18, v166, v26
	v_max_f32_e32 v28, 0, v28
	v_mfma_f32_32x32x16_bf16 v[2:17], v[34:37], v[50:53], v[2:17]
	v_fmac_f32_e32 v18, v165, v27
	v_max_f32_e32 v29, 0, v29
	v_fmac_f32_e32 v18, v164, v28
	v_max_f32_e32 v30, 0, v30
	v_fmac_f32_e32 v18, v163, v29
	v_fmac_f32_e32 v18, v162, v30
	v_max_f32_e32 v19, 0, v31
	v_fmac_f32_e32 v18, v161, v19
	v_max_f32_e32 v19, 0, v32
	v_fmac_f32_e32 v18, v160, v19
	v_mfma_f32_32x32x16_bf16 v[2:17], v[42:45], v[62:65], v[2:17]
	ds_read_b128 v[58:61], v74 offset:53248
	ds_read_b128 v[54:57], v75 offset:53248
	ds_read_b128 v[50:53], v76 offset:53248
	ds_read_b128 v[62:65], v77 offset:53248
	v_max_f32_e32 v19, 0, v33
	v_fmac_f32_e32 v18, v89, v19
	v_not_b32_e32 v19, v18
	v_or_b32_e32 v20, 0x80000000, v18
	v_cmp_gt_i32_e32 vcc, 0, v18
	s_nop 1
	v_cndmask_b32_e32 v18, v20, v19, vcc
	v_cmp_le_u32_e32 vcc, v108, v87
	s_nop 1
	v_cndmask_b32_e32 v189, 0, v18, vcc
.LBB0_457:
	s_or_b64 exec, exec, s[82:83]
	s_movk_i32 s2, 0x1df
	v_cmp_lt_u32_e32 vcc, s2, v177
	v_mov_b32_e32 v191, 0
	s_and_saveexec_b64 s[82:83], vcc
	s_cbranch_execz .Lidxp_e15
	s_waitcnt lgkmcnt(0)
	v_mfma_f32_32x32x16_bf16 v[18:33], v[38:41], v[58:61], 0
	v_max_f32_e32 v2, 0, v2
	v_max_f32_e32 v3, 0, v3
	v_fma_f32 v2, v174, v2, 0
	v_max_f32_e32 v4, 0, v4
	v_fmac_f32_e32 v2, v173, v3
	v_max_f32_e32 v5, 0, v5
	v_fmac_f32_e32 v2, v172, v4
	v_max_f32_e32 v6, 0, v6
	v_fmac_f32_e32 v2, v171, v5
	v_max_f32_e32 v7, 0, v7
	v_mfma_f32_32x32x16_bf16 v[18:33], v[46:49], v[54:57], v[18:33]
	v_fmac_f32_e32 v2, v170, v6
	v_max_f32_e32 v8, 0, v8
	v_fmac_f32_e32 v2, v169, v7
	v_max_f32_e32 v9, 0, v9
	v_fmac_f32_e32 v2, v168, v8
	v_max_f32_e32 v10, 0, v10
	v_fmac_f32_e32 v2, v167, v9
	v_max_f32_e32 v11, 0, v11
	v_fmac_f32_e32 v2, v166, v10
	v_max_f32_e32 v12, 0, v12
	v_mfma_f32_32x32x16_bf16 v[18:33], v[34:37], v[50:53], v[18:33]
	v_fmac_f32_e32 v2, v165, v11
	v_max_f32_e32 v13, 0, v13
	v_fmac_f32_e32 v2, v164, v12
	v_max_f32_e32 v14, 0, v14
	v_fmac_f32_e32 v2, v163, v13
	v_fmac_f32_e32 v2, v162, v14
	v_max_f32_e32 v3, 0, v15
	v_fmac_f32_e32 v2, v161, v3
	v_max_f32_e32 v3, 0, v16
	v_fmac_f32_e32 v2, v160, v3
	v_mfma_f32_32x32x16_bf16 v[18:33], v[42:45], v[62:65], v[18:33]
	ds_read_b128 v[58:61], v74 offset:57344
	ds_read_b128 v[54:57], v75 offset:57344
	ds_read_b128 v[50:53], v76 offset:57344
	ds_read_b128 v[62:65], v77 offset:57344
	v_max_f32_e32 v3, 0, v17
	v_fmac_f32_e32 v2, v89, v3
	v_not_b32_e32 v3, v2
	v_or_b32_e32 v4, 0x80000000, v2
	v_cmp_gt_i32_e32 vcc, 0, v2
	s_nop 1
	v_cndmask_b32_e32 v2, v4, v3, vcc
	v_cmp_le_u32_e32 vcc, v109, v87
	s_nop 1
	v_cndmask_b32_e32 v190, 0, v2, vcc
.LBB0_461:
	s_or_b64 exec, exec, s[82:83]
	s_movk_i32 s2, 0x1ff
	v_cmp_lt_u32_e32 vcc, s2, v177
	v_mov_b32_e32 v192, 0
	s_and_saveexec_b64 s[82:83], vcc
	s_cbranch_execz .Lidxp_e16
	s_waitcnt lgkmcnt(0)
	v_mfma_f32_32x32x16_bf16 v[2:17], v[38:41], v[58:61], 0
	v_max_f32_e32 v18, 0, v18
	v_max_f32_e32 v19, 0, v19
	v_fma_f32 v18, v174, v18, 0
	v_max_f32_e32 v20, 0, v20
	v_fmac_f32_e32 v18, v173, v19
	v_max_f32_e32 v21, 0, v21
	v_fmac_f32_e32 v18, v172, v20
	v_max_f32_e32 v22, 0, v22
	v_fmac_f32_e32 v18, v171, v21
	v_max_f32_e32 v23, 0, v23
	v_mfma_f32_32x32x16_bf16 v[2:17], v[46:49], v[54:57], v[2:17]
	v_fmac_f32_e32 v18, v170, v22
	v_max_f32_e32 v24, 0, v24
	v_fmac_f32_e32 v18, v169, v23
	v_max_f32_e32 v25, 0, v25
	v_fmac_f32_e32 v18, v168, v24
	v_max_f32_e32 v26, 0, v26
	v_fmac_f32_e32 v18, v167, v25
	v_max_f32_e32 v27, 0, v27
	v_fmac_f32_e32 v18, v166, v26
	v_max_f32_e32 v28, 0, v28
	v_mfma_f32_32x32x16_bf16 v[2:17], v[34:37], v[50:53], v[2:17]
	v_fmac_f32_e32 v18, v165, v27
	v_max_f32_e32 v29, 0, v29
	v_fmac_f32_e32 v18, v164, v28
	v_max_f32_e32 v30, 0, v30
	v_fmac_f32_e32 v18, v163, v29
	v_fmac_f32_e32 v18, v162, v30
	v_max_f32_e32 v19, 0, v31
	v_fmac_f32_e32 v18, v161, v19
	v_max_f32_e32 v19, 0, v32
	v_fmac_f32_e32 v18, v160, v19
	v_mfma_f32_32x32x16_bf16 v[2:17], v[42:45], v[62:65], v[2:17]
	ds_read_b128 v[58:61], v74 offset:61440
	ds_read_b128 v[54:57], v75 offset:61440
	ds_read_b128 v[50:53], v76 offset:61440
	ds_read_b128 v[62:65], v77 offset:61440
	v_max_f32_e32 v19, 0, v33
	v_fmac_f32_e32 v18, v89, v19
	v_not_b32_e32 v19, v18
	v_or_b32_e32 v20, 0x80000000, v18
	v_cmp_gt_i32_e32 vcc, 0, v18
	s_nop 1
	v_cndmask_b32_e32 v18, v20, v19, vcc
	v_cmp_le_u32_e32 vcc, v110, v87
	s_nop 1
	v_cndmask_b32_e32 v191, 0, v18, vcc
.LBB0_465:
	s_or_b64 exec, exec, s[82:83]
	s_movk_i32 s2, 0x21f
	v_cmp_lt_u32_e32 vcc, s2, v177
	v_mov_b32_e32 v193, 0
	s_and_saveexec_b64 s[82:83], vcc
	s_cbranch_execz .Lidxp_e17
	s_waitcnt lgkmcnt(0)
	s_waitcnt vmcnt(0)
	s_barrier
	v_cmp_le_u32_e32 vcc, v79, v80
	s_and_b64 vcc, exec, vcc
	s_cbranch_vccz .Lidxd_s2
	s_nop 0
	global_load_lds_dwordx4 v72, s[100:101]
	s_add_u32 m0, m0, 0x400
	s_add_u32 s100, s100, 0x1a000
	s_addc_u32 s101, s101, 0
	s_nop 0
	global_load_lds_dwordx4 v73, s[100:101]
	s_add_u32 m0, m0, 0x400
	s_add_u32 s100, s100, 0x1a000
	s_addc_u32 s101, s101, 0
	s_nop 0
	global_load_lds_dwordx4 v72, s[100:101]
	s_add_u32 m0, m0, 0x400
	s_add_u32 s100, s100, 0x1a000
	s_addc_u32 s101, s101, 0
	s_nop 0
	global_load_lds_dwordx4 v73, s[100:101]
	s_add_u32 m0, m0, 0x400
	s_add_u32 s100, s100, 0x1a000
	s_addc_u32 s101, s101, 0
	s_sub_u32 m0, m0, 0x9000
	s_add_u32 s100, s100, 0x2d8000
	s_addc_u32 s101, s101, 0
	v_add_u32_e32 v79, 8, v79
.Lidxd_s2:
	v_mfma_f32_32x32x16_bf16 v[18:33], v[38:41], v[58:61], 0
	v_max_f32_e32 v2, 0, v2
	v_max_f32_e32 v3, 0, v3
	v_fma_f32 v2, v174, v2, 0
	v_max_f32_e32 v4, 0, v4
	v_fmac_f32_e32 v2, v173, v3
	v_max_f32_e32 v5, 0, v5
	v_fmac_f32_e32 v2, v172, v4
	v_max_f32_e32 v6, 0, v6
	v_fmac_f32_e32 v2, v171, v5
	v_max_f32_e32 v7, 0, v7
	v_mfma_f32_32x32x16_bf16 v[18:33], v[46:49], v[54:57], v[18:33]
	v_fmac_f32_e32 v2, v170, v6
	v_max_f32_e32 v8, 0, v8
	v_fmac_f32_e32 v2, v169, v7
	v_max_f32_e32 v9, 0, v9
	v_fmac_f32_e32 v2, v168, v8
	v_max_f32_e32 v10, 0, v10
	v_fmac_f32_e32 v2, v167, v9
	v_max_f32_e32 v11, 0, v11
	v_fmac_f32_e32 v2, v166, v10
	v_max_f32_e32 v12, 0, v12
	v_mfma_f32_32x32x16_bf16 v[18:33], v[34:37], v[50:53], v[18:33]
	v_fmac_f32_e32 v2, v165, v11
	v_max_f32_e32 v13, 0, v13
	v_fmac_f32_e32 v2, v164, v12
	v_max_f32_e32 v14, 0, v14
	v_fmac_f32_e32 v2, v163, v13
	v_fmac_f32_e32 v2, v162, v14
	v_max_f32_e32 v3, 0, v15
	v_fmac_f32_e32 v2, v161, v3
	v_max_f32_e32 v3, 0, v16
	v_fmac_f32_e32 v2, v160, v3
	v_mfma_f32_32x32x16_bf16 v[18:33], v[42:45], v[62:65], v[18:33]
	ds_read_b128 v[58:61], v74 offset:0
	ds_read_b128 v[54:57], v75 offset:0
	ds_read_b128 v[50:53], v76 offset:0
	ds_read_b128 v[62:65], v77 offset:0
	v_max_f32_e32 v3, 0, v17
	v_fmac_f32_e32 v2, v89, v3
	v_not_b32_e32 v3, v2
	v_or_b32_e32 v4, 0x80000000, v2
	v_cmp_gt_i32_e32 vcc, 0, v2
	s_nop 1
	v_cndmask_b32_e32 v2, v4, v3, vcc
	v_cmp_le_u32_e32 vcc, v111, v87
	s_nop 1
	v_cndmask_b32_e32 v192, 0, v2, vcc
.LBB0_469:
	s_or_b64 exec, exec, s[82:83]
	s_movk_i32 s2, 0x23f
	v_cmp_lt_u32_e32 vcc, s2, v177
	v_mov_b32_e32 v194, 0
	s_and_saveexec_b64 s[82:83], vcc
	s_cbranch_execz .Lidxp_e18
	s_waitcnt lgkmcnt(0)
	v_mfma_f32_32x32x16_bf16 v[2:17], v[38:41], v[58:61], 0
	v_max_f32_e32 v18, 0, v18
	v_max_f32_e32 v19, 0, v19
	v_fma_f32 v18, v174, v18, 0
	v_max_f32_e32 v20, 0, v20
	v_fmac_f32_e32 v18, v173, v19
	v_max_f32_e32 v21, 0, v21
	v_fmac_f32_e32 v18, v172, v20
	v_max_f32_e32 v22, 0, v22
	v_fmac_f32_e32 v18, v171, v21
	v_max_f32_e32 v23, 0, v23
	v_mfma_f32_32x32x16_bf16 v[2:17], v[46:49], v[54:57], v[2:17]
	v_fmac_f32_e32 v18, v170, v22
	v_max_f32_e32 v24, 0, v24
	v_fmac_f32_e32 v18, v169, v23
	v_max_f32_e32 v25, 0, v25
	v_fmac_f32_e32 v18, v168, v24
	v_max_f32_e32 v26, 0, v26
	v_fmac_f32_e32 v18, v167, v25
	v_max_f32_e32 v27, 0, v27
	v_fmac_f32_e32 v18, v166, v26
	v_max_f32_e32 v28, 0, v28
	v_mfma_f32_32x32x16_bf16 v[2:17], v[34:37], v[50:53], v[2:17]
	v_fmac_f32_e32 v18, v165, v27
	v_max_f32_e32 v29, 0, v29
	v_fmac_f32_e32 v18, v164, v28
	v_max_f32_e32 v30, 0, v30
	v_fmac_f32_e32 v18, v163, v29
	v_fmac_f32_e32 v18, v162, v30
	v_max_f32_e32 v19, 0, v31
	v_fmac_f32_e32 v18, v161, v19
	v_max_f32_e32 v19, 0, v32
	v_fmac_f32_e32 v18, v160, v19
	v_mfma_f32_32x32x16_bf16 v[2:17], v[42:45], v[62:65], v[2:17]
	ds_read_b128 v[58:61], v74 offset:4096
	ds_read_b128 v[54:57], v75 offset:4096
	ds_read_b128 v[50:53], v76 offset:4096
	ds_read_b128 v[62:65], v77 offset:4096
	v_max_f32_e32 v19, 0, v33
	v_fmac_f32_e32 v18, v89, v19
	v_not_b32_e32 v19, v18
	v_or_b32_e32 v20, 0x80000000, v18
	v_cmp_gt_i32_e32 vcc, 0, v18
	s_nop 1
	v_cndmask_b32_e32 v18, v20, v19, vcc
	v_cmp_le_u32_e32 vcc, v112, v87
	s_nop 1
	v_cndmask_b32_e32 v193, 0, v18, vcc
.LBB0_473:
	s_or_b64 exec, exec, s[82:83]
	s_movk_i32 s2, 0x25f
	v_cmp_lt_u32_e32 vcc, s2, v177
	v_mov_b32_e32 v195, 0
	s_and_saveexec_b64 s[82:83], vcc
	s_cbranch_execz .Lidxp_e19
	s_waitcnt lgkmcnt(0)
	v_mfma_f32_32x32x16_bf16 v[18:33], v[38:41], v[58:61], 0
	v_max_f32_e32 v2, 0, v2
	v_max_f32_e32 v3, 0, v3
	v_fma_f32 v2, v174, v2, 0
	v_max_f32_e32 v4, 0, v4
	v_fmac_f32_e32 v2, v173, v3
	v_max_f32_e32 v5, 0, v5
	v_fmac_f32_e32 v2, v172, v4
	v_max_f32_e32 v6, 0, v6
	v_fmac_f32_e32 v2, v171, v5
	v_max_f32_e32 v7, 0, v7
	v_mfma_f32_32x32x16_bf16 v[18:33], v[46:49], v[54:57], v[18:33]
	v_fmac_f32_e32 v2, v170, v6
	v_max_f32_e32 v8, 0, v8
	v_fmac_f32_e32 v2, v169, v7
	v_max_f32_e32 v9, 0, v9
	v_fmac_f32_e32 v2, v168, v8
	v_max_f32_e32 v10, 0, v10
	v_fmac_f32_e32 v2, v167, v9
	v_max_f32_e32 v11, 0, v11
	v_fmac_f32_e32 v2, v166, v10
	v_max_f32_e32 v12, 0, v12
	v_mfma_f32_32x32x16_bf16 v[18:33], v[34:37], v[50:53], v[18:33]
	v_fmac_f32_e32 v2, v165, v11
	v_max_f32_e32 v13, 0, v13
	v_fmac_f32_e32 v2, v164, v12
	v_max_f32_e32 v14, 0, v14
	v_fmac_f32_e32 v2, v163, v13
	v_fmac_f32_e32 v2, v162, v14
	v_max_f32_e32 v3, 0, v15
	v_fmac_f32_e32 v2, v161, v3
	v_max_f32_e32 v3, 0, v16
	v_fmac_f32_e32 v2, v160, v3
	v_mfma_f32_32x32x16_bf16 v[18:33], v[42:45], v[62:65], v[18:33]
	ds_read_b128 v[58:61], v74 offset:8192
	ds_read_b128 v[54:57], v75 offset:8192
	ds_read_b128 v[50:53], v76 offset:8192
	ds_read_b128 v[62:65], v77 offset:8192
	v_max_f32_e32 v3, 0, v17
	v_fmac_f32_e32 v2, v89, v3
	v_not_b32_e32 v3, v2
	v_or_b32_e32 v4, 0x80000000, v2
	v_cmp_gt_i32_e32 vcc, 0, v2
	s_nop 1
	v_cndmask_b32_e32 v2, v4, v3, vcc
	v_cmp_le_u32_e32 vcc, v113, v87
	s_nop 1
	v_cndmask_b32_e32 v194, 0, v2, vcc
.LBB0_477:
	s_or_b64 exec, exec, s[82:83]
	s_movk_i32 s2, 0x27f
	v_cmp_lt_u32_e32 vcc, s2, v177
	v_mov_b32_e32 v196, 0
	s_and_saveexec_b64 s[82:83], vcc
	s_cbranch_execz .Lidxp_e20
	s_waitcnt lgkmcnt(0)
	v_mfma_f32_32x32x16_bf16 v[2:17], v[38:41], v[58:61], 0
	v_max_f32_e32 v18, 0, v18
	v_max_f32_e32 v19, 0, v19
	v_fma_f32 v18, v174, v18, 0
	v_max_f32_e32 v20, 0, v20
	v_fmac_f32_e32 v18, v173, v19
	v_max_f32_e32 v21, 0, v21
	v_fmac_f32_e32 v18, v172, v20
	v_max_f32_e32 v22, 0, v22
	v_fmac_f32_e32 v18, v171, v21
	v_max_f32_e32 v23, 0, v23
	v_mfma_f32_32x32x16_bf16 v[2:17], v[46:49], v[54:57], v[2:17]
	v_fmac_f32_e32 v18, v170, v22
	v_max_f32_e32 v24, 0, v24
	v_fmac_f32_e32 v18, v169, v23
	v_max_f32_e32 v25, 0, v25
	v_fmac_f32_e32 v18, v168, v24
	v_max_f32_e32 v26, 0, v26
	v_fmac_f32_e32 v18, v167, v25
	v_max_f32_e32 v27, 0, v27
	v_fmac_f32_e32 v18, v166, v26
	v_max_f32_e32 v28, 0, v28
	v_mfma_f32_32x32x16_bf16 v[2:17], v[34:37], v[50:53], v[2:17]
	v_fmac_f32_e32 v18, v165, v27
	v_max_f32_e32 v29, 0, v29
	v_fmac_f32_e32 v18, v164, v28
	v_max_f32_e32 v30, 0, v30
	v_fmac_f32_e32 v18, v163, v29
	v_fmac_f32_e32 v18, v162, v30
	v_max_f32_e32 v19, 0, v31
	v_fmac_f32_e32 v18, v161, v19
	v_max_f32_e32 v19, 0, v32
	v_fmac_f32_e32 v18, v160, v19
	v_mfma_f32_32x32x16_bf16 v[2:17], v[42:45], v[62:65], v[2:17]
	ds_read_b128 v[58:61], v74 offset:12288
	ds_read_b128 v[54:57], v75 offset:12288
	ds_read_b128 v[50:53], v76 offset:12288
	ds_read_b128 v[62:65], v77 offset:12288
	v_max_f32_e32 v19, 0, v33
	v_fmac_f32_e32 v18, v89, v19
	v_not_b32_e32 v19, v18
	v_or_b32_e32 v20, 0x80000000, v18
	v_cmp_gt_i32_e32 vcc, 0, v18
	s_nop 1
	v_cndmask_b32_e32 v18, v20, v19, vcc
	v_cmp_le_u32_e32 vcc, v114, v87
	s_nop 1
	v_cndmask_b32_e32 v195, 0, v18, vcc
.LBB0_481:
	s_or_b64 exec, exec, s[82:83]
	s_movk_i32 s2, 0x29f
	v_cmp_lt_u32_e32 vcc, s2, v177
	v_mov_b32_e32 v197, 0
	s_and_saveexec_b64 s[82:83], vcc
	s_cbranch_execz .Lidxp_e21
	s_waitcnt lgkmcnt(0)
	v_mfma_f32_32x32x16_bf16 v[18:33], v[38:41], v[58:61], 0
	v_max_f32_e32 v2, 0, v2
	v_max_f32_e32 v3, 0, v3
	v_fma_f32 v2, v174, v2, 0
	v_max_f32_e32 v4, 0, v4
	v_fmac_f32_e32 v2, v173, v3
	v_max_f32_e32 v5, 0, v5
	v_fmac_f32_e32 v2, v172, v4
	v_max_f32_e32 v6, 0, v6
	v_fmac_f32_e32 v2, v171, v5
	v_max_f32_e32 v7, 0, v7
	v_mfma_f32_32x32x16_bf16 v[18:33], v[46:49], v[54:57], v[18:33]
	v_fmac_f32_e32 v2, v170, v6
	v_max_f32_e32 v8, 0, v8
	v_fmac_f32_e32 v2, v169, v7
	v_max_f32_e32 v9, 0, v9
	v_fmac_f32_e32 v2, v168, v8
	v_max_f32_e32 v10, 0, v10
	v_fmac_f32_e32 v2, v167, v9
	v_max_f32_e32 v11, 0, v11
	v_fmac_f32_e32 v2, v166, v10
	v_max_f32_e32 v12, 0, v12
	v_mfma_f32_32x32x16_bf16 v[18:33], v[34:37], v[50:53], v[18:33]
	v_fmac_f32_e32 v2, v165, v11
	v_max_f32_e32 v13, 0, v13
	v_fmac_f32_e32 v2, v164, v12
	v_max_f32_e32 v14, 0, v14
	v_fmac_f32_e32 v2, v163, v13
	v_fmac_f32_e32 v2, v162, v14
	v_max_f32_e32 v3, 0, v15
	v_fmac_f32_e32 v2, v161, v3
	v_max_f32_e32 v3, 0, v16
	v_fmac_f32_e32 v2, v160, v3
	v_mfma_f32_32x32x16_bf16 v[18:33], v[42:45], v[62:65], v[18:33]
	ds_read_b128 v[58:61], v74 offset:16384
	ds_read_b128 v[54:57], v75 offset:16384
	ds_read_b128 v[50:53], v76 offset:16384
	ds_read_b128 v[62:65], v77 offset:16384
	v_max_f32_e32 v3, 0, v17
	v_fmac_f32_e32 v2, v89, v3
	v_not_b32_e32 v3, v2
	v_or_b32_e32 v4, 0x80000000, v2
	v_cmp_gt_i32_e32 vcc, 0, v2
	s_nop 1
	v_cndmask_b32_e32 v2, v4, v3, vcc
	v_cmp_le_u32_e32 vcc, v115, v87
	s_nop 1
	v_cndmask_b32_e32 v196, 0, v2, vcc
.LBB0_485:
	s_or_b64 exec, exec, s[82:83]
	s_movk_i32 s2, 0x2bf
	v_cmp_lt_u32_e32 vcc, s2, v177
	v_mov_b32_e32 v216, 0
	s_and_saveexec_b64 s[82:83], vcc
	s_cbranch_execz .Lidxp_e22
	s_waitcnt lgkmcnt(0)
	v_mfma_f32_32x32x16_bf16 v[2:17], v[38:41], v[58:61], 0
	v_max_f32_e32 v18, 0, v18
	v_max_f32_e32 v19, 0, v19
	v_fma_f32 v18, v174, v18, 0
	v_max_f32_e32 v20, 0, v20
	v_fmac_f32_e32 v18, v173, v19
	v_max_f32_e32 v21, 0, v21
	v_fmac_f32_e32 v18, v172, v20
	v_max_f32_e32 v22, 0, v22
	v_fmac_f32_e32 v18, v171, v21
	v_max_f32_e32 v23, 0, v23
	v_mfma_f32_32x32x16_bf16 v[2:17], v[46:49], v[54:57], v[2:17]
	v_fmac_f32_e32 v18, v170, v22
	v_max_f32_e32 v24, 0, v24
	v_fmac_f32_e32 v18, v169, v23
	v_max_f32_e32 v25, 0, v25
	v_fmac_f32_e32 v18, v168, v24
	v_max_f32_e32 v26, 0, v26
	v_fmac_f32_e32 v18, v167, v25
	v_max_f32_e32 v27, 0, v27
	v_fmac_f32_e32 v18, v166, v26
	v_max_f32_e32 v28, 0, v28
	v_mfma_f32_32x32x16_bf16 v[2:17], v[34:37], v[50:53], v[2:17]
	v_fmac_f32_e32 v18, v165, v27
	v_max_f32_e32 v29, 0, v29
	v_fmac_f32_e32 v18, v164, v28
	v_max_f32_e32 v30, 0, v30
	v_fmac_f32_e32 v18, v163, v29
	v_fmac_f32_e32 v18, v162, v30
	v_max_f32_e32 v19, 0, v31
	v_fmac_f32_e32 v18, v161, v19
	v_max_f32_e32 v19, 0, v32
	v_fmac_f32_e32 v18, v160, v19
	v_mfma_f32_32x32x16_bf16 v[2:17], v[42:45], v[62:65], v[2:17]
	ds_read_b128 v[58:61], v74 offset:20480
	ds_read_b128 v[54:57], v75 offset:20480
	ds_read_b128 v[50:53], v76 offset:20480
	ds_read_b128 v[62:65], v77 offset:20480
	v_max_f32_e32 v19, 0, v33
	v_fmac_f32_e32 v18, v89, v19
	v_not_b32_e32 v19, v18
	v_or_b32_e32 v20, 0x80000000, v18
	v_cmp_gt_i32_e32 vcc, 0, v18
	s_nop 1
	v_cndmask_b32_e32 v18, v20, v19, vcc
	v_cmp_le_u32_e32 vcc, v116, v87
	s_nop 1
	v_cndmask_b32_e32 v197, 0, v18, vcc
.LBB0_489:
	s_or_b64 exec, exec, s[82:83]
	s_movk_i32 s2, 0x2df
	v_cmp_lt_u32_e32 vcc, s2, v177
	v_mov_b32_e32 v217, 0
	s_and_saveexec_b64 s[82:83], vcc
	s_cbranch_execz .Lidxp_e23
	s_waitcnt lgkmcnt(0)
	v_mfma_f32_32x32x16_bf16 v[18:33], v[38:41], v[58:61], 0
	v_max_f32_e32 v2, 0, v2
	v_max_f32_e32 v3, 0, v3
	v_fma_f32 v2, v174, v2, 0
	v_max_f32_e32 v4, 0, v4
	v_fmac_f32_e32 v2, v173, v3
	v_max_f32_e32 v5, 0, v5
	v_fmac_f32_e32 v2, v172, v4
	v_max_f32_e32 v6, 0, v6
	v_fmac_f32_e32 v2, v171, v5
	v_max_f32_e32 v7, 0, v7
	v_mfma_f32_32x32x16_bf16 v[18:33], v[46:49], v[54:57], v[18:33]
	v_fmac_f32_e32 v2, v170, v6
	v_max_f32_e32 v8, 0, v8
	v_fmac_f32_e32 v2, v169, v7
	v_max_f32_e32 v9, 0, v9
	v_fmac_f32_e32 v2, v168, v8
	v_max_f32_e32 v10, 0, v10
	v_fmac_f32_e32 v2, v167, v9
	v_max_f32_e32 v11, 0, v11
	v_fmac_f32_e32 v2, v166, v10
	v_max_f32_e32 v12, 0, v12
	v_mfma_f32_32x32x16_bf16 v[18:33], v[34:37], v[50:53], v[18:33]
	v_fmac_f32_e32 v2, v165, v11
	v_max_f32_e32 v13, 0, v13
	v_fmac_f32_e32 v2, v164, v12
	v_max_f32_e32 v14, 0, v14
	v_fmac_f32_e32 v2, v163, v13
	v_fmac_f32_e32 v2, v162, v14
	v_max_f32_e32 v3, 0, v15
	v_fmac_f32_e32 v2, v161, v3
	v_max_f32_e32 v3, 0, v16
	v_fmac_f32_e32 v2, v160, v3
	v_mfma_f32_32x32x16_bf16 v[18:33], v[42:45], v[62:65], v[18:33]
	ds_read_b128 v[58:61], v74 offset:24576
	ds_read_b128 v[54:57], v75 offset:24576
	ds_read_b128 v[50:53], v76 offset:24576
	ds_read_b128 v[62:65], v77 offset:24576
	v_max_f32_e32 v3, 0, v17
	v_fmac_f32_e32 v2, v89, v3
	v_not_b32_e32 v3, v2
	v_or_b32_e32 v4, 0x80000000, v2
	v_cmp_gt_i32_e32 vcc, 0, v2
	s_nop 1
	v_cndmask_b32_e32 v2, v4, v3, vcc
	v_cmp_le_u32_e32 vcc, v117, v87
	s_nop 1
	v_cndmask_b32_e32 v216, 0, v2, vcc
.LBB0_493:
	s_or_b64 exec, exec, s[82:83]
	s_movk_i32 s2, 0x2ff
	v_cmp_lt_u32_e32 vcc, s2, v177
	v_mov_b32_e32 v218, 0
	s_and_saveexec_b64 s[82:83], vcc
	s_cbranch_execz .Lidxp_e24
	s_waitcnt lgkmcnt(0)
	v_mfma_f32_32x32x16_bf16 v[2:17], v[38:41], v[58:61], 0
	v_max_f32_e32 v18, 0, v18
	v_max_f32_e32 v19, 0, v19
	v_fma_f32 v18, v174, v18, 0
	v_max_f32_e32 v20, 0, v20
	v_fmac_f32_e32 v18, v173, v19
	v_max_f32_e32 v21, 0, v21
	v_fmac_f32_e32 v18, v172, v20
	v_max_f32_e32 v22, 0, v22
	v_fmac_f32_e32 v18, v171, v21
	v_max_f32_e32 v23, 0, v23
	v_mfma_f32_32x32x16_bf16 v[2:17], v[46:49], v[54:57], v[2:17]
	v_fmac_f32_e32 v18, v170, v22
	v_max_f32_e32 v24, 0, v24
	v_fmac_f32_e32 v18, v169, v23
	v_max_f32_e32 v25, 0, v25
	v_fmac_f32_e32 v18, v168, v24
	v_max_f32_e32 v26, 0, v26
	v_fmac_f32_e32 v18, v167, v25
	v_max_f32_e32 v27, 0, v27
	v_fmac_f32_e32 v18, v166, v26
	v_max_f32_e32 v28, 0, v28
	v_mfma_f32_32x32x16_bf16 v[2:17], v[34:37], v[50:53], v[2:17]
	v_fmac_f32_e32 v18, v165, v27
	v_max_f32_e32 v29, 0, v29
	v_fmac_f32_e32 v18, v164, v28
	v_max_f32_e32 v30, 0, v30
	v_fmac_f32_e32 v18, v163, v29
	v_fmac_f32_e32 v18, v162, v30
	v_max_f32_e32 v19, 0, v31
	v_fmac_f32_e32 v18, v161, v19
	v_max_f32_e32 v19, 0, v32
	v_fmac_f32_e32 v18, v160, v19
	v_mfma_f32_32x32x16_bf16 v[2:17], v[42:45], v[62:65], v[2:17]
	ds_read_b128 v[58:61], v74 offset:28672
	ds_read_b128 v[54:57], v75 offset:28672
	ds_read_b128 v[50:53], v76 offset:28672
	ds_read_b128 v[62:65], v77 offset:28672
	v_max_f32_e32 v19, 0, v33
	v_fmac_f32_e32 v18, v89, v19
	v_not_b32_e32 v19, v18
	v_or_b32_e32 v20, 0x80000000, v18
	v_cmp_gt_i32_e32 vcc, 0, v18
	s_nop 1
	v_cndmask_b32_e32 v18, v20, v19, vcc
	v_cmp_le_u32_e32 vcc, v118, v87
	s_nop 1
	v_cndmask_b32_e32 v217, 0, v18, vcc
.LBB0_497:
	s_or_b64 exec, exec, s[82:83]
	s_movk_i32 s2, 0x31f
	v_cmp_lt_u32_e32 vcc, s2, v177
	v_mov_b32_e32 v219, 0
	s_and_saveexec_b64 s[82:83], vcc
	s_cbranch_execz .Lidxp_e25
	s_waitcnt lgkmcnt(0)
	s_waitcnt vmcnt(0)
	s_barrier
	v_cmp_le_u32_e32 vcc, v79, v80
	s_and_b64 vcc, exec, vcc
	s_cbranch_vccz .Lidxd_s3
	s_nop 0
	global_load_lds_dwordx4 v72, s[100:101]
	s_add_u32 m0, m0, 0x400
	s_add_u32 s100, s100, 0x1a000
	s_addc_u32 s101, s101, 0
	s_nop 0
	global_load_lds_dwordx4 v73, s[100:101]
	s_add_u32 m0, m0, 0x400
	s_add_u32 s100, s100, 0x1a000
	s_addc_u32 s101, s101, 0
	s_nop 0
	global_load_lds_dwordx4 v72, s[100:101]
	s_add_u32 m0, m0, 0x400
	s_add_u32 s100, s100, 0x1a000
	s_addc_u32 s101, s101, 0
	s_nop 0
	global_load_lds_dwordx4 v73, s[100:101]
	s_add_u32 m0, m0, 0x400
	s_add_u32 s100, s100, 0x1a000
	s_addc_u32 s101, s101, 0
	s_add_u32 m0, m0, 0x7000
	s_add_u32 s100, s100, 0x2d8000
	s_addc_u32 s101, s101, 0
	v_add_u32_e32 v79, 8, v79
.Lidxd_s3:
	v_mfma_f32_32x32x16_bf16 v[18:33], v[38:41], v[58:61], 0
	v_max_f32_e32 v2, 0, v2
	v_max_f32_e32 v3, 0, v3
	v_fma_f32 v2, v174, v2, 0
	v_max_f32_e32 v4, 0, v4
	v_fmac_f32_e32 v2, v173, v3
	v_max_f32_e32 v5, 0, v5
	v_fmac_f32_e32 v2, v172, v4
	v_max_f32_e32 v6, 0, v6
	v_fmac_f32_e32 v2, v171, v5
	v_max_f32_e32 v7, 0, v7
	v_mfma_f32_32x32x16_bf16 v[18:33], v[46:49], v[54:57], v[18:33]
	v_fmac_f32_e32 v2, v170, v6
	v_max_f32_e32 v8, 0, v8
	v_fmac_f32_e32 v2, v169, v7
	v_max_f32_e32 v9, 0, v9
	v_fmac_f32_e32 v2, v168, v8
	v_max_f32_e32 v10, 0, v10
	v_fmac_f32_e32 v2, v167, v9
	v_max_f32_e32 v11, 0, v11
	v_fmac_f32_e32 v2, v166, v10
	v_max_f32_e32 v12, 0, v12
	v_mfma_f32_32x32x16_bf16 v[18:33], v[34:37], v[50:53], v[18:33]
	v_fmac_f32_e32 v2, v165, v11
	v_max_f32_e32 v13, 0, v13
	v_fmac_f32_e32 v2, v164, v12
	v_max_f32_e32 v14, 0, v14
	v_fmac_f32_e32 v2, v163, v13
	v_fmac_f32_e32 v2, v162, v14
	v_max_f32_e32 v3, 0, v15
	v_fmac_f32_e32 v2, v161, v3
	v_max_f32_e32 v3, 0, v16
	v_fmac_f32_e32 v2, v160, v3
	v_mfma_f32_32x32x16_bf16 v[18:33], v[42:45], v[62:65], v[18:33]
	ds_read_b128 v[58:61], v74 offset:32768
	ds_read_b128 v[54:57], v75 offset:32768
	ds_read_b128 v[50:53], v76 offset:32768
	ds_read_b128 v[62:65], v77 offset:32768
	v_max_f32_e32 v3, 0, v17
	v_fmac_f32_e32 v2, v89, v3
	v_not_b32_e32 v3, v2
	v_or_b32_e32 v4, 0x80000000, v2
	v_cmp_gt_i32_e32 vcc, 0, v2
	s_nop 1
	v_cndmask_b32_e32 v2, v4, v3, vcc
	v_cmp_le_u32_e32 vcc, v119, v87
	s_nop 1
	v_cndmask_b32_e32 v218, 0, v2, vcc
.LBB0_501:
	s_or_b64 exec, exec, s[82:83]
	s_movk_i32 s2, 0x33f
	v_cmp_lt_u32_e32 vcc, s2, v177
	v_mov_b32_e32 v220, 0
	s_and_saveexec_b64 s[82:83], vcc
	s_cbranch_execz .Lidxp_e26
	s_waitcnt lgkmcnt(0)
	v_mfma_f32_32x32x16_bf16 v[2:17], v[38:41], v[58:61], 0
	v_max_f32_e32 v18, 0, v18
	v_max_f32_e32 v19, 0, v19
	v_fma_f32 v18, v174, v18, 0
	v_max_f32_e32 v20, 0, v20
	v_fmac_f32_e32 v18, v173, v19
	v_max_f32_e32 v21, 0, v21
	v_fmac_f32_e32 v18, v172, v20
	v_max_f32_e32 v22, 0, v22
	v_fmac_f32_e32 v18, v171, v21
	v_max_f32_e32 v23, 0, v23
	v_mfma_f32_32x32x16_bf16 v[2:17], v[46:49], v[54:57], v[2:17]
	v_fmac_f32_e32 v18, v170, v22
	v_max_f32_e32 v24, 0, v24
	v_fmac_f32_e32 v18, v169, v23
	v_max_f32_e32 v25, 0, v25
	v_fmac_f32_e32 v18, v168, v24
	v_max_f32_e32 v26, 0, v26
	v_fmac_f32_e32 v18, v167, v25
	v_max_f32_e32 v27, 0, v27
	v_fmac_f32_e32 v18, v166, v26
	v_max_f32_e32 v28, 0, v28
	v_mfma_f32_32x32x16_bf16 v[2:17], v[34:37], v[50:53], v[2:17]
	v_fmac_f32_e32 v18, v165, v27
	v_max_f32_e32 v29, 0, v29
	v_fmac_f32_e32 v18, v164, v28
	v_max_f32_e32 v30, 0, v30
	v_fmac_f32_e32 v18, v163, v29
	v_fmac_f32_e32 v18, v162, v30
	v_max_f32_e32 v19, 0, v31
	v_fmac_f32_e32 v18, v161, v19
	v_max_f32_e32 v19, 0, v32
	v_fmac_f32_e32 v18, v160, v19
	v_mfma_f32_32x32x16_bf16 v[2:17], v[42:45], v[62:65], v[2:17]
	ds_read_b128 v[58:61], v74 offset:36864
	ds_read_b128 v[54:57], v75 offset:36864
	ds_read_b128 v[50:53], v76 offset:36864
	ds_read_b128 v[62:65], v77 offset:36864
	v_max_f32_e32 v19, 0, v33
	v_fmac_f32_e32 v18, v89, v19
	v_not_b32_e32 v19, v18
	v_or_b32_e32 v20, 0x80000000, v18
	v_cmp_gt_i32_e32 vcc, 0, v18
	s_nop 1
	v_cndmask_b32_e32 v18, v20, v19, vcc
	v_cmp_le_u32_e32 vcc, v120, v87
	s_nop 1
	v_cndmask_b32_e32 v219, 0, v18, vcc
.LBB0_505:
	s_or_b64 exec, exec, s[82:83]
	s_movk_i32 s2, 0x35f
	v_cmp_lt_u32_e32 vcc, s2, v177
	v_mov_b32_e32 v221, 0
	s_and_saveexec_b64 s[82:83], vcc
	s_cbranch_execz .Lidxp_e27
	s_waitcnt lgkmcnt(0)
	v_mfma_f32_32x32x16_bf16 v[18:33], v[38:41], v[58:61], 0
	v_max_f32_e32 v2, 0, v2
	v_max_f32_e32 v3, 0, v3
	v_fma_f32 v2, v174, v2, 0
	v_max_f32_e32 v4, 0, v4
	v_fmac_f32_e32 v2, v173, v3
	v_max_f32_e32 v5, 0, v5
	v_fmac_f32_e32 v2, v172, v4
	v_max_f32_e32 v6, 0, v6
	v_fmac_f32_e32 v2, v171, v5
	v_max_f32_e32 v7, 0, v7
	v_mfma_f32_32x32x16_bf16 v[18:33], v[46:49], v[54:57], v[18:33]
	v_fmac_f32_e32 v2, v170, v6
	v_max_f32_e32 v8, 0, v8
	v_fmac_f32_e32 v2, v169, v7
	v_max_f32_e32 v9, 0, v9
	v_fmac_f32_e32 v2, v168, v8
	v_max_f32_e32 v10, 0, v10
	v_fmac_f32_e32 v2, v167, v9
	v_max_f32_e32 v11, 0, v11
	v_fmac_f32_e32 v2, v166, v10
	v_max_f32_e32 v12, 0, v12
	v_mfma_f32_32x32x16_bf16 v[18:33], v[34:37], v[50:53], v[18:33]
	v_fmac_f32_e32 v2, v165, v11
	v_max_f32_e32 v13, 0, v13
	v_fmac_f32_e32 v2, v164, v12
	v_max_f32_e32 v14, 0, v14
	v_fmac_f32_e32 v2, v163, v13
	v_fmac_f32_e32 v2, v162, v14
	v_max_f32_e32 v3, 0, v15
	v_fmac_f32_e32 v2, v161, v3
	v_max_f32_e32 v3, 0, v16
	v_fmac_f32_e32 v2, v160, v3
	v_mfma_f32_32x32x16_bf16 v[18:33], v[42:45], v[62:65], v[18:33]
	ds_read_b128 v[58:61], v74 offset:40960
	ds_read_b128 v[54:57], v75 offset:40960
	ds_read_b128 v[50:53], v76 offset:40960
	ds_read_b128 v[62:65], v77 offset:40960
	v_max_f32_e32 v3, 0, v17
	v_fmac_f32_e32 v2, v89, v3
	v_not_b32_e32 v3, v2
	v_or_b32_e32 v4, 0x80000000, v2
	v_cmp_gt_i32_e32 vcc, 0, v2
	s_nop 1
	v_cndmask_b32_e32 v2, v4, v3, vcc
	v_cmp_le_u32_e32 vcc, v121, v87
	s_nop 1
	v_cndmask_b32_e32 v220, 0, v2, vcc
.LBB0_509:
	s_or_b64 exec, exec, s[82:83]
	s_movk_i32 s2, 0x37f
	v_cmp_lt_u32_e32 vcc, s2, v177
	v_mov_b32_e32 v222, 0
	s_and_saveexec_b64 s[82:83], vcc
	s_cbranch_execz .Lidxp_e28
	s_waitcnt lgkmcnt(0)
	v_mfma_f32_32x32x16_bf16 v[2:17], v[38:41], v[58:61], 0
	v_max_f32_e32 v18, 0, v18
	v_max_f32_e32 v19, 0, v19
	v_fma_f32 v18, v174, v18, 0
	v_max_f32_e32 v20, 0, v20
	v_fmac_f32_e32 v18, v173, v19
	v_max_f32_e32 v21, 0, v21
	v_fmac_f32_e32 v18, v172, v20
	v_max_f32_e32 v22, 0, v22
	v_fmac_f32_e32 v18, v171, v21
	v_max_f32_e32 v23, 0, v23
	v_mfma_f32_32x32x16_bf16 v[2:17], v[46:49], v[54:57], v[2:17]
	v_fmac_f32_e32 v18, v170, v22
	v_max_f32_e32 v24, 0, v24
	v_fmac_f32_e32 v18, v169, v23
	v_max_f32_e32 v25, 0, v25
	v_fmac_f32_e32 v18, v168, v24
	v_max_f32_e32 v26, 0, v26
	v_fmac_f32_e32 v18, v167, v25
	v_max_f32_e32 v27, 0, v27
	v_fmac_f32_e32 v18, v166, v26
	v_max_f32_e32 v28, 0, v28
	v_mfma_f32_32x32x16_bf16 v[2:17], v[34:37], v[50:53], v[2:17]
	v_fmac_f32_e32 v18, v165, v27
	v_max_f32_e32 v29, 0, v29
	v_fmac_f32_e32 v18, v164, v28
	v_max_f32_e32 v30, 0, v30
	v_fmac_f32_e32 v18, v163, v29
	v_fmac_f32_e32 v18, v162, v30
	v_max_f32_e32 v19, 0, v31
	v_fmac_f32_e32 v18, v161, v19
	v_max_f32_e32 v19, 0, v32
	v_fmac_f32_e32 v18, v160, v19
	v_mfma_f32_32x32x16_bf16 v[2:17], v[42:45], v[62:65], v[2:17]
	ds_read_b128 v[58:61], v74 offset:45056
	ds_read_b128 v[54:57], v75 offset:45056
	ds_read_b128 v[50:53], v76 offset:45056
	ds_read_b128 v[62:65], v77 offset:45056
	v_max_f32_e32 v19, 0, v33
	v_fmac_f32_e32 v18, v89, v19
	v_not_b32_e32 v19, v18
	v_or_b32_e32 v20, 0x80000000, v18
	v_cmp_gt_i32_e32 vcc, 0, v18
	s_nop 1
	v_cndmask_b32_e32 v18, v20, v19, vcc
	v_cmp_le_u32_e32 vcc, v122, v87
	s_nop 1
	v_cndmask_b32_e32 v221, 0, v18, vcc
.LBB0_513:
	s_or_b64 exec, exec, s[82:83]
	s_movk_i32 s2, 0x39f
	v_cmp_lt_u32_e32 vcc, s2, v177
	v_mov_b32_e32 v223, 0
	s_and_saveexec_b64 s[82:83], vcc
	s_cbranch_execz .Lidxp_e29
	s_waitcnt lgkmcnt(0)
	v_mfma_f32_32x32x16_bf16 v[18:33], v[38:41], v[58:61], 0
	v_max_f32_e32 v2, 0, v2
	v_max_f32_e32 v3, 0, v3
	v_fma_f32 v2, v174, v2, 0
	v_max_f32_e32 v4, 0, v4
	v_fmac_f32_e32 v2, v173, v3
	v_max_f32_e32 v5, 0, v5
	v_fmac_f32_e32 v2, v172, v4
	v_max_f32_e32 v6, 0, v6
	v_fmac_f32_e32 v2, v171, v5
	v_max_f32_e32 v7, 0, v7
	v_mfma_f32_32x32x16_bf16 v[18:33], v[46:49], v[54:57], v[18:33]
	v_fmac_f32_e32 v2, v170, v6
	v_max_f32_e32 v8, 0, v8
	v_fmac_f32_e32 v2, v169, v7
	v_max_f32_e32 v9, 0, v9
	v_fmac_f32_e32 v2, v168, v8
	v_max_f32_e32 v10, 0, v10
	v_fmac_f32_e32 v2, v167, v9
	v_max_f32_e32 v11, 0, v11
	v_fmac_f32_e32 v2, v166, v10
	v_max_f32_e32 v12, 0, v12
	v_mfma_f32_32x32x16_bf16 v[18:33], v[34:37], v[50:53], v[18:33]
	v_fmac_f32_e32 v2, v165, v11
	v_max_f32_e32 v13, 0, v13
	v_fmac_f32_e32 v2, v164, v12
	v_max_f32_e32 v14, 0, v14
	v_fmac_f32_e32 v2, v163, v13
	v_fmac_f32_e32 v2, v162, v14
	v_max_f32_e32 v3, 0, v15
	v_fmac_f32_e32 v2, v161, v3
	v_max_f32_e32 v3, 0, v16
	v_fmac_f32_e32 v2, v160, v3
	v_mfma_f32_32x32x16_bf16 v[18:33], v[42:45], v[62:65], v[18:33]
	ds_read_b128 v[58:61], v74 offset:49152
	ds_read_b128 v[54:57], v75 offset:49152
	ds_read_b128 v[50:53], v76 offset:49152
	ds_read_b128 v[62:65], v77 offset:49152
	v_max_f32_e32 v3, 0, v17
	v_fmac_f32_e32 v2, v89, v3
	v_not_b32_e32 v3, v2
	v_or_b32_e32 v4, 0x80000000, v2
	v_cmp_gt_i32_e32 vcc, 0, v2
	s_nop 1
	v_cndmask_b32_e32 v2, v4, v3, vcc
	v_cmp_le_u32_e32 vcc, v123, v87
	s_nop 1
	v_cndmask_b32_e32 v222, 0, v2, vcc
.LBB0_517:
	s_or_b64 exec, exec, s[82:83]
	s_movk_i32 s2, 0x3bf
	v_cmp_lt_u32_e32 vcc, s2, v177
	v_mov_b32_e32 v224, 0
	s_and_saveexec_b64 s[82:83], vcc
	s_cbranch_execz .Lidxp_e30
	s_waitcnt lgkmcnt(0)
	v_mfma_f32_32x32x16_bf16 v[2:17], v[38:41], v[58:61], 0
	v_max_f32_e32 v18, 0, v18
	v_max_f32_e32 v19, 0, v19
	v_fma_f32 v18, v174, v18, 0
	v_max_f32_e32 v20, 0, v20
	v_fmac_f32_e32 v18, v173, v19
	v_max_f32_e32 v21, 0, v21
	v_fmac_f32_e32 v18, v172, v20
	v_max_f32_e32 v22, 0, v22
	v_fmac_f32_e32 v18, v171, v21
	v_max_f32_e32 v23, 0, v23
	v_mfma_f32_32x32x16_bf16 v[2:17], v[46:49], v[54:57], v[2:17]
	v_fmac_f32_e32 v18, v170, v22
	v_max_f32_e32 v24, 0, v24
	v_fmac_f32_e32 v18, v169, v23
	v_max_f32_e32 v25, 0, v25
	v_fmac_f32_e32 v18, v168, v24
	v_max_f32_e32 v26, 0, v26
	v_fmac_f32_e32 v18, v167, v25
	v_max_f32_e32 v27, 0, v27
	v_fmac_f32_e32 v18, v166, v26
	v_max_f32_e32 v28, 0, v28
	v_mfma_f32_32x32x16_bf16 v[2:17], v[34:37], v[50:53], v[2:17]
	v_fmac_f32_e32 v18, v165, v27
	v_max_f32_e32 v29, 0, v29
	v_fmac_f32_e32 v18, v164, v28
	v_max_f32_e32 v30, 0, v30
	v_fmac_f32_e32 v18, v163, v29
	v_fmac_f32_e32 v18, v162, v30
	v_max_f32_e32 v19, 0, v31
	v_fmac_f32_e32 v18, v161, v19
	v_max_f32_e32 v19, 0, v32
	v_fmac_f32_e32 v18, v160, v19
	v_mfma_f32_32x32x16_bf16 v[2:17], v[42:45], v[62:65], v[2:17]
	ds_read_b128 v[58:61], v74 offset:53248
	ds_read_b128 v[54:57], v75 offset:53248
	ds_read_b128 v[50:53], v76 offset:53248
	ds_read_b128 v[62:65], v77 offset:53248
	v_max_f32_e32 v19, 0, v33
	v_fmac_f32_e32 v18, v89, v19
	v_not_b32_e32 v19, v18
	v_or_b32_e32 v20, 0x80000000, v18
	v_cmp_gt_i32_e32 vcc, 0, v18
	s_nop 1
	v_cndmask_b32_e32 v18, v20, v19, vcc
	v_cmp_le_u32_e32 vcc, v124, v87
	s_nop 1
	v_cndmask_b32_e32 v223, 0, v18, vcc
.LBB0_521:
	s_or_b64 exec, exec, s[82:83]
	s_movk_i32 s2, 0x3df
	v_cmp_lt_u32_e32 vcc, s2, v177
	v_mov_b32_e32 v225, 0
	s_and_saveexec_b64 s[82:83], vcc
	s_cbranch_execz .Lidxp_e31
	s_waitcnt lgkmcnt(0)
	v_mfma_f32_32x32x16_bf16 v[18:33], v[38:41], v[58:61], 0
	v_max_f32_e32 v2, 0, v2
	v_max_f32_e32 v3, 0, v3
	v_fma_f32 v2, v174, v2, 0
	v_max_f32_e32 v4, 0, v4
	v_fmac_f32_e32 v2, v173, v3
	v_max_f32_e32 v5, 0, v5
	v_fmac_f32_e32 v2, v172, v4
	v_max_f32_e32 v6, 0, v6
	v_fmac_f32_e32 v2, v171, v5
	v_max_f32_e32 v7, 0, v7
	v_mfma_f32_32x32x16_bf16 v[18:33], v[46:49], v[54:57], v[18:33]
	v_fmac_f32_e32 v2, v170, v6
	v_max_f32_e32 v8, 0, v8
	v_fmac_f32_e32 v2, v169, v7
	v_max_f32_e32 v9, 0, v9
	v_fmac_f32_e32 v2, v168, v8
	v_max_f32_e32 v10, 0, v10
	v_fmac_f32_e32 v2, v167, v9
	v_max_f32_e32 v11, 0, v11
	v_fmac_f32_e32 v2, v166, v10
	v_max_f32_e32 v12, 0, v12
	v_mfma_f32_32x32x16_bf16 v[18:33], v[34:37], v[50:53], v[18:33]
	v_fmac_f32_e32 v2, v165, v11
	v_max_f32_e32 v13, 0, v13
	v_fmac_f32_e32 v2, v164, v12
	v_max_f32_e32 v14, 0, v14
	v_fmac_f32_e32 v2, v163, v13
	v_fmac_f32_e32 v2, v162, v14
	v_max_f32_e32 v3, 0, v15
	v_fmac_f32_e32 v2, v161, v3
	v_max_f32_e32 v3, 0, v16
	v_fmac_f32_e32 v2, v160, v3
	v_mfma_f32_32x32x16_bf16 v[18:33], v[42:45], v[62:65], v[18:33]
	ds_read_b128 v[58:61], v74 offset:57344
	ds_read_b128 v[54:57], v75 offset:57344
	ds_read_b128 v[50:53], v76 offset:57344
	ds_read_b128 v[62:65], v77 offset:57344
	v_max_f32_e32 v3, 0, v17
	v_fmac_f32_e32 v2, v89, v3
	v_not_b32_e32 v3, v2
	v_or_b32_e32 v4, 0x80000000, v2
	v_cmp_gt_i32_e32 vcc, 0, v2
	s_nop 1
	v_cndmask_b32_e32 v2, v4, v3, vcc
	v_cmp_le_u32_e32 vcc, v125, v87
	s_nop 1
	v_cndmask_b32_e32 v224, 0, v2, vcc
.LBB0_525:
	s_or_b64 exec, exec, s[82:83]
	s_movk_i32 s2, 0x3ff
	v_cmp_lt_u32_e32 vcc, s2, v177
	v_mov_b32_e32 v226, 0
	s_and_saveexec_b64 s[82:83], vcc
	s_cbranch_execz .Lidxp_e32
	s_waitcnt lgkmcnt(0)
	v_mfma_f32_32x32x16_bf16 v[2:17], v[38:41], v[58:61], 0
	v_max_f32_e32 v18, 0, v18
	v_max_f32_e32 v19, 0, v19
	v_fma_f32 v18, v174, v18, 0
	v_max_f32_e32 v20, 0, v20
	v_fmac_f32_e32 v18, v173, v19
	v_max_f32_e32 v21, 0, v21
	v_fmac_f32_e32 v18, v172, v20
	v_max_f32_e32 v22, 0, v22
	v_fmac_f32_e32 v18, v171, v21
	v_max_f32_e32 v23, 0, v23
	v_mfma_f32_32x32x16_bf16 v[2:17], v[46:49], v[54:57], v[2:17]
	v_fmac_f32_e32 v18, v170, v22
	v_max_f32_e32 v24, 0, v24
	v_fmac_f32_e32 v18, v169, v23
	v_max_f32_e32 v25, 0, v25
	v_fmac_f32_e32 v18, v168, v24
	v_max_f32_e32 v26, 0, v26
	v_fmac_f32_e32 v18, v167, v25
	v_max_f32_e32 v27, 0, v27
	v_fmac_f32_e32 v18, v166, v26
	v_max_f32_e32 v28, 0, v28
	v_mfma_f32_32x32x16_bf16 v[2:17], v[34:37], v[50:53], v[2:17]
	v_fmac_f32_e32 v18, v165, v27
	v_max_f32_e32 v29, 0, v29
	v_fmac_f32_e32 v18, v164, v28
	v_max_f32_e32 v30, 0, v30
	v_fmac_f32_e32 v18, v163, v29
	v_fmac_f32_e32 v18, v162, v30
	v_max_f32_e32 v19, 0, v31
	v_fmac_f32_e32 v18, v161, v19
	v_max_f32_e32 v19, 0, v32
	v_fmac_f32_e32 v18, v160, v19
	v_mfma_f32_32x32x16_bf16 v[2:17], v[42:45], v[62:65], v[2:17]
	ds_read_b128 v[58:61], v74 offset:61440
	ds_read_b128 v[54:57], v75 offset:61440
	ds_read_b128 v[50:53], v76 offset:61440
	ds_read_b128 v[62:65], v77 offset:61440
	v_max_f32_e32 v19, 0, v33
	v_fmac_f32_e32 v18, v89, v19
	v_not_b32_e32 v19, v18
	v_or_b32_e32 v20, 0x80000000, v18
	v_cmp_gt_i32_e32 vcc, 0, v18
	s_nop 1
	v_cndmask_b32_e32 v18, v20, v19, vcc
	v_cmp_le_u32_e32 vcc, v126, v87
	s_nop 1
	v_cndmask_b32_e32 v225, 0, v18, vcc
.LBB0_529:
	s_or_b64 exec, exec, s[82:83]
	s_movk_i32 s2, 0x41f
	v_cmp_lt_u32_e32 vcc, s2, v177
	v_mov_b32_e32 v227, 0
	s_and_saveexec_b64 s[82:83], vcc
	s_cbranch_execz .Lidxp_e33
	s_waitcnt lgkmcnt(0)
	s_waitcnt vmcnt(0)
	s_barrier
	v_cmp_le_u32_e32 vcc, v79, v80
	s_and_b64 vcc, exec, vcc
	s_cbranch_vccz .Lidxd_s4
	s_nop 0
	global_load_lds_dwordx4 v72, s[100:101]
	s_add_u32 m0, m0, 0x400
	s_add_u32 s100, s100, 0x1a000
	s_addc_u32 s101, s101, 0
	s_nop 0
	global_load_lds_dwordx4 v73, s[100:101]
	s_add_u32 m0, m0, 0x400
	s_add_u32 s100, s100, 0x1a000
	s_addc_u32 s101, s101, 0
	s_nop 0
	global_load_lds_dwordx4 v72, s[100:101]
	s_add_u32 m0, m0, 0x400
	s_add_u32 s100, s100, 0x1a000
	s_addc_u32 s101, s101, 0
	s_nop 0
	global_load_lds_dwordx4 v73, s[100:101]
	s_add_u32 m0, m0, 0x400
	s_add_u32 s100, s100, 0x1a000
	s_addc_u32 s101, s101, 0
	s_sub_u32 m0, m0, 0x9000
	s_add_u32 s100, s100, 0x2d8000
	s_addc_u32 s101, s101, 0
	v_add_u32_e32 v79, 8, v79
.Lidxd_s4:
	v_mfma_f32_32x32x16_bf16 v[18:33], v[38:41], v[58:61], 0
	v_max_f32_e32 v2, 0, v2
	v_max_f32_e32 v3, 0, v3
	v_fma_f32 v2, v174, v2, 0
	v_max_f32_e32 v4, 0, v4
	v_fmac_f32_e32 v2, v173, v3
	v_max_f32_e32 v5, 0, v5
	v_fmac_f32_e32 v2, v172, v4
	v_max_f32_e32 v6, 0, v6
	v_fmac_f32_e32 v2, v171, v5
	v_max_f32_e32 v7, 0, v7
	v_mfma_f32_32x32x16_bf16 v[18:33], v[46:49], v[54:57], v[18:33]
	v_fmac_f32_e32 v2, v170, v6
	v_max_f32_e32 v8, 0, v8
	v_fmac_f32_e32 v2, v169, v7
	v_max_f32_e32 v9, 0, v9
	v_fmac_f32_e32 v2, v168, v8
	v_max_f32_e32 v10, 0, v10
	v_fmac_f32_e32 v2, v167, v9
	v_max_f32_e32 v11, 0, v11
	v_fmac_f32_e32 v2, v166, v10
	v_max_f32_e32 v12, 0, v12
	v_mfma_f32_32x32x16_bf16 v[18:33], v[34:37], v[50:53], v[18:33]
	v_fmac_f32_e32 v2, v165, v11
	v_max_f32_e32 v13, 0, v13
	v_fmac_f32_e32 v2, v164, v12
	v_max_f32_e32 v14, 0, v14
	v_fmac_f32_e32 v2, v163, v13
	v_fmac_f32_e32 v2, v162, v14
	v_max_f32_e32 v3, 0, v15
	v_fmac_f32_e32 v2, v161, v3
	v_max_f32_e32 v3, 0, v16
	v_fmac_f32_e32 v2, v160, v3
	v_mfma_f32_32x32x16_bf16 v[18:33], v[42:45], v[62:65], v[18:33]
	ds_read_b128 v[58:61], v74 offset:0
	ds_read_b128 v[54:57], v75 offset:0
	ds_read_b128 v[50:53], v76 offset:0
	ds_read_b128 v[62:65], v77 offset:0
	v_max_f32_e32 v3, 0, v17
	v_fmac_f32_e32 v2, v89, v3
	v_not_b32_e32 v3, v2
	v_or_b32_e32 v4, 0x80000000, v2
	v_cmp_gt_i32_e32 vcc, 0, v2
	s_nop 1
	v_cndmask_b32_e32 v2, v4, v3, vcc
	v_cmp_le_u32_e32 vcc, v127, v87
	s_nop 1
	v_cndmask_b32_e32 v226, 0, v2, vcc
.LBB0_533:
	s_or_b64 exec, exec, s[82:83]
	s_movk_i32 s2, 0x43f
	v_cmp_lt_u32_e32 vcc, s2, v177
	v_mov_b32_e32 v228, 0
	s_and_saveexec_b64 s[82:83], vcc
	s_cbranch_execz .Lidxp_e34
	s_waitcnt lgkmcnt(0)
	v_mfma_f32_32x32x16_bf16 v[2:17], v[38:41], v[58:61], 0
	v_max_f32_e32 v18, 0, v18
	v_max_f32_e32 v19, 0, v19
	v_fma_f32 v18, v174, v18, 0
	v_max_f32_e32 v20, 0, v20
	v_fmac_f32_e32 v18, v173, v19
	v_max_f32_e32 v21, 0, v21
	v_fmac_f32_e32 v18, v172, v20
	v_max_f32_e32 v22, 0, v22
	v_fmac_f32_e32 v18, v171, v21
	v_max_f32_e32 v23, 0, v23
	v_mfma_f32_32x32x16_bf16 v[2:17], v[46:49], v[54:57], v[2:17]
	v_fmac_f32_e32 v18, v170, v22
	v_max_f32_e32 v24, 0, v24
	v_fmac_f32_e32 v18, v169, v23
	v_max_f32_e32 v25, 0, v25
	v_fmac_f32_e32 v18, v168, v24
	v_max_f32_e32 v26, 0, v26
	v_fmac_f32_e32 v18, v167, v25
	v_max_f32_e32 v27, 0, v27
	v_fmac_f32_e32 v18, v166, v26
	v_max_f32_e32 v28, 0, v28
	v_mfma_f32_32x32x16_bf16 v[2:17], v[34:37], v[50:53], v[2:17]
	v_fmac_f32_e32 v18, v165, v27
	v_max_f32_e32 v29, 0, v29
	v_fmac_f32_e32 v18, v164, v28
	v_max_f32_e32 v30, 0, v30
	v_fmac_f32_e32 v18, v163, v29
	v_fmac_f32_e32 v18, v162, v30
	v_max_f32_e32 v19, 0, v31
	v_fmac_f32_e32 v18, v161, v19
	v_max_f32_e32 v19, 0, v32
	v_fmac_f32_e32 v18, v160, v19
	v_mfma_f32_32x32x16_bf16 v[2:17], v[42:45], v[62:65], v[2:17]
	ds_read_b128 v[58:61], v74 offset:4096
	ds_read_b128 v[54:57], v75 offset:4096
	ds_read_b128 v[50:53], v76 offset:4096
	ds_read_b128 v[62:65], v77 offset:4096
	v_max_f32_e32 v19, 0, v33
	v_fmac_f32_e32 v18, v89, v19
	v_not_b32_e32 v19, v18
	v_or_b32_e32 v20, 0x80000000, v18
	v_cmp_gt_i32_e32 vcc, 0, v18
	s_nop 1
	v_cndmask_b32_e32 v18, v20, v19, vcc
	v_cmp_le_u32_e32 vcc, v128, v87
	s_nop 1
	v_cndmask_b32_e32 v227, 0, v18, vcc
.LBB0_537:
	s_or_b64 exec, exec, s[82:83]
	s_movk_i32 s2, 0x45f
	v_cmp_lt_u32_e32 vcc, s2, v177
	v_mov_b32_e32 v229, 0
	s_and_saveexec_b64 s[82:83], vcc
	s_cbranch_execz .Lidxp_e35
	s_waitcnt lgkmcnt(0)
	v_mfma_f32_32x32x16_bf16 v[18:33], v[38:41], v[58:61], 0
	v_max_f32_e32 v2, 0, v2
	v_max_f32_e32 v3, 0, v3
	v_fma_f32 v2, v174, v2, 0
	v_max_f32_e32 v4, 0, v4
	v_fmac_f32_e32 v2, v173, v3
	v_max_f32_e32 v5, 0, v5
	v_fmac_f32_e32 v2, v172, v4
	v_max_f32_e32 v6, 0, v6
	v_fmac_f32_e32 v2, v171, v5
	v_max_f32_e32 v7, 0, v7
	v_mfma_f32_32x32x16_bf16 v[18:33], v[46:49], v[54:57], v[18:33]
	v_fmac_f32_e32 v2, v170, v6
	v_max_f32_e32 v8, 0, v8
	v_fmac_f32_e32 v2, v169, v7
	v_max_f32_e32 v9, 0, v9
	v_fmac_f32_e32 v2, v168, v8
	v_max_f32_e32 v10, 0, v10
	v_fmac_f32_e32 v2, v167, v9
	v_max_f32_e32 v11, 0, v11
	v_fmac_f32_e32 v2, v166, v10
	v_max_f32_e32 v12, 0, v12
	v_mfma_f32_32x32x16_bf16 v[18:33], v[34:37], v[50:53], v[18:33]
	v_fmac_f32_e32 v2, v165, v11
	v_max_f32_e32 v13, 0, v13
	v_fmac_f32_e32 v2, v164, v12
	v_max_f32_e32 v14, 0, v14
	v_fmac_f32_e32 v2, v163, v13
	v_fmac_f32_e32 v2, v162, v14
	v_max_f32_e32 v3, 0, v15
	v_fmac_f32_e32 v2, v161, v3
	v_max_f32_e32 v3, 0, v16
	v_fmac_f32_e32 v2, v160, v3
	v_mfma_f32_32x32x16_bf16 v[18:33], v[42:45], v[62:65], v[18:33]
	ds_read_b128 v[58:61], v74 offset:8192
	ds_read_b128 v[54:57], v75 offset:8192
	ds_read_b128 v[50:53], v76 offset:8192
	ds_read_b128 v[62:65], v77 offset:8192
	v_max_f32_e32 v3, 0, v17
	v_fmac_f32_e32 v2, v89, v3
	v_not_b32_e32 v3, v2
	v_or_b32_e32 v4, 0x80000000, v2
	v_cmp_gt_i32_e32 vcc, 0, v2
	s_nop 1
	v_cndmask_b32_e32 v2, v4, v3, vcc
	v_cmp_le_u32_e32 vcc, v129, v87
	s_nop 1
	v_cndmask_b32_e32 v228, 0, v2, vcc
.LBB0_541:
	s_or_b64 exec, exec, s[82:83]
	s_movk_i32 s2, 0x47f
	v_cmp_lt_u32_e32 vcc, s2, v177
	v_mov_b32_e32 v230, 0
	s_and_saveexec_b64 s[82:83], vcc
	s_cbranch_execz .Lidxp_e36
	s_waitcnt lgkmcnt(0)
	v_mfma_f32_32x32x16_bf16 v[2:17], v[38:41], v[58:61], 0
	v_max_f32_e32 v18, 0, v18
	v_max_f32_e32 v19, 0, v19
	v_fma_f32 v18, v174, v18, 0
	v_max_f32_e32 v20, 0, v20
	v_fmac_f32_e32 v18, v173, v19
	v_max_f32_e32 v21, 0, v21
	v_fmac_f32_e32 v18, v172, v20
	v_max_f32_e32 v22, 0, v22
	v_fmac_f32_e32 v18, v171, v21
	v_max_f32_e32 v23, 0, v23
	v_mfma_f32_32x32x16_bf16 v[2:17], v[46:49], v[54:57], v[2:17]
	v_fmac_f32_e32 v18, v170, v22
	v_max_f32_e32 v24, 0, v24
	v_fmac_f32_e32 v18, v169, v23
	v_max_f32_e32 v25, 0, v25
	v_fmac_f32_e32 v18, v168, v24
	v_max_f32_e32 v26, 0, v26
	v_fmac_f32_e32 v18, v167, v25
	v_max_f32_e32 v27, 0, v27
	v_fmac_f32_e32 v18, v166, v26
	v_max_f32_e32 v28, 0, v28
	v_mfma_f32_32x32x16_bf16 v[2:17], v[34:37], v[50:53], v[2:17]
	v_fmac_f32_e32 v18, v165, v27
	v_max_f32_e32 v29, 0, v29
	v_fmac_f32_e32 v18, v164, v28
	v_max_f32_e32 v30, 0, v30
	v_fmac_f32_e32 v18, v163, v29
	v_fmac_f32_e32 v18, v162, v30
	v_max_f32_e32 v19, 0, v31
	v_fmac_f32_e32 v18, v161, v19
	v_max_f32_e32 v19, 0, v32
	v_fmac_f32_e32 v18, v160, v19
	v_mfma_f32_32x32x16_bf16 v[2:17], v[42:45], v[62:65], v[2:17]
	ds_read_b128 v[58:61], v74 offset:12288
	ds_read_b128 v[54:57], v75 offset:12288
	ds_read_b128 v[50:53], v76 offset:12288
	ds_read_b128 v[62:65], v77 offset:12288
	v_max_f32_e32 v19, 0, v33
	v_fmac_f32_e32 v18, v89, v19
	v_not_b32_e32 v19, v18
	v_or_b32_e32 v20, 0x80000000, v18
	v_cmp_gt_i32_e32 vcc, 0, v18
	s_nop 1
	v_cndmask_b32_e32 v18, v20, v19, vcc
	v_cmp_le_u32_e32 vcc, v130, v87
	s_nop 1
	v_cndmask_b32_e32 v229, 0, v18, vcc
.LBB0_545:
	s_or_b64 exec, exec, s[82:83]
	s_movk_i32 s2, 0x49f
	v_cmp_lt_u32_e32 vcc, s2, v177
	v_mov_b32_e32 v231, 0
	s_and_saveexec_b64 s[82:83], vcc
	s_cbranch_execz .Lidxp_e37
	s_waitcnt lgkmcnt(0)
	v_mfma_f32_32x32x16_bf16 v[18:33], v[38:41], v[58:61], 0
	v_max_f32_e32 v2, 0, v2
	v_max_f32_e32 v3, 0, v3
	v_fma_f32 v2, v174, v2, 0
	v_max_f32_e32 v4, 0, v4
	v_fmac_f32_e32 v2, v173, v3
	v_max_f32_e32 v5, 0, v5
	v_fmac_f32_e32 v2, v172, v4
	v_max_f32_e32 v6, 0, v6
	v_fmac_f32_e32 v2, v171, v5
	v_max_f32_e32 v7, 0, v7
	v_mfma_f32_32x32x16_bf16 v[18:33], v[46:49], v[54:57], v[18:33]
	v_fmac_f32_e32 v2, v170, v6
	v_max_f32_e32 v8, 0, v8
	v_fmac_f32_e32 v2, v169, v7
	v_max_f32_e32 v9, 0, v9
	v_fmac_f32_e32 v2, v168, v8
	v_max_f32_e32 v10, 0, v10
	v_fmac_f32_e32 v2, v167, v9
	v_max_f32_e32 v11, 0, v11
	v_fmac_f32_e32 v2, v166, v10
	v_max_f32_e32 v12, 0, v12
	v_mfma_f32_32x32x16_bf16 v[18:33], v[34:37], v[50:53], v[18:33]
	v_fmac_f32_e32 v2, v165, v11
	v_max_f32_e32 v13, 0, v13
	v_fmac_f32_e32 v2, v164, v12
	v_max_f32_e32 v14, 0, v14
	v_fmac_f32_e32 v2, v163, v13
	v_fmac_f32_e32 v2, v162, v14
	v_max_f32_e32 v3, 0, v15
	v_fmac_f32_e32 v2, v161, v3
	v_max_f32_e32 v3, 0, v16
	v_fmac_f32_e32 v2, v160, v3
	v_mfma_f32_32x32x16_bf16 v[18:33], v[42:45], v[62:65], v[18:33]
	ds_read_b128 v[58:61], v74 offset:16384
	ds_read_b128 v[54:57], v75 offset:16384
	ds_read_b128 v[50:53], v76 offset:16384
	ds_read_b128 v[62:65], v77 offset:16384
	v_max_f32_e32 v3, 0, v17
	v_fmac_f32_e32 v2, v89, v3
	v_not_b32_e32 v3, v2
	v_or_b32_e32 v4, 0x80000000, v2
	v_cmp_gt_i32_e32 vcc, 0, v2
	s_nop 1
	v_cndmask_b32_e32 v2, v4, v3, vcc
	v_cmp_le_u32_e32 vcc, v131, v87
	s_nop 1
	v_cndmask_b32_e32 v230, 0, v2, vcc
.LBB0_549:
	s_or_b64 exec, exec, s[82:83]
	s_movk_i32 s2, 0x4bf
	v_cmp_lt_u32_e32 vcc, s2, v177
	v_mov_b32_e32 v232, 0
	s_and_saveexec_b64 s[82:83], vcc
	s_cbranch_execz .Lidxp_e38
	s_waitcnt lgkmcnt(0)
	v_mfma_f32_32x32x16_bf16 v[2:17], v[38:41], v[58:61], 0
	v_max_f32_e32 v18, 0, v18
	v_max_f32_e32 v19, 0, v19
	v_fma_f32 v18, v174, v18, 0
	v_max_f32_e32 v20, 0, v20
	v_fmac_f32_e32 v18, v173, v19
	v_max_f32_e32 v21, 0, v21
	v_fmac_f32_e32 v18, v172, v20
	v_max_f32_e32 v22, 0, v22
	v_fmac_f32_e32 v18, v171, v21
	v_max_f32_e32 v23, 0, v23
	v_mfma_f32_32x32x16_bf16 v[2:17], v[46:49], v[54:57], v[2:17]
	v_fmac_f32_e32 v18, v170, v22
	v_max_f32_e32 v24, 0, v24
	v_fmac_f32_e32 v18, v169, v23
	v_max_f32_e32 v25, 0, v25
	v_fmac_f32_e32 v18, v168, v24
	v_max_f32_e32 v26, 0, v26
	v_fmac_f32_e32 v18, v167, v25
	v_max_f32_e32 v27, 0, v27
	v_fmac_f32_e32 v18, v166, v26
	v_max_f32_e32 v28, 0, v28
	v_mfma_f32_32x32x16_bf16 v[2:17], v[34:37], v[50:53], v[2:17]
	v_fmac_f32_e32 v18, v165, v27
	v_max_f32_e32 v29, 0, v29
	v_fmac_f32_e32 v18, v164, v28
	v_max_f32_e32 v30, 0, v30
	v_fmac_f32_e32 v18, v163, v29
	v_fmac_f32_e32 v18, v162, v30
	v_max_f32_e32 v19, 0, v31
	v_fmac_f32_e32 v18, v161, v19
	v_max_f32_e32 v19, 0, v32
	v_fmac_f32_e32 v18, v160, v19
	v_mfma_f32_32x32x16_bf16 v[2:17], v[42:45], v[62:65], v[2:17]
	ds_read_b128 v[58:61], v74 offset:20480
	ds_read_b128 v[54:57], v75 offset:20480
	ds_read_b128 v[50:53], v76 offset:20480
	ds_read_b128 v[62:65], v77 offset:20480
	v_max_f32_e32 v19, 0, v33
	v_fmac_f32_e32 v18, v89, v19
	v_not_b32_e32 v19, v18
	v_or_b32_e32 v20, 0x80000000, v18
	v_cmp_gt_i32_e32 vcc, 0, v18
	s_nop 1
	v_cndmask_b32_e32 v18, v20, v19, vcc
	v_cmp_le_u32_e32 vcc, v132, v87
	s_nop 1
	v_cndmask_b32_e32 v231, 0, v18, vcc
.LBB0_553:
	s_or_b64 exec, exec, s[82:83]
	s_movk_i32 s2, 0x4df
	v_cmp_lt_u32_e32 vcc, s2, v177
	v_mov_b32_e32 v233, 0
	s_and_saveexec_b64 s[82:83], vcc
	s_cbranch_execz .Lidxp_e39
	s_waitcnt lgkmcnt(0)
	v_mfma_f32_32x32x16_bf16 v[18:33], v[38:41], v[58:61], 0
	v_max_f32_e32 v2, 0, v2
	v_max_f32_e32 v3, 0, v3
	v_fma_f32 v2, v174, v2, 0
	v_max_f32_e32 v4, 0, v4
	v_fmac_f32_e32 v2, v173, v3
	v_max_f32_e32 v5, 0, v5
	v_fmac_f32_e32 v2, v172, v4
	v_max_f32_e32 v6, 0, v6
	v_fmac_f32_e32 v2, v171, v5
	v_max_f32_e32 v7, 0, v7
	v_mfma_f32_32x32x16_bf16 v[18:33], v[46:49], v[54:57], v[18:33]
	v_fmac_f32_e32 v2, v170, v6
	v_max_f32_e32 v8, 0, v8
	v_fmac_f32_e32 v2, v169, v7
	v_max_f32_e32 v9, 0, v9
	v_fmac_f32_e32 v2, v168, v8
	v_max_f32_e32 v10, 0, v10
	v_fmac_f32_e32 v2, v167, v9
	v_max_f32_e32 v11, 0, v11
	v_fmac_f32_e32 v2, v166, v10
	v_max_f32_e32 v12, 0, v12
	v_mfma_f32_32x32x16_bf16 v[18:33], v[34:37], v[50:53], v[18:33]
	v_fmac_f32_e32 v2, v165, v11
	v_max_f32_e32 v13, 0, v13
	v_fmac_f32_e32 v2, v164, v12
	v_max_f32_e32 v14, 0, v14
	v_fmac_f32_e32 v2, v163, v13
	v_fmac_f32_e32 v2, v162, v14
	v_max_f32_e32 v3, 0, v15
	v_fmac_f32_e32 v2, v161, v3
	v_max_f32_e32 v3, 0, v16
	v_fmac_f32_e32 v2, v160, v3
	v_mfma_f32_32x32x16_bf16 v[18:33], v[42:45], v[62:65], v[18:33]
	ds_read_b128 v[58:61], v74 offset:24576
	ds_read_b128 v[54:57], v75 offset:24576
	ds_read_b128 v[50:53], v76 offset:24576
	ds_read_b128 v[62:65], v77 offset:24576
	v_max_f32_e32 v3, 0, v17
	v_fmac_f32_e32 v2, v89, v3
	v_not_b32_e32 v3, v2
	v_or_b32_e32 v4, 0x80000000, v2
	v_cmp_gt_i32_e32 vcc, 0, v2
	s_nop 1
	v_cndmask_b32_e32 v2, v4, v3, vcc
	v_cmp_le_u32_e32 vcc, v133, v87
	s_nop 1
	v_cndmask_b32_e32 v232, 0, v2, vcc
.LBB0_557:
	s_or_b64 exec, exec, s[82:83]
	s_movk_i32 s2, 0x4ff
	v_cmp_lt_u32_e32 vcc, s2, v177
	v_mov_b32_e32 v234, 0
	s_and_saveexec_b64 s[82:83], vcc
	s_cbranch_execz .Lidxp_e40
	s_waitcnt lgkmcnt(0)
	v_mfma_f32_32x32x16_bf16 v[2:17], v[38:41], v[58:61], 0
	v_max_f32_e32 v18, 0, v18
	v_max_f32_e32 v19, 0, v19
	v_fma_f32 v18, v174, v18, 0
	v_max_f32_e32 v20, 0, v20
	v_fmac_f32_e32 v18, v173, v19
	v_max_f32_e32 v21, 0, v21
	v_fmac_f32_e32 v18, v172, v20
	v_max_f32_e32 v22, 0, v22
	v_fmac_f32_e32 v18, v171, v21
	v_max_f32_e32 v23, 0, v23
	v_mfma_f32_32x32x16_bf16 v[2:17], v[46:49], v[54:57], v[2:17]
	v_fmac_f32_e32 v18, v170, v22
	v_max_f32_e32 v24, 0, v24
	v_fmac_f32_e32 v18, v169, v23
	v_max_f32_e32 v25, 0, v25
	v_fmac_f32_e32 v18, v168, v24
	v_max_f32_e32 v26, 0, v26
	v_fmac_f32_e32 v18, v167, v25
	v_max_f32_e32 v27, 0, v27
	v_fmac_f32_e32 v18, v166, v26
	v_max_f32_e32 v28, 0, v28
	v_mfma_f32_32x32x16_bf16 v[2:17], v[34:37], v[50:53], v[2:17]
	v_fmac_f32_e32 v18, v165, v27
	v_max_f32_e32 v29, 0, v29
	v_fmac_f32_e32 v18, v164, v28
	v_max_f32_e32 v30, 0, v30
	v_fmac_f32_e32 v18, v163, v29
	v_fmac_f32_e32 v18, v162, v30
	v_max_f32_e32 v19, 0, v31
	v_fmac_f32_e32 v18, v161, v19
	v_max_f32_e32 v19, 0, v32
	v_fmac_f32_e32 v18, v160, v19
	v_mfma_f32_32x32x16_bf16 v[2:17], v[42:45], v[62:65], v[2:17]
	ds_read_b128 v[58:61], v74 offset:28672
	ds_read_b128 v[54:57], v75 offset:28672
	ds_read_b128 v[50:53], v76 offset:28672
	ds_read_b128 v[62:65], v77 offset:28672
	v_max_f32_e32 v19, 0, v33
	v_fmac_f32_e32 v18, v89, v19
	v_not_b32_e32 v19, v18
	v_or_b32_e32 v20, 0x80000000, v18
	v_cmp_gt_i32_e32 vcc, 0, v18
	s_nop 1
	v_cndmask_b32_e32 v18, v20, v19, vcc
	v_cmp_le_u32_e32 vcc, v134, v87
	s_nop 1
	v_cndmask_b32_e32 v233, 0, v18, vcc
.LBB0_561:
	s_or_b64 exec, exec, s[82:83]
	s_movk_i32 s2, 0x51f
	v_cmp_lt_u32_e32 vcc, s2, v177
	v_mov_b32_e32 v235, 0
	s_and_saveexec_b64 s[82:83], vcc
	s_cbranch_execz .Lidxp_e41
	s_waitcnt lgkmcnt(0)
	s_waitcnt vmcnt(0)
	s_barrier
	v_cmp_le_u32_e32 vcc, v79, v80
	s_and_b64 vcc, exec, vcc
	s_cbranch_vccz .Lidxd_s5
	s_nop 0
	global_load_lds_dwordx4 v72, s[100:101]
	s_add_u32 m0, m0, 0x400
	s_add_u32 s100, s100, 0x1a000
	s_addc_u32 s101, s101, 0
	s_nop 0
	global_load_lds_dwordx4 v73, s[100:101]
	s_add_u32 m0, m0, 0x400
	s_add_u32 s100, s100, 0x1a000
	s_addc_u32 s101, s101, 0
	s_nop 0
	global_load_lds_dwordx4 v72, s[100:101]
	s_add_u32 m0, m0, 0x400
	s_add_u32 s100, s100, 0x1a000
	s_addc_u32 s101, s101, 0
	s_nop 0
	global_load_lds_dwordx4 v73, s[100:101]
	s_add_u32 m0, m0, 0x400
	s_add_u32 s100, s100, 0x1a000
	s_addc_u32 s101, s101, 0
	s_add_u32 m0, m0, 0x7000
	s_add_u32 s100, s100, 0x2d8000
	s_addc_u32 s101, s101, 0
	v_add_u32_e32 v79, 8, v79
.Lidxd_s5:
	v_mfma_f32_32x32x16_bf16 v[18:33], v[38:41], v[58:61], 0
	v_max_f32_e32 v2, 0, v2
	v_max_f32_e32 v3, 0, v3
	v_fma_f32 v2, v174, v2, 0
	v_max_f32_e32 v4, 0, v4
	v_fmac_f32_e32 v2, v173, v3
	v_max_f32_e32 v5, 0, v5
	v_fmac_f32_e32 v2, v172, v4
	v_max_f32_e32 v6, 0, v6
	v_fmac_f32_e32 v2, v171, v5
	v_max_f32_e32 v7, 0, v7
	v_mfma_f32_32x32x16_bf16 v[18:33], v[46:49], v[54:57], v[18:33]
	v_fmac_f32_e32 v2, v170, v6
	v_max_f32_e32 v8, 0, v8
	v_fmac_f32_e32 v2, v169, v7
	v_max_f32_e32 v9, 0, v9
	v_fmac_f32_e32 v2, v168, v8
	v_max_f32_e32 v10, 0, v10
	v_fmac_f32_e32 v2, v167, v9
	v_max_f32_e32 v11, 0, v11
	v_fmac_f32_e32 v2, v166, v10
	v_max_f32_e32 v12, 0, v12
	v_mfma_f32_32x32x16_bf16 v[18:33], v[34:37], v[50:53], v[18:33]
	v_fmac_f32_e32 v2, v165, v11
	v_max_f32_e32 v13, 0, v13
	v_fmac_f32_e32 v2, v164, v12
	v_max_f32_e32 v14, 0, v14
	v_fmac_f32_e32 v2, v163, v13
	v_fmac_f32_e32 v2, v162, v14
	v_max_f32_e32 v3, 0, v15
	v_fmac_f32_e32 v2, v161, v3
	v_max_f32_e32 v3, 0, v16
	v_fmac_f32_e32 v2, v160, v3
	v_mfma_f32_32x32x16_bf16 v[18:33], v[42:45], v[62:65], v[18:33]
	ds_read_b128 v[58:61], v74 offset:32768
	ds_read_b128 v[54:57], v75 offset:32768
	ds_read_b128 v[50:53], v76 offset:32768
	ds_read_b128 v[62:65], v77 offset:32768
	v_max_f32_e32 v3, 0, v17
	v_fmac_f32_e32 v2, v89, v3
	v_not_b32_e32 v3, v2
	v_or_b32_e32 v4, 0x80000000, v2
	v_cmp_gt_i32_e32 vcc, 0, v2
	s_nop 1
	v_cndmask_b32_e32 v2, v4, v3, vcc
	v_cmp_le_u32_e32 vcc, v135, v87
	s_nop 1
	v_cndmask_b32_e32 v234, 0, v2, vcc
.LBB0_565:
	s_or_b64 exec, exec, s[82:83]
	s_movk_i32 s2, 0x53f
	v_cmp_lt_u32_e32 vcc, s2, v177
	v_mov_b32_e32 v236, 0
	s_and_saveexec_b64 s[82:83], vcc
	s_cbranch_execz .Lidxp_e42
	s_waitcnt lgkmcnt(0)
	v_mfma_f32_32x32x16_bf16 v[2:17], v[38:41], v[58:61], 0
	v_max_f32_e32 v18, 0, v18
	v_max_f32_e32 v19, 0, v19
	v_fma_f32 v18, v174, v18, 0
	v_max_f32_e32 v20, 0, v20
	v_fmac_f32_e32 v18, v173, v19
	v_max_f32_e32 v21, 0, v21
	v_fmac_f32_e32 v18, v172, v20
	v_max_f32_e32 v22, 0, v22
	v_fmac_f32_e32 v18, v171, v21
	v_max_f32_e32 v23, 0, v23
	v_mfma_f32_32x32x16_bf16 v[2:17], v[46:49], v[54:57], v[2:17]
	v_fmac_f32_e32 v18, v170, v22
	v_max_f32_e32 v24, 0, v24
	v_fmac_f32_e32 v18, v169, v23
	v_max_f32_e32 v25, 0, v25
	v_fmac_f32_e32 v18, v168, v24
	v_max_f32_e32 v26, 0, v26
	v_fmac_f32_e32 v18, v167, v25
	v_max_f32_e32 v27, 0, v27
	v_fmac_f32_e32 v18, v166, v26
	v_max_f32_e32 v28, 0, v28
	v_mfma_f32_32x32x16_bf16 v[2:17], v[34:37], v[50:53], v[2:17]
	v_fmac_f32_e32 v18, v165, v27
	v_max_f32_e32 v29, 0, v29
	v_fmac_f32_e32 v18, v164, v28
	v_max_f32_e32 v30, 0, v30
	v_fmac_f32_e32 v18, v163, v29
	v_fmac_f32_e32 v18, v162, v30
	v_max_f32_e32 v19, 0, v31
	v_fmac_f32_e32 v18, v161, v19
	v_max_f32_e32 v19, 0, v32
	v_fmac_f32_e32 v18, v160, v19
	v_mfma_f32_32x32x16_bf16 v[2:17], v[42:45], v[62:65], v[2:17]
	ds_read_b128 v[58:61], v74 offset:36864
	ds_read_b128 v[54:57], v75 offset:36864
	ds_read_b128 v[50:53], v76 offset:36864
	ds_read_b128 v[62:65], v77 offset:36864
	v_max_f32_e32 v19, 0, v33
	v_fmac_f32_e32 v18, v89, v19
	v_not_b32_e32 v19, v18
	v_or_b32_e32 v20, 0x80000000, v18
	v_cmp_gt_i32_e32 vcc, 0, v18
	s_nop 1
	v_cndmask_b32_e32 v18, v20, v19, vcc
	v_cmp_le_u32_e32 vcc, v136, v87
	s_nop 1
	v_cndmask_b32_e32 v235, 0, v18, vcc
.LBB0_569:
	s_or_b64 exec, exec, s[82:83]
	s_movk_i32 s2, 0x55f
	v_cmp_lt_u32_e32 vcc, s2, v177
	v_mov_b32_e32 v237, 0
	s_and_saveexec_b64 s[82:83], vcc
	s_cbranch_execz .Lidxp_e43
	s_waitcnt lgkmcnt(0)
	v_mfma_f32_32x32x16_bf16 v[18:33], v[38:41], v[58:61], 0
	v_max_f32_e32 v2, 0, v2
	v_max_f32_e32 v3, 0, v3
	v_fma_f32 v2, v174, v2, 0
	v_max_f32_e32 v4, 0, v4
	v_fmac_f32_e32 v2, v173, v3
	v_max_f32_e32 v5, 0, v5
	v_fmac_f32_e32 v2, v172, v4
	v_max_f32_e32 v6, 0, v6
	v_fmac_f32_e32 v2, v171, v5
	v_max_f32_e32 v7, 0, v7
	v_mfma_f32_32x32x16_bf16 v[18:33], v[46:49], v[54:57], v[18:33]
	v_fmac_f32_e32 v2, v170, v6
	v_max_f32_e32 v8, 0, v8
	v_fmac_f32_e32 v2, v169, v7
	v_max_f32_e32 v9, 0, v9
	v_fmac_f32_e32 v2, v168, v8
	v_max_f32_e32 v10, 0, v10
	v_fmac_f32_e32 v2, v167, v9
	v_max_f32_e32 v11, 0, v11
	v_fmac_f32_e32 v2, v166, v10
	v_max_f32_e32 v12, 0, v12
	v_mfma_f32_32x32x16_bf16 v[18:33], v[34:37], v[50:53], v[18:33]
	v_fmac_f32_e32 v2, v165, v11
	v_max_f32_e32 v13, 0, v13
	v_fmac_f32_e32 v2, v164, v12
	v_max_f32_e32 v14, 0, v14
	v_fmac_f32_e32 v2, v163, v13
	v_fmac_f32_e32 v2, v162, v14
	v_max_f32_e32 v3, 0, v15
	v_fmac_f32_e32 v2, v161, v3
	v_max_f32_e32 v3, 0, v16
	v_fmac_f32_e32 v2, v160, v3
	v_mfma_f32_32x32x16_bf16 v[18:33], v[42:45], v[62:65], v[18:33]
	ds_read_b128 v[58:61], v74 offset:40960
	ds_read_b128 v[54:57], v75 offset:40960
	ds_read_b128 v[50:53], v76 offset:40960
	ds_read_b128 v[62:65], v77 offset:40960
	v_max_f32_e32 v3, 0, v17
	v_fmac_f32_e32 v2, v89, v3
	v_not_b32_e32 v3, v2
	v_or_b32_e32 v4, 0x80000000, v2
	v_cmp_gt_i32_e32 vcc, 0, v2
	s_nop 1
	v_cndmask_b32_e32 v2, v4, v3, vcc
	v_cmp_le_u32_e32 vcc, v137, v87
	s_nop 1
	v_cndmask_b32_e32 v236, 0, v2, vcc
.LBB0_573:
	s_or_b64 exec, exec, s[82:83]
	s_movk_i32 s2, 0x57f
	v_cmp_lt_u32_e32 vcc, s2, v177
	v_mov_b32_e32 v238, 0
	s_and_saveexec_b64 s[82:83], vcc
	s_cbranch_execz .Lidxp_e44
	s_waitcnt lgkmcnt(0)
	v_mfma_f32_32x32x16_bf16 v[2:17], v[38:41], v[58:61], 0
	v_max_f32_e32 v18, 0, v18
	v_max_f32_e32 v19, 0, v19
	v_fma_f32 v18, v174, v18, 0
	v_max_f32_e32 v20, 0, v20
	v_fmac_f32_e32 v18, v173, v19
	v_max_f32_e32 v21, 0, v21
	v_fmac_f32_e32 v18, v172, v20
	v_max_f32_e32 v22, 0, v22
	v_fmac_f32_e32 v18, v171, v21
	v_max_f32_e32 v23, 0, v23
	v_mfma_f32_32x32x16_bf16 v[2:17], v[46:49], v[54:57], v[2:17]
	v_fmac_f32_e32 v18, v170, v22
	v_max_f32_e32 v24, 0, v24
	v_fmac_f32_e32 v18, v169, v23
	v_max_f32_e32 v25, 0, v25
	v_fmac_f32_e32 v18, v168, v24
	v_max_f32_e32 v26, 0, v26
	v_fmac_f32_e32 v18, v167, v25
	v_max_f32_e32 v27, 0, v27
	v_fmac_f32_e32 v18, v166, v26
	v_max_f32_e32 v28, 0, v28
	v_mfma_f32_32x32x16_bf16 v[2:17], v[34:37], v[50:53], v[2:17]
	v_fmac_f32_e32 v18, v165, v27
	v_max_f32_e32 v29, 0, v29
	v_fmac_f32_e32 v18, v164, v28
	v_max_f32_e32 v30, 0, v30
	v_fmac_f32_e32 v18, v163, v29
	v_fmac_f32_e32 v18, v162, v30
	v_max_f32_e32 v19, 0, v31
	v_fmac_f32_e32 v18, v161, v19
	v_max_f32_e32 v19, 0, v32
	v_fmac_f32_e32 v18, v160, v19
	v_mfma_f32_32x32x16_bf16 v[2:17], v[42:45], v[62:65], v[2:17]
	ds_read_b128 v[58:61], v74 offset:45056
	ds_read_b128 v[54:57], v75 offset:45056
	ds_read_b128 v[50:53], v76 offset:45056
	ds_read_b128 v[62:65], v77 offset:45056
	v_max_f32_e32 v19, 0, v33
	v_fmac_f32_e32 v18, v89, v19
	v_not_b32_e32 v19, v18
	v_or_b32_e32 v20, 0x80000000, v18
	v_cmp_gt_i32_e32 vcc, 0, v18
	s_nop 1
	v_cndmask_b32_e32 v18, v20, v19, vcc
	v_cmp_le_u32_e32 vcc, v138, v87
	s_nop 1
	v_cndmask_b32_e32 v237, 0, v18, vcc
.LBB0_577:
	s_or_b64 exec, exec, s[82:83]
	s_movk_i32 s2, 0x59f
	v_cmp_lt_u32_e32 vcc, s2, v177
	v_mov_b32_e32 v239, 0
	s_and_saveexec_b64 s[82:83], vcc
	s_cbranch_execz .Lidxp_e45
	s_waitcnt lgkmcnt(0)
	v_mfma_f32_32x32x16_bf16 v[18:33], v[38:41], v[58:61], 0
	v_max_f32_e32 v2, 0, v2
	v_max_f32_e32 v3, 0, v3
	v_fma_f32 v2, v174, v2, 0
	v_max_f32_e32 v4, 0, v4
	v_fmac_f32_e32 v2, v173, v3
	v_max_f32_e32 v5, 0, v5
	v_fmac_f32_e32 v2, v172, v4
	v_max_f32_e32 v6, 0, v6
	v_fmac_f32_e32 v2, v171, v5
	v_max_f32_e32 v7, 0, v7
	v_mfma_f32_32x32x16_bf16 v[18:33], v[46:49], v[54:57], v[18:33]
	v_fmac_f32_e32 v2, v170, v6
	v_max_f32_e32 v8, 0, v8
	v_fmac_f32_e32 v2, v169, v7
	v_max_f32_e32 v9, 0, v9
	v_fmac_f32_e32 v2, v168, v8
	v_max_f32_e32 v10, 0, v10
	v_fmac_f32_e32 v2, v167, v9
	v_max_f32_e32 v11, 0, v11
	v_fmac_f32_e32 v2, v166, v10
	v_max_f32_e32 v12, 0, v12
	v_mfma_f32_32x32x16_bf16 v[18:33], v[34:37], v[50:53], v[18:33]
	v_fmac_f32_e32 v2, v165, v11
	v_max_f32_e32 v13, 0, v13
	v_fmac_f32_e32 v2, v164, v12
	v_max_f32_e32 v14, 0, v14
	v_fmac_f32_e32 v2, v163, v13
	v_fmac_f32_e32 v2, v162, v14
	v_max_f32_e32 v3, 0, v15
	v_fmac_f32_e32 v2, v161, v3
	v_max_f32_e32 v3, 0, v16
	v_fmac_f32_e32 v2, v160, v3
	v_mfma_f32_32x32x16_bf16 v[18:33], v[42:45], v[62:65], v[18:33]
	ds_read_b128 v[58:61], v74 offset:49152
	ds_read_b128 v[54:57], v75 offset:49152
	ds_read_b128 v[50:53], v76 offset:49152
	ds_read_b128 v[62:65], v77 offset:49152
	v_max_f32_e32 v3, 0, v17
	v_fmac_f32_e32 v2, v89, v3
	v_not_b32_e32 v3, v2
	v_or_b32_e32 v4, 0x80000000, v2
	v_cmp_gt_i32_e32 vcc, 0, v2
	s_nop 1
	v_cndmask_b32_e32 v2, v4, v3, vcc
	v_cmp_le_u32_e32 vcc, v139, v87
	s_nop 1
	v_cndmask_b32_e32 v238, 0, v2, vcc
.LBB0_581:
	s_or_b64 exec, exec, s[82:83]
	s_movk_i32 s2, 0x5bf
	v_cmp_lt_u32_e32 vcc, s2, v177
	v_mov_b32_e32 v240, 0
	s_and_saveexec_b64 s[82:83], vcc
	s_cbranch_execz .Lidxp_e46
	s_waitcnt lgkmcnt(0)
	v_mfma_f32_32x32x16_bf16 v[2:17], v[38:41], v[58:61], 0
	v_max_f32_e32 v18, 0, v18
	v_max_f32_e32 v19, 0, v19
	v_fma_f32 v18, v174, v18, 0
	v_max_f32_e32 v20, 0, v20
	v_fmac_f32_e32 v18, v173, v19
	v_max_f32_e32 v21, 0, v21
	v_fmac_f32_e32 v18, v172, v20
	v_max_f32_e32 v22, 0, v22
	v_fmac_f32_e32 v18, v171, v21
	v_max_f32_e32 v23, 0, v23
	v_mfma_f32_32x32x16_bf16 v[2:17], v[46:49], v[54:57], v[2:17]
	v_fmac_f32_e32 v18, v170, v22
	v_max_f32_e32 v24, 0, v24
	v_fmac_f32_e32 v18, v169, v23
	v_max_f32_e32 v25, 0, v25
	v_fmac_f32_e32 v18, v168, v24
	v_max_f32_e32 v26, 0, v26
	v_fmac_f32_e32 v18, v167, v25
	v_max_f32_e32 v27, 0, v27
	v_fmac_f32_e32 v18, v166, v26
	v_max_f32_e32 v28, 0, v28
	v_mfma_f32_32x32x16_bf16 v[2:17], v[34:37], v[50:53], v[2:17]
	v_fmac_f32_e32 v18, v165, v27
	v_max_f32_e32 v29, 0, v29
	v_fmac_f32_e32 v18, v164, v28
	v_max_f32_e32 v30, 0, v30
	v_fmac_f32_e32 v18, v163, v29
	v_fmac_f32_e32 v18, v162, v30
	v_max_f32_e32 v19, 0, v31
	v_fmac_f32_e32 v18, v161, v19
	v_max_f32_e32 v19, 0, v32
	v_fmac_f32_e32 v18, v160, v19
	v_mfma_f32_32x32x16_bf16 v[2:17], v[42:45], v[62:65], v[2:17]
	ds_read_b128 v[58:61], v74 offset:53248
	ds_read_b128 v[54:57], v75 offset:53248
	ds_read_b128 v[50:53], v76 offset:53248
	ds_read_b128 v[62:65], v77 offset:53248
	v_max_f32_e32 v19, 0, v33
	v_fmac_f32_e32 v18, v89, v19
	v_not_b32_e32 v19, v18
	v_or_b32_e32 v20, 0x80000000, v18
	v_cmp_gt_i32_e32 vcc, 0, v18
	s_nop 1
	v_cndmask_b32_e32 v18, v20, v19, vcc
	v_cmp_le_u32_e32 vcc, v140, v87
	s_nop 1
	v_cndmask_b32_e32 v239, 0, v18, vcc
.LBB0_585:
	s_or_b64 exec, exec, s[82:83]
	s_movk_i32 s2, 0x5df
	v_cmp_lt_u32_e32 vcc, s2, v177
	v_mov_b32_e32 v241, 0
	s_and_saveexec_b64 s[82:83], vcc
	s_cbranch_execz .Lidxp_e47
	s_waitcnt lgkmcnt(0)
	v_mfma_f32_32x32x16_bf16 v[18:33], v[38:41], v[58:61], 0
	v_max_f32_e32 v2, 0, v2
	v_max_f32_e32 v3, 0, v3
	v_fma_f32 v2, v174, v2, 0
	v_max_f32_e32 v4, 0, v4
	v_fmac_f32_e32 v2, v173, v3
	v_max_f32_e32 v5, 0, v5
	v_fmac_f32_e32 v2, v172, v4
	v_max_f32_e32 v6, 0, v6
	v_fmac_f32_e32 v2, v171, v5
	v_max_f32_e32 v7, 0, v7
	v_mfma_f32_32x32x16_bf16 v[18:33], v[46:49], v[54:57], v[18:33]
	v_fmac_f32_e32 v2, v170, v6
	v_max_f32_e32 v8, 0, v8
	v_fmac_f32_e32 v2, v169, v7
	v_max_f32_e32 v9, 0, v9
	v_fmac_f32_e32 v2, v168, v8
	v_max_f32_e32 v10, 0, v10
	v_fmac_f32_e32 v2, v167, v9
	v_max_f32_e32 v11, 0, v11
	v_fmac_f32_e32 v2, v166, v10
	v_max_f32_e32 v12, 0, v12
	v_mfma_f32_32x32x16_bf16 v[18:33], v[34:37], v[50:53], v[18:33]
	v_fmac_f32_e32 v2, v165, v11
	v_max_f32_e32 v13, 0, v13
	v_fmac_f32_e32 v2, v164, v12
	v_max_f32_e32 v14, 0, v14
	v_fmac_f32_e32 v2, v163, v13
	v_fmac_f32_e32 v2, v162, v14
	v_max_f32_e32 v3, 0, v15
	v_fmac_f32_e32 v2, v161, v3
	v_max_f32_e32 v3, 0, v16
	v_fmac_f32_e32 v2, v160, v3
	v_mfma_f32_32x32x16_bf16 v[18:33], v[42:45], v[62:65], v[18:33]
	ds_read_b128 v[58:61], v74 offset:57344
	ds_read_b128 v[54:57], v75 offset:57344
	ds_read_b128 v[50:53], v76 offset:57344
	ds_read_b128 v[62:65], v77 offset:57344
	v_max_f32_e32 v3, 0, v17
	v_fmac_f32_e32 v2, v89, v3
	v_not_b32_e32 v3, v2
	v_or_b32_e32 v4, 0x80000000, v2
	v_cmp_gt_i32_e32 vcc, 0, v2
	s_nop 1
	v_cndmask_b32_e32 v2, v4, v3, vcc
	v_cmp_le_u32_e32 vcc, v141, v87
	s_nop 1
	v_cndmask_b32_e32 v240, 0, v2, vcc
.LBB0_589:
	s_or_b64 exec, exec, s[82:83]
	s_movk_i32 s2, 0x5ff
	v_cmp_lt_u32_e32 vcc, s2, v177
	v_mov_b32_e32 v242, 0
	s_and_saveexec_b64 s[82:83], vcc
	s_cbranch_execz .Lidxp_e48
	s_waitcnt lgkmcnt(0)
	v_mfma_f32_32x32x16_bf16 v[2:17], v[38:41], v[58:61], 0
	v_max_f32_e32 v18, 0, v18
	v_max_f32_e32 v19, 0, v19
	v_fma_f32 v18, v174, v18, 0
	v_max_f32_e32 v20, 0, v20
	v_fmac_f32_e32 v18, v173, v19
	v_max_f32_e32 v21, 0, v21
	v_fmac_f32_e32 v18, v172, v20
	v_max_f32_e32 v22, 0, v22
	v_fmac_f32_e32 v18, v171, v21
	v_max_f32_e32 v23, 0, v23
	v_mfma_f32_32x32x16_bf16 v[2:17], v[46:49], v[54:57], v[2:17]
	v_fmac_f32_e32 v18, v170, v22
	v_max_f32_e32 v24, 0, v24
	v_fmac_f32_e32 v18, v169, v23
	v_max_f32_e32 v25, 0, v25
	v_fmac_f32_e32 v18, v168, v24
	v_max_f32_e32 v26, 0, v26
	v_fmac_f32_e32 v18, v167, v25
	v_max_f32_e32 v27, 0, v27
	v_fmac_f32_e32 v18, v166, v26
	v_max_f32_e32 v28, 0, v28
	v_mfma_f32_32x32x16_bf16 v[2:17], v[34:37], v[50:53], v[2:17]
	v_fmac_f32_e32 v18, v165, v27
	v_max_f32_e32 v29, 0, v29
	v_fmac_f32_e32 v18, v164, v28
	v_max_f32_e32 v30, 0, v30
	v_fmac_f32_e32 v18, v163, v29
	v_fmac_f32_e32 v18, v162, v30
	v_max_f32_e32 v19, 0, v31
	v_fmac_f32_e32 v18, v161, v19
	v_max_f32_e32 v19, 0, v32
	v_fmac_f32_e32 v18, v160, v19
	v_mfma_f32_32x32x16_bf16 v[2:17], v[42:45], v[62:65], v[2:17]
	ds_read_b128 v[58:61], v74 offset:61440
	ds_read_b128 v[54:57], v75 offset:61440
	ds_read_b128 v[50:53], v76 offset:61440
	ds_read_b128 v[62:65], v77 offset:61440
	v_max_f32_e32 v19, 0, v33
	v_fmac_f32_e32 v18, v89, v19
	v_not_b32_e32 v19, v18
	v_or_b32_e32 v20, 0x80000000, v18
	v_cmp_gt_i32_e32 vcc, 0, v18
	s_nop 1
	v_cndmask_b32_e32 v18, v20, v19, vcc
	v_cmp_le_u32_e32 vcc, v142, v87
	s_nop 1
	v_cndmask_b32_e32 v241, 0, v18, vcc
.LBB0_593:
	s_or_b64 exec, exec, s[82:83]
	s_movk_i32 s2, 0x61f
	v_cmp_lt_u32_e32 vcc, s2, v177
	v_mov_b32_e32 v243, 0
	s_and_saveexec_b64 s[82:83], vcc
	s_cbranch_execz .Lidxp_e49
	s_waitcnt lgkmcnt(0)
	s_waitcnt vmcnt(0)
	s_barrier
	v_cmp_le_u32_e32 vcc, v79, v80
	s_and_b64 vcc, exec, vcc
	s_cbranch_vccz .Lidxd_s6
	s_nop 0
	global_load_lds_dwordx4 v72, s[100:101]
	s_add_u32 m0, m0, 0x400
	s_add_u32 s100, s100, 0x1a000
	s_addc_u32 s101, s101, 0
	s_nop 0
	global_load_lds_dwordx4 v73, s[100:101]
	s_add_u32 m0, m0, 0x400
	s_add_u32 s100, s100, 0x1a000
	s_addc_u32 s101, s101, 0
	s_nop 0
	global_load_lds_dwordx4 v72, s[100:101]
	s_add_u32 m0, m0, 0x400
	s_add_u32 s100, s100, 0x1a000
	s_addc_u32 s101, s101, 0
	s_nop 0
	global_load_lds_dwordx4 v73, s[100:101]
	s_add_u32 m0, m0, 0x400
	s_add_u32 s100, s100, 0x1a000
	s_addc_u32 s101, s101, 0
	s_sub_u32 m0, m0, 0x9000
	s_add_u32 s100, s100, 0x2d8000
	s_addc_u32 s101, s101, 0
	v_add_u32_e32 v79, 8, v79
.Lidxd_s6:
	v_mfma_f32_32x32x16_bf16 v[18:33], v[38:41], v[58:61], 0
	v_max_f32_e32 v2, 0, v2
	v_max_f32_e32 v3, 0, v3
	v_fma_f32 v2, v174, v2, 0
	v_max_f32_e32 v4, 0, v4
	v_fmac_f32_e32 v2, v173, v3
	v_max_f32_e32 v5, 0, v5
	v_fmac_f32_e32 v2, v172, v4
	v_max_f32_e32 v6, 0, v6
	v_fmac_f32_e32 v2, v171, v5
	v_max_f32_e32 v7, 0, v7
	v_mfma_f32_32x32x16_bf16 v[18:33], v[46:49], v[54:57], v[18:33]
	v_fmac_f32_e32 v2, v170, v6
	v_max_f32_e32 v8, 0, v8
	v_fmac_f32_e32 v2, v169, v7
	v_max_f32_e32 v9, 0, v9
	v_fmac_f32_e32 v2, v168, v8
	v_max_f32_e32 v10, 0, v10
	v_fmac_f32_e32 v2, v167, v9
	v_max_f32_e32 v11, 0, v11
	v_fmac_f32_e32 v2, v166, v10
	v_max_f32_e32 v12, 0, v12
	v_mfma_f32_32x32x16_bf16 v[18:33], v[34:37], v[50:53], v[18:33]
	v_fmac_f32_e32 v2, v165, v11
	v_max_f32_e32 v13, 0, v13
	v_fmac_f32_e32 v2, v164, v12
	v_max_f32_e32 v14, 0, v14
	v_fmac_f32_e32 v2, v163, v13
	v_fmac_f32_e32 v2, v162, v14
	v_max_f32_e32 v3, 0, v15
	v_fmac_f32_e32 v2, v161, v3
	v_max_f32_e32 v3, 0, v16
	v_fmac_f32_e32 v2, v160, v3
	v_mfma_f32_32x32x16_bf16 v[18:33], v[42:45], v[62:65], v[18:33]
	ds_read_b128 v[58:61], v74 offset:0
	ds_read_b128 v[54:57], v75 offset:0
	ds_read_b128 v[50:53], v76 offset:0
	ds_read_b128 v[62:65], v77 offset:0
	v_max_f32_e32 v3, 0, v17
	v_fmac_f32_e32 v2, v89, v3
	v_not_b32_e32 v3, v2
	v_or_b32_e32 v4, 0x80000000, v2
	v_cmp_gt_i32_e32 vcc, 0, v2
	s_nop 1
	v_cndmask_b32_e32 v2, v4, v3, vcc
	v_cmp_le_u32_e32 vcc, v143, v87
	s_nop 1
	v_cndmask_b32_e32 v242, 0, v2, vcc
.LBB0_597:
	s_or_b64 exec, exec, s[82:83]
	s_movk_i32 s2, 0x63f
	v_cmp_lt_u32_e32 vcc, s2, v177
	v_mov_b32_e32 v244, 0
	s_and_saveexec_b64 s[82:83], vcc
	s_cbranch_execz .Lidxp_e50
	s_waitcnt lgkmcnt(0)
	v_mfma_f32_32x32x16_bf16 v[2:17], v[38:41], v[58:61], 0
	v_max_f32_e32 v18, 0, v18
	v_max_f32_e32 v19, 0, v19
	v_fma_f32 v18, v174, v18, 0
	v_max_f32_e32 v20, 0, v20
	v_fmac_f32_e32 v18, v173, v19
	v_max_f32_e32 v21, 0, v21
	v_fmac_f32_e32 v18, v172, v20
	v_max_f32_e32 v22, 0, v22
	v_fmac_f32_e32 v18, v171, v21
	v_max_f32_e32 v23, 0, v23
	v_mfma_f32_32x32x16_bf16 v[2:17], v[46:49], v[54:57], v[2:17]
	v_fmac_f32_e32 v18, v170, v22
	v_max_f32_e32 v24, 0, v24
	v_fmac_f32_e32 v18, v169, v23
	v_max_f32_e32 v25, 0, v25
	v_fmac_f32_e32 v18, v168, v24
	v_max_f32_e32 v26, 0, v26
	v_fmac_f32_e32 v18, v167, v25
	v_max_f32_e32 v27, 0, v27
	v_fmac_f32_e32 v18, v166, v26
	v_max_f32_e32 v28, 0, v28
	v_mfma_f32_32x32x16_bf16 v[2:17], v[34:37], v[50:53], v[2:17]
	v_fmac_f32_e32 v18, v165, v27
	v_max_f32_e32 v29, 0, v29
	v_fmac_f32_e32 v18, v164, v28
	v_max_f32_e32 v30, 0, v30
	v_fmac_f32_e32 v18, v163, v29
	v_fmac_f32_e32 v18, v162, v30
	v_max_f32_e32 v19, 0, v31
	v_fmac_f32_e32 v18, v161, v19
	v_max_f32_e32 v19, 0, v32
	v_fmac_f32_e32 v18, v160, v19
	v_mfma_f32_32x32x16_bf16 v[2:17], v[42:45], v[62:65], v[2:17]
	ds_read_b128 v[58:61], v74 offset:4096
	ds_read_b128 v[54:57], v75 offset:4096
	ds_read_b128 v[50:53], v76 offset:4096
	ds_read_b128 v[62:65], v77 offset:4096
	v_max_f32_e32 v19, 0, v33
	v_fmac_f32_e32 v18, v89, v19
	v_not_b32_e32 v19, v18
	v_or_b32_e32 v20, 0x80000000, v18
	v_cmp_gt_i32_e32 vcc, 0, v18
	s_nop 1
	v_cndmask_b32_e32 v18, v20, v19, vcc
	v_cmp_le_u32_e32 vcc, v144, v87
	s_nop 1
	v_cndmask_b32_e32 v243, 0, v18, vcc
.LBB0_601:
	s_or_b64 exec, exec, s[82:83]
	s_movk_i32 s2, 0x65f
	v_cmp_lt_u32_e32 vcc, s2, v177
	v_mov_b32_e32 v245, 0
	s_and_saveexec_b64 s[82:83], vcc
	s_cbranch_execz .Lidxp_e51
	s_waitcnt lgkmcnt(0)
	v_mfma_f32_32x32x16_bf16 v[18:33], v[38:41], v[58:61], 0
	v_max_f32_e32 v2, 0, v2
	v_max_f32_e32 v3, 0, v3
	v_fma_f32 v2, v174, v2, 0
	v_max_f32_e32 v4, 0, v4
	v_fmac_f32_e32 v2, v173, v3
	v_max_f32_e32 v5, 0, v5
	v_fmac_f32_e32 v2, v172, v4
	v_max_f32_e32 v6, 0, v6
	v_fmac_f32_e32 v2, v171, v5
	v_max_f32_e32 v7, 0, v7
	v_mfma_f32_32x32x16_bf16 v[18:33], v[46:49], v[54:57], v[18:33]
	v_fmac_f32_e32 v2, v170, v6
	v_max_f32_e32 v8, 0, v8
	v_fmac_f32_e32 v2, v169, v7
	v_max_f32_e32 v9, 0, v9
	v_fmac_f32_e32 v2, v168, v8
	v_max_f32_e32 v10, 0, v10
	v_fmac_f32_e32 v2, v167, v9
	v_max_f32_e32 v11, 0, v11
	v_fmac_f32_e32 v2, v166, v10
	v_max_f32_e32 v12, 0, v12
	v_mfma_f32_32x32x16_bf16 v[18:33], v[34:37], v[50:53], v[18:33]
	v_fmac_f32_e32 v2, v165, v11
	v_max_f32_e32 v13, 0, v13
	v_fmac_f32_e32 v2, v164, v12
	v_max_f32_e32 v14, 0, v14
	v_fmac_f32_e32 v2, v163, v13
	v_fmac_f32_e32 v2, v162, v14
	v_max_f32_e32 v3, 0, v15
	v_fmac_f32_e32 v2, v161, v3
	v_max_f32_e32 v3, 0, v16
	v_fmac_f32_e32 v2, v160, v3
	v_mfma_f32_32x32x16_bf16 v[18:33], v[42:45], v[62:65], v[18:33]
	ds_read_b128 v[58:61], v74 offset:8192
	ds_read_b128 v[54:57], v75 offset:8192
	ds_read_b128 v[50:53], v76 offset:8192
	ds_read_b128 v[62:65], v77 offset:8192
	v_max_f32_e32 v3, 0, v17
	v_fmac_f32_e32 v2, v89, v3
	v_not_b32_e32 v3, v2
	v_or_b32_e32 v4, 0x80000000, v2
	v_cmp_gt_i32_e32 vcc, 0, v2
	s_nop 1
	v_cndmask_b32_e32 v2, v4, v3, vcc
	v_cmp_le_u32_e32 vcc, v145, v87
	s_nop 1
	v_cndmask_b32_e32 v244, 0, v2, vcc
.LBB0_605:
	s_or_b64 exec, exec, s[82:83]
	s_movk_i32 s2, 0x67f
	v_cmp_lt_u32_e32 vcc, s2, v177
	v_mov_b32_e32 v246, 0
	s_and_saveexec_b64 s[82:83], vcc
	s_cbranch_execz .Lidxp_e52
	s_waitcnt lgkmcnt(0)
	v_mfma_f32_32x32x16_bf16 v[2:17], v[38:41], v[58:61], 0
	v_max_f32_e32 v18, 0, v18
	v_max_f32_e32 v19, 0, v19
	v_fma_f32 v18, v174, v18, 0
	v_max_f32_e32 v20, 0, v20
	v_fmac_f32_e32 v18, v173, v19
	v_max_f32_e32 v21, 0, v21
	v_fmac_f32_e32 v18, v172, v20
	v_max_f32_e32 v22, 0, v22
	v_fmac_f32_e32 v18, v171, v21
	v_max_f32_e32 v23, 0, v23
	v_mfma_f32_32x32x16_bf16 v[2:17], v[46:49], v[54:57], v[2:17]
	v_fmac_f32_e32 v18, v170, v22
	v_max_f32_e32 v24, 0, v24
	v_fmac_f32_e32 v18, v169, v23
	v_max_f32_e32 v25, 0, v25
	v_fmac_f32_e32 v18, v168, v24
	v_max_f32_e32 v26, 0, v26
	v_fmac_f32_e32 v18, v167, v25
	v_max_f32_e32 v27, 0, v27
	v_fmac_f32_e32 v18, v166, v26
	v_max_f32_e32 v28, 0, v28
	v_mfma_f32_32x32x16_bf16 v[2:17], v[34:37], v[50:53], v[2:17]
	v_fmac_f32_e32 v18, v165, v27
	v_max_f32_e32 v29, 0, v29
	v_fmac_f32_e32 v18, v164, v28
	v_max_f32_e32 v30, 0, v30
	v_fmac_f32_e32 v18, v163, v29
	v_fmac_f32_e32 v18, v162, v30
	v_max_f32_e32 v19, 0, v31
	v_fmac_f32_e32 v18, v161, v19
	v_max_f32_e32 v19, 0, v32
	v_fmac_f32_e32 v18, v160, v19
	v_mfma_f32_32x32x16_bf16 v[2:17], v[42:45], v[62:65], v[2:17]
	ds_read_b128 v[58:61], v74 offset:12288
	ds_read_b128 v[54:57], v75 offset:12288
	ds_read_b128 v[50:53], v76 offset:12288
	ds_read_b128 v[62:65], v77 offset:12288
	v_max_f32_e32 v19, 0, v33
	v_fmac_f32_e32 v18, v89, v19
	v_not_b32_e32 v19, v18
	v_or_b32_e32 v20, 0x80000000, v18
	v_cmp_gt_i32_e32 vcc, 0, v18
	s_nop 1
	v_cndmask_b32_e32 v18, v20, v19, vcc
	v_cmp_le_u32_e32 vcc, v146, v87
	s_nop 1
	v_cndmask_b32_e32 v245, 0, v18, vcc
.LBB0_609:
	s_or_b64 exec, exec, s[82:83]
	s_movk_i32 s2, 0x69f
	v_cmp_lt_u32_e32 vcc, s2, v177
	v_mov_b32_e32 v247, 0
	s_and_saveexec_b64 s[82:83], vcc
	s_cbranch_execz .Lidxp_e53
	s_waitcnt lgkmcnt(0)
	v_mfma_f32_32x32x16_bf16 v[18:33], v[38:41], v[58:61], 0
	v_max_f32_e32 v2, 0, v2
	v_max_f32_e32 v3, 0, v3
	v_fma_f32 v2, v174, v2, 0
	v_max_f32_e32 v4, 0, v4
	v_fmac_f32_e32 v2, v173, v3
	v_max_f32_e32 v5, 0, v5
	v_fmac_f32_e32 v2, v172, v4
	v_max_f32_e32 v6, 0, v6
	v_fmac_f32_e32 v2, v171, v5
	v_max_f32_e32 v7, 0, v7
	v_mfma_f32_32x32x16_bf16 v[18:33], v[46:49], v[54:57], v[18:33]
	v_fmac_f32_e32 v2, v170, v6
	v_max_f32_e32 v8, 0, v8
	v_fmac_f32_e32 v2, v169, v7
	v_max_f32_e32 v9, 0, v9
	v_fmac_f32_e32 v2, v168, v8
	v_max_f32_e32 v10, 0, v10
	v_fmac_f32_e32 v2, v167, v9
	v_max_f32_e32 v11, 0, v11
	v_fmac_f32_e32 v2, v166, v10
	v_max_f32_e32 v12, 0, v12
	v_mfma_f32_32x32x16_bf16 v[18:33], v[34:37], v[50:53], v[18:33]
	v_fmac_f32_e32 v2, v165, v11
	v_max_f32_e32 v13, 0, v13
	v_fmac_f32_e32 v2, v164, v12
	v_max_f32_e32 v14, 0, v14
	v_fmac_f32_e32 v2, v163, v13
	v_fmac_f32_e32 v2, v162, v14
	v_max_f32_e32 v3, 0, v15
	v_fmac_f32_e32 v2, v161, v3
	v_max_f32_e32 v3, 0, v16
	v_fmac_f32_e32 v2, v160, v3
	v_mfma_f32_32x32x16_bf16 v[18:33], v[42:45], v[62:65], v[18:33]
	ds_read_b128 v[58:61], v74 offset:16384
	ds_read_b128 v[54:57], v75 offset:16384
	ds_read_b128 v[50:53], v76 offset:16384
	ds_read_b128 v[62:65], v77 offset:16384
	v_max_f32_e32 v3, 0, v17
	v_fmac_f32_e32 v2, v89, v3
	v_not_b32_e32 v3, v2
	v_or_b32_e32 v4, 0x80000000, v2
	v_cmp_gt_i32_e32 vcc, 0, v2
	s_nop 1
	v_cndmask_b32_e32 v2, v4, v3, vcc
	v_cmp_le_u32_e32 vcc, v147, v87
	s_nop 1
	v_cndmask_b32_e32 v246, 0, v2, vcc
.LBB0_613:
	s_or_b64 exec, exec, s[82:83]
	s_movk_i32 s2, 0x6bf
	v_cmp_lt_u32_e32 vcc, s2, v177
	v_mov_b32_e32 v248, 0
	s_and_saveexec_b64 s[82:83], vcc
	s_cbranch_execz .Lidxp_e54
	s_waitcnt lgkmcnt(0)
	v_mfma_f32_32x32x16_bf16 v[2:17], v[38:41], v[58:61], 0
	v_max_f32_e32 v18, 0, v18
	v_max_f32_e32 v19, 0, v19
	v_fma_f32 v18, v174, v18, 0
	v_max_f32_e32 v20, 0, v20
	v_fmac_f32_e32 v18, v173, v19
	v_max_f32_e32 v21, 0, v21
	v_fmac_f32_e32 v18, v172, v20
	v_max_f32_e32 v22, 0, v22
	v_fmac_f32_e32 v18, v171, v21
	v_max_f32_e32 v23, 0, v23
	v_mfma_f32_32x32x16_bf16 v[2:17], v[46:49], v[54:57], v[2:17]
	v_fmac_f32_e32 v18, v170, v22
	v_max_f32_e32 v24, 0, v24
	v_fmac_f32_e32 v18, v169, v23
	v_max_f32_e32 v25, 0, v25
	v_fmac_f32_e32 v18, v168, v24
	v_max_f32_e32 v26, 0, v26
	v_fmac_f32_e32 v18, v167, v25
	v_max_f32_e32 v27, 0, v27
	v_fmac_f32_e32 v18, v166, v26
	v_max_f32_e32 v28, 0, v28
	v_mfma_f32_32x32x16_bf16 v[2:17], v[34:37], v[50:53], v[2:17]
	v_fmac_f32_e32 v18, v165, v27
	v_max_f32_e32 v29, 0, v29
	v_fmac_f32_e32 v18, v164, v28
	v_max_f32_e32 v30, 0, v30
	v_fmac_f32_e32 v18, v163, v29
	v_fmac_f32_e32 v18, v162, v30
	v_max_f32_e32 v19, 0, v31
	v_fmac_f32_e32 v18, v161, v19
	v_max_f32_e32 v19, 0, v32
	v_fmac_f32_e32 v18, v160, v19
	v_mfma_f32_32x32x16_bf16 v[2:17], v[42:45], v[62:65], v[2:17]
	ds_read_b128 v[58:61], v74 offset:20480
	ds_read_b128 v[54:57], v75 offset:20480
	ds_read_b128 v[50:53], v76 offset:20480
	ds_read_b128 v[62:65], v77 offset:20480
	v_max_f32_e32 v19, 0, v33
	v_fmac_f32_e32 v18, v89, v19
	v_not_b32_e32 v19, v18
	v_or_b32_e32 v20, 0x80000000, v18
	v_cmp_gt_i32_e32 vcc, 0, v18
	s_nop 1
	v_cndmask_b32_e32 v18, v20, v19, vcc
	v_cmp_le_u32_e32 vcc, v148, v87
	s_nop 1
	v_cndmask_b32_e32 v247, 0, v18, vcc
.LBB0_617:
	s_or_b64 exec, exec, s[82:83]
	s_movk_i32 s2, 0x6df
	v_cmp_lt_u32_e32 vcc, s2, v177
	v_mov_b32_e32 v249, 0
	s_and_saveexec_b64 s[82:83], vcc
	s_cbranch_execz .Lidxp_e55
	s_waitcnt lgkmcnt(0)
	v_mfma_f32_32x32x16_bf16 v[18:33], v[38:41], v[58:61], 0
	v_max_f32_e32 v2, 0, v2
	v_max_f32_e32 v3, 0, v3
	v_fma_f32 v2, v174, v2, 0
	v_max_f32_e32 v4, 0, v4
	v_fmac_f32_e32 v2, v173, v3
	v_max_f32_e32 v5, 0, v5
	v_fmac_f32_e32 v2, v172, v4
	v_max_f32_e32 v6, 0, v6
	v_fmac_f32_e32 v2, v171, v5
	v_max_f32_e32 v7, 0, v7
	v_mfma_f32_32x32x16_bf16 v[18:33], v[46:49], v[54:57], v[18:33]
	v_fmac_f32_e32 v2, v170, v6
	v_max_f32_e32 v8, 0, v8
	v_fmac_f32_e32 v2, v169, v7
	v_max_f32_e32 v9, 0, v9
	v_fmac_f32_e32 v2, v168, v8
	v_max_f32_e32 v10, 0, v10
	v_fmac_f32_e32 v2, v167, v9
	v_max_f32_e32 v11, 0, v11
	v_fmac_f32_e32 v2, v166, v10
	v_max_f32_e32 v12, 0, v12
	v_mfma_f32_32x32x16_bf16 v[18:33], v[34:37], v[50:53], v[18:33]
	v_fmac_f32_e32 v2, v165, v11
	v_max_f32_e32 v13, 0, v13
	v_fmac_f32_e32 v2, v164, v12
	v_max_f32_e32 v14, 0, v14
	v_fmac_f32_e32 v2, v163, v13
	v_fmac_f32_e32 v2, v162, v14
	v_max_f32_e32 v3, 0, v15
	v_fmac_f32_e32 v2, v161, v3
	v_max_f32_e32 v3, 0, v16
	v_fmac_f32_e32 v2, v160, v3
	v_mfma_f32_32x32x16_bf16 v[18:33], v[42:45], v[62:65], v[18:33]
	ds_read_b128 v[58:61], v74 offset:24576
	ds_read_b128 v[54:57], v75 offset:24576
	ds_read_b128 v[50:53], v76 offset:24576
	ds_read_b128 v[62:65], v77 offset:24576
	v_max_f32_e32 v3, 0, v17
	v_fmac_f32_e32 v2, v89, v3
	v_not_b32_e32 v3, v2
	v_or_b32_e32 v4, 0x80000000, v2
	v_cmp_gt_i32_e32 vcc, 0, v2
	s_nop 1
	v_cndmask_b32_e32 v2, v4, v3, vcc
	v_cmp_le_u32_e32 vcc, v149, v87
	s_nop 1
	v_cndmask_b32_e32 v248, 0, v2, vcc
.LBB0_621:
	s_or_b64 exec, exec, s[82:83]
	s_movk_i32 s2, 0x6ff
	v_cmp_lt_u32_e32 vcc, s2, v177
	v_mov_b32_e32 v250, 0
	s_and_saveexec_b64 s[82:83], vcc
	s_cbranch_execz .Lidxp_e56
	s_waitcnt lgkmcnt(0)
	v_mfma_f32_32x32x16_bf16 v[2:17], v[38:41], v[58:61], 0
	v_max_f32_e32 v18, 0, v18
	v_max_f32_e32 v19, 0, v19
	v_fma_f32 v18, v174, v18, 0
	v_max_f32_e32 v20, 0, v20
	v_fmac_f32_e32 v18, v173, v19
	v_max_f32_e32 v21, 0, v21
	v_fmac_f32_e32 v18, v172, v20
	v_max_f32_e32 v22, 0, v22
	v_fmac_f32_e32 v18, v171, v21
	v_max_f32_e32 v23, 0, v23
	v_mfma_f32_32x32x16_bf16 v[2:17], v[46:49], v[54:57], v[2:17]
	v_fmac_f32_e32 v18, v170, v22
	v_max_f32_e32 v24, 0, v24
	v_fmac_f32_e32 v18, v169, v23
	v_max_f32_e32 v25, 0, v25
	v_fmac_f32_e32 v18, v168, v24
	v_max_f32_e32 v26, 0, v26
	v_fmac_f32_e32 v18, v167, v25
	v_max_f32_e32 v27, 0, v27
	v_fmac_f32_e32 v18, v166, v26
	v_max_f32_e32 v28, 0, v28
	v_mfma_f32_32x32x16_bf16 v[2:17], v[34:37], v[50:53], v[2:17]
	v_fmac_f32_e32 v18, v165, v27
	v_max_f32_e32 v29, 0, v29
	v_fmac_f32_e32 v18, v164, v28
	v_max_f32_e32 v30, 0, v30
	v_fmac_f32_e32 v18, v163, v29
	v_fmac_f32_e32 v18, v162, v30
	v_max_f32_e32 v19, 0, v31
	v_fmac_f32_e32 v18, v161, v19
	v_max_f32_e32 v19, 0, v32
	v_fmac_f32_e32 v18, v160, v19
	v_mfma_f32_32x32x16_bf16 v[2:17], v[42:45], v[62:65], v[2:17]
	ds_read_b128 v[58:61], v74 offset:28672
	ds_read_b128 v[54:57], v75 offset:28672
	ds_read_b128 v[50:53], v76 offset:28672
	ds_read_b128 v[62:65], v77 offset:28672
	v_max_f32_e32 v19, 0, v33
	v_fmac_f32_e32 v18, v89, v19
	v_not_b32_e32 v19, v18
	v_or_b32_e32 v20, 0x80000000, v18
	v_cmp_gt_i32_e32 vcc, 0, v18
	s_nop 1
	v_cndmask_b32_e32 v18, v20, v19, vcc
	v_cmp_le_u32_e32 vcc, v150, v87
	s_nop 1
	v_cndmask_b32_e32 v249, 0, v18, vcc
.LBB0_625:
	s_or_b64 exec, exec, s[82:83]
	s_movk_i32 s2, 0x71f
	v_cmp_lt_u32_e32 vcc, s2, v177
	v_mov_b32_e32 v199, 0
	s_and_saveexec_b64 s[82:83], vcc
	s_cbranch_execz .Lidxp_e57
	s_waitcnt lgkmcnt(0)
	s_waitcnt vmcnt(0)
	s_barrier
	v_mfma_f32_32x32x16_bf16 v[18:33], v[38:41], v[58:61], 0
	v_max_f32_e32 v2, 0, v2
	v_max_f32_e32 v3, 0, v3
	v_fma_f32 v2, v174, v2, 0
	v_max_f32_e32 v4, 0, v4
	v_fmac_f32_e32 v2, v173, v3
	v_max_f32_e32 v5, 0, v5
	v_fmac_f32_e32 v2, v172, v4
	v_max_f32_e32 v6, 0, v6
	v_fmac_f32_e32 v2, v171, v5
	v_max_f32_e32 v7, 0, v7
	v_mfma_f32_32x32x16_bf16 v[18:33], v[46:49], v[54:57], v[18:33]
	v_fmac_f32_e32 v2, v170, v6
	v_max_f32_e32 v8, 0, v8
	v_fmac_f32_e32 v2, v169, v7
	v_max_f32_e32 v9, 0, v9
	v_fmac_f32_e32 v2, v168, v8
	v_max_f32_e32 v10, 0, v10
	v_fmac_f32_e32 v2, v167, v9
	v_max_f32_e32 v11, 0, v11
	v_fmac_f32_e32 v2, v166, v10
	v_max_f32_e32 v12, 0, v12
	v_mfma_f32_32x32x16_bf16 v[18:33], v[34:37], v[50:53], v[18:33]
	v_fmac_f32_e32 v2, v165, v11
	v_max_f32_e32 v13, 0, v13
	v_fmac_f32_e32 v2, v164, v12
	v_max_f32_e32 v14, 0, v14
	v_fmac_f32_e32 v2, v163, v13
	v_fmac_f32_e32 v2, v162, v14
	v_max_f32_e32 v3, 0, v15
	v_fmac_f32_e32 v2, v161, v3
	v_max_f32_e32 v3, 0, v16
	v_fmac_f32_e32 v2, v160, v3
	v_mfma_f32_32x32x16_bf16 v[18:33], v[42:45], v[62:65], v[18:33]
	ds_read_b128 v[58:61], v74 offset:32768
	ds_read_b128 v[54:57], v75 offset:32768
	ds_read_b128 v[50:53], v76 offset:32768
	ds_read_b128 v[62:65], v77 offset:32768
	v_max_f32_e32 v3, 0, v17
	v_fmac_f32_e32 v2, v89, v3
	v_not_b32_e32 v3, v2
	v_or_b32_e32 v4, 0x80000000, v2
	v_cmp_gt_i32_e32 vcc, 0, v2
	s_nop 1
	v_cndmask_b32_e32 v2, v4, v3, vcc
	v_cmp_le_u32_e32 vcc, v151, v87
	s_nop 1
	v_cndmask_b32_e32 v250, 0, v2, vcc
.LBB0_629:
	s_or_b64 exec, exec, s[82:83]
	s_movk_i32 s2, 0x73f
	v_cmp_lt_u32_e32 vcc, s2, v177
	v_mov_b32_e32 v200, 0
	s_and_saveexec_b64 s[82:83], vcc
	s_cbranch_execz .Lidxp_e58
	s_waitcnt lgkmcnt(0)
	v_mfma_f32_32x32x16_bf16 v[2:17], v[38:41], v[58:61], 0
	v_max_f32_e32 v18, 0, v18
	v_max_f32_e32 v19, 0, v19
	v_fma_f32 v18, v174, v18, 0
	v_max_f32_e32 v20, 0, v20
	v_fmac_f32_e32 v18, v173, v19
	v_max_f32_e32 v21, 0, v21
	v_fmac_f32_e32 v18, v172, v20
	v_max_f32_e32 v22, 0, v22
	v_fmac_f32_e32 v18, v171, v21
	v_max_f32_e32 v23, 0, v23
	v_mfma_f32_32x32x16_bf16 v[2:17], v[46:49], v[54:57], v[2:17]
	v_fmac_f32_e32 v18, v170, v22
	v_max_f32_e32 v24, 0, v24
	v_fmac_f32_e32 v18, v169, v23
	v_max_f32_e32 v25, 0, v25
	v_fmac_f32_e32 v18, v168, v24
	v_max_f32_e32 v26, 0, v26
	v_fmac_f32_e32 v18, v167, v25
	v_max_f32_e32 v27, 0, v27
	v_fmac_f32_e32 v18, v166, v26
	v_max_f32_e32 v28, 0, v28
	v_mfma_f32_32x32x16_bf16 v[2:17], v[34:37], v[50:53], v[2:17]
	v_fmac_f32_e32 v18, v165, v27
	v_max_f32_e32 v29, 0, v29
	v_fmac_f32_e32 v18, v164, v28
	v_max_f32_e32 v30, 0, v30
	v_fmac_f32_e32 v18, v163, v29
	v_fmac_f32_e32 v18, v162, v30
	v_max_f32_e32 v19, 0, v31
	v_fmac_f32_e32 v18, v161, v19
	v_max_f32_e32 v19, 0, v32
	v_fmac_f32_e32 v18, v160, v19
	v_mfma_f32_32x32x16_bf16 v[2:17], v[42:45], v[62:65], v[2:17]
	ds_read_b128 v[58:61], v74 offset:36864
	ds_read_b128 v[54:57], v75 offset:36864
	ds_read_b128 v[50:53], v76 offset:36864
	ds_read_b128 v[62:65], v77 offset:36864
	v_max_f32_e32 v19, 0, v33
	v_fmac_f32_e32 v18, v89, v19
	v_not_b32_e32 v19, v18
	v_or_b32_e32 v20, 0x80000000, v18
	v_cmp_gt_i32_e32 vcc, 0, v18
	s_nop 1
	v_cndmask_b32_e32 v18, v20, v19, vcc
	v_cmp_le_u32_e32 vcc, v152, v87
	s_nop 1
	v_cndmask_b32_e32 v199, 0, v18, vcc
.LBB0_633:
	s_or_b64 exec, exec, s[82:83]
	s_movk_i32 s2, 0x75f
	v_cmp_lt_u32_e32 vcc, s2, v177
	v_mov_b32_e32 v207, 0
	s_and_saveexec_b64 s[82:83], vcc
	s_cbranch_execz .Lidxp_e59
	s_waitcnt lgkmcnt(0)
	v_mfma_f32_32x32x16_bf16 v[18:33], v[38:41], v[58:61], 0
	v_max_f32_e32 v2, 0, v2
	v_max_f32_e32 v3, 0, v3
	v_fma_f32 v2, v174, v2, 0
	v_max_f32_e32 v4, 0, v4
	v_fmac_f32_e32 v2, v173, v3
	v_max_f32_e32 v5, 0, v5
	v_fmac_f32_e32 v2, v172, v4
	v_max_f32_e32 v6, 0, v6
	v_fmac_f32_e32 v2, v171, v5
	v_max_f32_e32 v7, 0, v7
	v_mfma_f32_32x32x16_bf16 v[18:33], v[46:49], v[54:57], v[18:33]
	v_fmac_f32_e32 v2, v170, v6
	v_max_f32_e32 v8, 0, v8
	v_fmac_f32_e32 v2, v169, v7
	v_max_f32_e32 v9, 0, v9
	v_fmac_f32_e32 v2, v168, v8
	v_max_f32_e32 v10, 0, v10
	v_fmac_f32_e32 v2, v167, v9
	v_max_f32_e32 v11, 0, v11
	v_fmac_f32_e32 v2, v166, v10
	v_max_f32_e32 v12, 0, v12
	v_mfma_f32_32x32x16_bf16 v[18:33], v[34:37], v[50:53], v[18:33]
	v_fmac_f32_e32 v2, v165, v11
	v_max_f32_e32 v13, 0, v13
	v_fmac_f32_e32 v2, v164, v12
	v_max_f32_e32 v14, 0, v14
	v_fmac_f32_e32 v2, v163, v13
	v_fmac_f32_e32 v2, v162, v14
	v_max_f32_e32 v3, 0, v15
	v_fmac_f32_e32 v2, v161, v3
	v_max_f32_e32 v3, 0, v16
	v_fmac_f32_e32 v2, v160, v3
	v_mfma_f32_32x32x16_bf16 v[18:33], v[42:45], v[62:65], v[18:33]
	ds_read_b128 v[58:61], v74 offset:40960
	ds_read_b128 v[54:57], v75 offset:40960
	ds_read_b128 v[50:53], v76 offset:40960
	ds_read_b128 v[62:65], v77 offset:40960
	v_max_f32_e32 v3, 0, v17
	v_fmac_f32_e32 v2, v89, v3
	v_not_b32_e32 v3, v2
	v_or_b32_e32 v4, 0x80000000, v2
	v_cmp_gt_i32_e32 vcc, 0, v2
	s_nop 1
	v_cndmask_b32_e32 v2, v4, v3, vcc
	v_cmp_le_u32_e32 vcc, v153, v87
	s_nop 1
	v_cndmask_b32_e32 v200, 0, v2, vcc
.LBB0_637:
	s_or_b64 exec, exec, s[82:83]
	s_movk_i32 s2, 0x77f
	v_cmp_lt_u32_e32 vcc, s2, v177
	v_mov_b32_e32 v208, 0
	s_and_saveexec_b64 s[82:83], vcc
	s_cbranch_execz .Lidxp_e60
	s_waitcnt lgkmcnt(0)
	v_mfma_f32_32x32x16_bf16 v[2:17], v[38:41], v[58:61], 0
	v_max_f32_e32 v18, 0, v18
	v_max_f32_e32 v19, 0, v19
	v_fma_f32 v18, v174, v18, 0
	v_max_f32_e32 v20, 0, v20
	v_fmac_f32_e32 v18, v173, v19
	v_max_f32_e32 v21, 0, v21
	v_fmac_f32_e32 v18, v172, v20
	v_max_f32_e32 v22, 0, v22
	v_fmac_f32_e32 v18, v171, v21
	v_max_f32_e32 v23, 0, v23
	v_mfma_f32_32x32x16_bf16 v[2:17], v[46:49], v[54:57], v[2:17]
	v_fmac_f32_e32 v18, v170, v22
	v_max_f32_e32 v24, 0, v24
	v_fmac_f32_e32 v18, v169, v23
	v_max_f32_e32 v25, 0, v25
	v_fmac_f32_e32 v18, v168, v24
	v_max_f32_e32 v26, 0, v26
	v_fmac_f32_e32 v18, v167, v25
	v_max_f32_e32 v27, 0, v27
	v_fmac_f32_e32 v18, v166, v26
	v_max_f32_e32 v28, 0, v28
	v_mfma_f32_32x32x16_bf16 v[2:17], v[34:37], v[50:53], v[2:17]
	v_fmac_f32_e32 v18, v165, v27
	v_max_f32_e32 v29, 0, v29
	v_fmac_f32_e32 v18, v164, v28
	v_max_f32_e32 v30, 0, v30
	v_fmac_f32_e32 v18, v163, v29
	v_fmac_f32_e32 v18, v162, v30
	v_max_f32_e32 v19, 0, v31
	v_fmac_f32_e32 v18, v161, v19
	v_max_f32_e32 v19, 0, v32
	v_fmac_f32_e32 v18, v160, v19
	v_mfma_f32_32x32x16_bf16 v[2:17], v[42:45], v[62:65], v[2:17]
	ds_read_b128 v[58:61], v74 offset:45056
	ds_read_b128 v[54:57], v75 offset:45056
	ds_read_b128 v[50:53], v76 offset:45056
	ds_read_b128 v[62:65], v77 offset:45056
	v_max_f32_e32 v19, 0, v33
	v_fmac_f32_e32 v18, v89, v19
	v_not_b32_e32 v19, v18
	v_or_b32_e32 v20, 0x80000000, v18
	v_cmp_gt_i32_e32 vcc, 0, v18
	s_nop 1
	v_cndmask_b32_e32 v18, v20, v19, vcc
	v_cmp_le_u32_e32 vcc, v154, v87
	s_nop 1
	v_cndmask_b32_e32 v207, 0, v18, vcc
.LBB0_641:
	s_or_b64 exec, exec, s[82:83]
	s_movk_i32 s2, 0x79f
	v_cmp_lt_u32_e32 vcc, s2, v177
	v_mov_b32_e32 v210, 0
	s_and_saveexec_b64 s[82:83], vcc
	s_cbranch_execz .Lidxp_e61
	s_waitcnt lgkmcnt(0)
	v_mfma_f32_32x32x16_bf16 v[18:33], v[38:41], v[58:61], 0
	v_max_f32_e32 v2, 0, v2
	v_max_f32_e32 v3, 0, v3
	v_fma_f32 v2, v174, v2, 0
	v_max_f32_e32 v4, 0, v4
	v_fmac_f32_e32 v2, v173, v3
	v_max_f32_e32 v5, 0, v5
	v_fmac_f32_e32 v2, v172, v4
	v_max_f32_e32 v6, 0, v6
	v_fmac_f32_e32 v2, v171, v5
	v_max_f32_e32 v7, 0, v7
	v_mfma_f32_32x32x16_bf16 v[18:33], v[46:49], v[54:57], v[18:33]
	v_fmac_f32_e32 v2, v170, v6
	v_max_f32_e32 v8, 0, v8
	v_fmac_f32_e32 v2, v169, v7
	v_max_f32_e32 v9, 0, v9
	v_fmac_f32_e32 v2, v168, v8
	v_max_f32_e32 v10, 0, v10
	v_fmac_f32_e32 v2, v167, v9
	v_max_f32_e32 v11, 0, v11
	v_fmac_f32_e32 v2, v166, v10
	v_max_f32_e32 v12, 0, v12
	v_mfma_f32_32x32x16_bf16 v[18:33], v[34:37], v[50:53], v[18:33]
	v_fmac_f32_e32 v2, v165, v11
	v_max_f32_e32 v13, 0, v13
	v_fmac_f32_e32 v2, v164, v12
	v_max_f32_e32 v14, 0, v14
	v_fmac_f32_e32 v2, v163, v13
	v_fmac_f32_e32 v2, v162, v14
	v_max_f32_e32 v3, 0, v15
	v_fmac_f32_e32 v2, v161, v3
	v_max_f32_e32 v3, 0, v16
	v_fmac_f32_e32 v2, v160, v3
	v_mfma_f32_32x32x16_bf16 v[18:33], v[42:45], v[62:65], v[18:33]
	ds_read_b128 v[58:61], v74 offset:49152
	ds_read_b128 v[54:57], v75 offset:49152
	ds_read_b128 v[50:53], v76 offset:49152
	ds_read_b128 v[62:65], v77 offset:49152
	v_max_f32_e32 v3, 0, v17
	v_fmac_f32_e32 v2, v89, v3
	v_not_b32_e32 v3, v2
	v_or_b32_e32 v4, 0x80000000, v2
	v_cmp_gt_i32_e32 vcc, 0, v2
	s_nop 1
	v_cndmask_b32_e32 v2, v4, v3, vcc
	v_cmp_le_u32_e32 vcc, v155, v87
	s_nop 1
	v_cndmask_b32_e32 v208, 0, v2, vcc
.LBB0_645:
	s_or_b64 exec, exec, s[82:83]
	s_movk_i32 s2, 0x7bf
	v_lshrrev_b32_e32 v201, 5, v177
	v_cmp_lt_u32_e32 vcc, s2, v177
	v_mov_b32_e32 v70, 0
	s_and_saveexec_b64 s[82:83], vcc
	s_cbranch_execz .Lidxp_e62
	s_waitcnt lgkmcnt(0)
	v_mfma_f32_32x32x16_bf16 v[2:17], v[38:41], v[58:61], 0
	v_max_f32_e32 v18, 0, v18
	v_max_f32_e32 v19, 0, v19
	v_fma_f32 v18, v174, v18, 0
	v_max_f32_e32 v20, 0, v20
	v_fmac_f32_e32 v18, v173, v19
	v_max_f32_e32 v21, 0, v21
	v_fmac_f32_e32 v18, v172, v20
	v_max_f32_e32 v22, 0, v22
	v_fmac_f32_e32 v18, v171, v21
	v_max_f32_e32 v23, 0, v23
	v_mfma_f32_32x32x16_bf16 v[2:17], v[46:49], v[54:57], v[2:17]
	v_fmac_f32_e32 v18, v170, v22
	v_max_f32_e32 v24, 0, v24
	v_fmac_f32_e32 v18, v169, v23
	v_max_f32_e32 v25, 0, v25
	v_fmac_f32_e32 v18, v168, v24
	v_max_f32_e32 v26, 0, v26
	v_fmac_f32_e32 v18, v167, v25
	v_max_f32_e32 v27, 0, v27
	v_fmac_f32_e32 v18, v166, v26
	v_max_f32_e32 v28, 0, v28
	v_mfma_f32_32x32x16_bf16 v[2:17], v[34:37], v[50:53], v[2:17]
	v_fmac_f32_e32 v18, v165, v27
	v_max_f32_e32 v29, 0, v29
	v_fmac_f32_e32 v18, v164, v28
	v_max_f32_e32 v30, 0, v30
	v_fmac_f32_e32 v18, v163, v29
	v_fmac_f32_e32 v18, v162, v30
	v_max_f32_e32 v19, 0, v31
	v_fmac_f32_e32 v18, v161, v19
	v_max_f32_e32 v19, 0, v32
	v_fmac_f32_e32 v18, v160, v19
	v_mfma_f32_32x32x16_bf16 v[2:17], v[42:45], v[62:65], v[2:17]
	ds_read_b128 v[58:61], v74 offset:53248
	ds_read_b128 v[54:57], v75 offset:53248
	ds_read_b128 v[50:53], v76 offset:53248
	ds_read_b128 v[62:65], v77 offset:53248
	v_max_f32_e32 v19, 0, v33
	v_fmac_f32_e32 v18, v89, v19
	v_not_b32_e32 v19, v18
	v_or_b32_e32 v20, 0x80000000, v18
	v_cmp_gt_i32_e32 vcc, 0, v18
	s_nop 1
	v_cndmask_b32_e32 v18, v20, v19, vcc
	v_cmp_le_u32_e32 vcc, v156, v87
	s_nop 1
	v_cndmask_b32_e32 v210, 0, v18, vcc
.LBB0_649:
	s_or_b64 exec, exec, s[82:83]
	v_cmp_eq_u32_e32 vcc, 63, v201
	v_mov_b32_e32 v66, 0
	v_mov_b32_e32 v18, 0
	s_and_saveexec_b64 s[82:83], vcc
	s_cbranch_execz .Lidxp_e63
	s_waitcnt lgkmcnt(0)
	v_mfma_f32_32x32x16_bf16 v[18:33], v[38:41], v[58:61], 0
	v_max_f32_e32 v2, 0, v2
	v_max_f32_e32 v3, 0, v3
	v_fma_f32 v2, v174, v2, 0
	v_max_f32_e32 v4, 0, v4
	v_fmac_f32_e32 v2, v173, v3
	v_max_f32_e32 v5, 0, v5
	v_fmac_f32_e32 v2, v172, v4
	v_max_f32_e32 v6, 0, v6
	v_fmac_f32_e32 v2, v171, v5
	v_max_f32_e32 v7, 0, v7
	v_mfma_f32_32x32x16_bf16 v[18:33], v[46:49], v[54:57], v[18:33]
	v_fmac_f32_e32 v2, v170, v6
	v_max_f32_e32 v8, 0, v8
	v_fmac_f32_e32 v2, v169, v7
	v_max_f32_e32 v9, 0, v9
	v_fmac_f32_e32 v2, v168, v8
	v_max_f32_e32 v10, 0, v10
	v_fmac_f32_e32 v2, v167, v9
	v_max_f32_e32 v11, 0, v11
	v_fmac_f32_e32 v2, v166, v10
	v_max_f32_e32 v12, 0, v12
	v_mfma_f32_32x32x16_bf16 v[18:33], v[34:37], v[50:53], v[18:33]
	v_fmac_f32_e32 v2, v165, v11
	v_max_f32_e32 v13, 0, v13
	v_fmac_f32_e32 v2, v164, v12
	v_max_f32_e32 v14, 0, v14
	v_fmac_f32_e32 v2, v163, v13
	v_fmac_f32_e32 v2, v162, v14
	v_max_f32_e32 v3, 0, v15
	v_fmac_f32_e32 v2, v161, v3
	v_max_f32_e32 v3, 0, v16
	v_fmac_f32_e32 v2, v160, v3
	v_mfma_f32_32x32x16_bf16 v[18:33], v[42:45], v[62:65], v[18:33]
	v_max_f32_e32 v3, 0, v17
	v_fmac_f32_e32 v2, v89, v3
	v_not_b32_e32 v3, v2
	v_or_b32_e32 v4, 0x80000000, v2
	v_cmp_gt_i32_e32 vcc, 0, v2
	s_nop 1
	v_cndmask_b32_e32 v2, v4, v3, vcc
	v_cmp_le_u32_e32 vcc, v157, v87
	s_nop 1
	v_cndmask_b32_e32 v70, 0, v2, vcc
.LBB0_651:
	s_or_b64 exec, exec, s[82:83]
	s_nop 11
	v_max_f32_e32 v18, 0, v18
	v_max_f32_e32 v19, 0, v19
	v_fma_f32 v18, v174, v18, 0
	v_max_f32_e32 v20, 0, v20
	v_fmac_f32_e32 v18, v173, v19
	v_max_f32_e32 v21, 0, v21
	v_fmac_f32_e32 v18, v172, v20
	v_max_f32_e32 v22, 0, v22
	v_fmac_f32_e32 v18, v171, v21
	v_max_f32_e32 v23, 0, v23
	v_fmac_f32_e32 v18, v170, v22
	v_max_f32_e32 v24, 0, v24
	v_fmac_f32_e32 v18, v169, v23
	v_max_f32_e32 v25, 0, v25
	v_fmac_f32_e32 v18, v168, v24
	v_max_f32_e32 v26, 0, v26
	v_fmac_f32_e32 v18, v167, v25
	v_max_f32_e32 v27, 0, v27
	v_fmac_f32_e32 v18, v166, v26
	v_max_f32_e32 v28, 0, v28
	v_fmac_f32_e32 v18, v165, v27
	v_max_f32_e32 v29, 0, v29
	v_fmac_f32_e32 v18, v164, v28
	v_max_f32_e32 v30, 0, v30
	v_fmac_f32_e32 v18, v163, v29
	v_max_f32_e32 v31, 0, v31
	v_fmac_f32_e32 v18, v162, v30
	v_max_f32_e32 v32, 0, v32
	v_fmac_f32_e32 v18, v161, v31
	v_fmac_f32_e32 v18, v160, v32
	v_max_f32_e32 v19, 0, v33
	v_fmac_f32_e32 v18, v89, v19
	v_not_b32_e32 v19, v18
	v_or_b32_e32 v20, 0x80000000, v18
	v_cmp_gt_i32_e32 vcc, 0, v18
	s_nop 1
	v_cndmask_b32_e32 v18, v20, v19, vcc
	v_cmp_le_u32_e32 vcc, v158, v87
	s_nop 1
	v_cndmask_b32_e32 v18, 0, v18, vcc
	s_branch .Lidxp_end
.Lidxp_e1:
	s_or_b64 exec, exec, s[80:81]
	s_nop 11
	v_max_f32_e32 v2, 0, v2
	v_fma_f32 v2, v174, v2, 0
	v_max_f32_e32 v3, 0, v3
	v_fmac_f32_e32 v2, v173, v3
	v_max_f32_e32 v3, 0, v4
	v_fmac_f32_e32 v2, v172, v3
	v_max_f32_e32 v3, 0, v5
	v_fmac_f32_e32 v2, v171, v3
	v_max_f32_e32 v3, 0, v6
	v_fmac_f32_e32 v2, v170, v3
	v_max_f32_e32 v3, 0, v7
	v_fmac_f32_e32 v2, v169, v3
	v_max_f32_e32 v3, 0, v8
	v_fmac_f32_e32 v2, v168, v3
	v_max_f32_e32 v3, 0, v9
	v_fmac_f32_e32 v2, v167, v3
	v_max_f32_e32 v3, 0, v10
	v_fmac_f32_e32 v2, v166, v3
	v_max_f32_e32 v3, 0, v11
	v_fmac_f32_e32 v2, v165, v3
	v_max_f32_e32 v3, 0, v12
	v_fmac_f32_e32 v2, v164, v3
	v_max_f32_e32 v3, 0, v13
	v_fmac_f32_e32 v2, v163, v3
	v_max_f32_e32 v3, 0, v14
	v_fmac_f32_e32 v2, v162, v3
	v_max_f32_e32 v3, 0, v15
	v_fmac_f32_e32 v2, v161, v3
	v_max_f32_e32 v3, 0, v16
	v_fmac_f32_e32 v2, v160, v3
	v_max_f32_e32 v3, 0, v17
	v_fmac_f32_e32 v2, v89, v3
	v_not_b32_e32 v3, v2
	v_or_b32_e32 v4, 0x80000000, v2
	v_cmp_gt_i32_e32 vcc, 0, v2
	s_nop 1
	v_cndmask_b32_e32 v2, v4, v3, vcc
	v_cmp_le_u32_e32 vcc, v93, v87
	s_nop 1
	v_cndmask_b32_e32 v81, 0, v2, vcc
	s_branch .Lidxp_w2
.Lidxp_e2:
	s_or_b64 exec, exec, s[74:75]
	v_max_f32_e32 v18, 0, v18
	v_max_f32_e32 v19, 0, v19
	v_fma_f32 v18, v174, v18, 0
	v_max_f32_e32 v20, 0, v20
	v_fmac_f32_e32 v18, v173, v19
	v_max_f32_e32 v21, 0, v21
	v_fmac_f32_e32 v18, v172, v20
	v_max_f32_e32 v22, 0, v22
	v_fmac_f32_e32 v18, v171, v21
	v_max_f32_e32 v23, 0, v23
	v_fmac_f32_e32 v18, v170, v22
	v_max_f32_e32 v24, 0, v24
	v_fmac_f32_e32 v18, v169, v23
	v_max_f32_e32 v25, 0, v25
	v_fmac_f32_e32 v18, v168, v24
	v_max_f32_e32 v26, 0, v26
	v_fmac_f32_e32 v18, v167, v25
	v_max_f32_e32 v27, 0, v27
	v_fmac_f32_e32 v18, v166, v26
	v_max_f32_e32 v28, 0, v28
	v_fmac_f32_e32 v18, v165, v27
	v_max_f32_e32 v29, 0, v29
	v_fmac_f32_e32 v18, v164, v28
	v_max_f32_e32 v30, 0, v30
	v_fmac_f32_e32 v18, v163, v29
	v_fmac_f32_e32 v18, v162, v30
	v_max_f32_e32 v19, 0, v31
	v_fmac_f32_e32 v18, v161, v19
	v_max_f32_e32 v19, 0, v32
	v_fmac_f32_e32 v18, v160, v19
	v_max_f32_e32 v19, 0, v33
	v_fmac_f32_e32 v18, v89, v19
	v_not_b32_e32 v19, v18
	v_or_b32_e32 v20, 0x80000000, v18
	v_cmp_gt_i32_e32 vcc, 0, v18
	s_nop 1
	v_cndmask_b32_e32 v18, v20, v19, vcc
	v_cmp_le_u32_e32 vcc, v96, v87
	s_nop 1
	v_cndmask_b32_e32 v175, 0, v18, vcc
	s_branch .Lidxp_w3
.Lidxp_e3:
	s_or_b64 exec, exec, s[74:75]
	v_max_f32_e32 v2, 0, v2
	v_max_f32_e32 v3, 0, v3
	v_fma_f32 v2, v174, v2, 0
	v_max_f32_e32 v4, 0, v4
	v_fmac_f32_e32 v2, v173, v3
	v_max_f32_e32 v5, 0, v5
	v_fmac_f32_e32 v2, v172, v4
	v_max_f32_e32 v6, 0, v6
	v_fmac_f32_e32 v2, v171, v5
	v_max_f32_e32 v7, 0, v7
	v_fmac_f32_e32 v2, v170, v6
	v_max_f32_e32 v8, 0, v8
	v_fmac_f32_e32 v2, v169, v7
	v_max_f32_e32 v9, 0, v9
	v_fmac_f32_e32 v2, v168, v8
	v_max_f32_e32 v10, 0, v10
	v_fmac_f32_e32 v2, v167, v9
	v_max_f32_e32 v11, 0, v11
	v_fmac_f32_e32 v2, v166, v10
	v_max_f32_e32 v12, 0, v12
	v_fmac_f32_e32 v2, v165, v11
	v_max_f32_e32 v13, 0, v13
	v_fmac_f32_e32 v2, v164, v12
	v_max_f32_e32 v14, 0, v14
	v_fmac_f32_e32 v2, v163, v13
	v_fmac_f32_e32 v2, v162, v14
	v_max_f32_e32 v3, 0, v15
	v_fmac_f32_e32 v2, v161, v3
	v_max_f32_e32 v3, 0, v16
	v_fmac_f32_e32 v2, v160, v3
	v_max_f32_e32 v3, 0, v17
	v_fmac_f32_e32 v2, v89, v3
	v_not_b32_e32 v3, v2
	v_or_b32_e32 v4, 0x80000000, v2
	v_cmp_gt_i32_e32 vcc, 0, v2
	s_nop 1
	v_cndmask_b32_e32 v2, v4, v3, vcc
	v_cmp_le_u32_e32 vcc, v97, v87
	s_nop 1
	v_cndmask_b32_e32 v176, 0, v2, vcc
	s_branch .Lidxp_w4
.Lidxp_e4:
	s_or_b64 exec, exec, s[74:75]
	v_max_f32_e32 v18, 0, v18
	v_max_f32_e32 v19, 0, v19
	v_fma_f32 v18, v174, v18, 0
	v_max_f32_e32 v20, 0, v20
	v_fmac_f32_e32 v18, v173, v19
	v_max_f32_e32 v21, 0, v21
	v_fmac_f32_e32 v18, v172, v20
	v_max_f32_e32 v22, 0, v22
	v_fmac_f32_e32 v18, v171, v21
	v_max_f32_e32 v23, 0, v23
	v_fmac_f32_e32 v18, v170, v22
	v_max_f32_e32 v24, 0, v24
	v_fmac_f32_e32 v18, v169, v23
	v_max_f32_e32 v25, 0, v25
	v_fmac_f32_e32 v18, v168, v24
	v_max_f32_e32 v26, 0, v26
	v_fmac_f32_e32 v18, v167, v25
	v_max_f32_e32 v27, 0, v27
	v_fmac_f32_e32 v18, v166, v26
	v_max_f32_e32 v28, 0, v28
	v_fmac_f32_e32 v18, v165, v27
	v_max_f32_e32 v29, 0, v29
	v_fmac_f32_e32 v18, v164, v28
	v_max_f32_e32 v30, 0, v30
	v_fmac_f32_e32 v18, v163, v29
	v_fmac_f32_e32 v18, v162, v30
	v_max_f32_e32 v19, 0, v31
	v_fmac_f32_e32 v18, v161, v19
	v_max_f32_e32 v19, 0, v32
	v_fmac_f32_e32 v18, v160, v19
	v_max_f32_e32 v19, 0, v33
	v_fmac_f32_e32 v18, v89, v19
	v_not_b32_e32 v19, v18
	v_or_b32_e32 v20, 0x80000000, v18
	v_cmp_gt_i32_e32 vcc, 0, v18
	s_nop 1
	v_cndmask_b32_e32 v18, v20, v19, vcc
	v_cmp_le_u32_e32 vcc, v98, v87
	s_nop 1
	v_cndmask_b32_e32 v179, 0, v18, vcc
	s_branch .Lidxp_w5
.Lidxp_e5:
	s_or_b64 exec, exec, s[74:75]
	v_max_f32_e32 v2, 0, v2
	v_max_f32_e32 v3, 0, v3
	v_fma_f32 v2, v174, v2, 0
	v_max_f32_e32 v4, 0, v4
	v_fmac_f32_e32 v2, v173, v3
	v_max_f32_e32 v5, 0, v5
	v_fmac_f32_e32 v2, v172, v4
	v_max_f32_e32 v6, 0, v6
	v_fmac_f32_e32 v2, v171, v5
	v_max_f32_e32 v7, 0, v7
	v_fmac_f32_e32 v2, v170, v6
	v_max_f32_e32 v8, 0, v8
	v_fmac_f32_e32 v2, v169, v7
	v_max_f32_e32 v9, 0, v9
	v_fmac_f32_e32 v2, v168, v8
	v_max_f32_e32 v10, 0, v10
	v_fmac_f32_e32 v2, v167, v9
	v_max_f32_e32 v11, 0, v11
	v_fmac_f32_e32 v2, v166, v10
	v_max_f32_e32 v12, 0, v12
	v_fmac_f32_e32 v2, v165, v11
	v_max_f32_e32 v13, 0, v13
	v_fmac_f32_e32 v2, v164, v12
	v_max_f32_e32 v14, 0, v14
	v_fmac_f32_e32 v2, v163, v13
	v_fmac_f32_e32 v2, v162, v14
	v_max_f32_e32 v3, 0, v15
	v_fmac_f32_e32 v2, v161, v3
	v_max_f32_e32 v3, 0, v16
	v_fmac_f32_e32 v2, v160, v3
	v_max_f32_e32 v3, 0, v17
	v_fmac_f32_e32 v2, v89, v3
	v_not_b32_e32 v3, v2
	v_or_b32_e32 v4, 0x80000000, v2
	v_cmp_gt_i32_e32 vcc, 0, v2
	s_nop 1
	v_cndmask_b32_e32 v2, v4, v3, vcc
	v_cmp_le_u32_e32 vcc, v99, v87
	s_nop 1
	v_cndmask_b32_e32 v180, 0, v2, vcc
	s_branch .Lidxp_w6
.Lidxp_e6:
	s_or_b64 exec, exec, s[74:75]
	v_max_f32_e32 v18, 0, v18
	v_max_f32_e32 v19, 0, v19
	v_fma_f32 v18, v174, v18, 0
	v_max_f32_e32 v20, 0, v20
	v_fmac_f32_e32 v18, v173, v19
	v_max_f32_e32 v21, 0, v21
	v_fmac_f32_e32 v18, v172, v20
	v_max_f32_e32 v22, 0, v22
	v_fmac_f32_e32 v18, v171, v21
	v_max_f32_e32 v23, 0, v23
	v_fmac_f32_e32 v18, v170, v22
	v_max_f32_e32 v24, 0, v24
	v_fmac_f32_e32 v18, v169, v23
	v_max_f32_e32 v25, 0, v25
	v_fmac_f32_e32 v18, v168, v24
	v_max_f32_e32 v26, 0, v26
	v_fmac_f32_e32 v18, v167, v25
	v_max_f32_e32 v27, 0, v27
	v_fmac_f32_e32 v18, v166, v26
	v_max_f32_e32 v28, 0, v28
	v_fmac_f32_e32 v18, v165, v27
	v_max_f32_e32 v29, 0, v29
	v_fmac_f32_e32 v18, v164, v28
	v_max_f32_e32 v30, 0, v30
	v_fmac_f32_e32 v18, v163, v29
	v_fmac_f32_e32 v18, v162, v30
	v_max_f32_e32 v19, 0, v31
	v_fmac_f32_e32 v18, v161, v19
	v_max_f32_e32 v19, 0, v32
	v_fmac_f32_e32 v18, v160, v19
	v_max_f32_e32 v19, 0, v33
	v_fmac_f32_e32 v18, v89, v19
	v_not_b32_e32 v19, v18
	v_or_b32_e32 v20, 0x80000000, v18
	v_cmp_gt_i32_e32 vcc, 0, v18
	s_nop 1
	v_cndmask_b32_e32 v18, v20, v19, vcc
	v_cmp_le_u32_e32 vcc, v100, v87
	s_nop 1
	v_cndmask_b32_e32 v181, 0, v18, vcc
	s_branch .Lidxp_w7
.Lidxp_e7:
	s_or_b64 exec, exec, s[74:75]
	v_max_f32_e32 v2, 0, v2
	v_max_f32_e32 v3, 0, v3
	v_fma_f32 v2, v174, v2, 0
	v_max_f32_e32 v4, 0, v4
	v_fmac_f32_e32 v2, v173, v3
	v_max_f32_e32 v5, 0, v5
	v_fmac_f32_e32 v2, v172, v4
	v_max_f32_e32 v6, 0, v6
	v_fmac_f32_e32 v2, v171, v5
	v_max_f32_e32 v7, 0, v7
	v_fmac_f32_e32 v2, v170, v6
	v_max_f32_e32 v8, 0, v8
	v_fmac_f32_e32 v2, v169, v7
	v_max_f32_e32 v9, 0, v9
	v_fmac_f32_e32 v2, v168, v8
	v_max_f32_e32 v10, 0, v10
	v_fmac_f32_e32 v2, v167, v9
	v_max_f32_e32 v11, 0, v11
	v_fmac_f32_e32 v2, v166, v10
	v_max_f32_e32 v12, 0, v12
	v_fmac_f32_e32 v2, v165, v11
	v_max_f32_e32 v13, 0, v13
	v_fmac_f32_e32 v2, v164, v12
	v_max_f32_e32 v14, 0, v14
	v_fmac_f32_e32 v2, v163, v13
	v_fmac_f32_e32 v2, v162, v14
	v_max_f32_e32 v3, 0, v15
	v_fmac_f32_e32 v2, v161, v3
	v_max_f32_e32 v3, 0, v16
	v_fmac_f32_e32 v2, v160, v3
	v_max_f32_e32 v3, 0, v17
	v_fmac_f32_e32 v2, v89, v3
	v_not_b32_e32 v3, v2
	v_or_b32_e32 v4, 0x80000000, v2
	v_cmp_gt_i32_e32 vcc, 0, v2
	s_nop 1
	v_cndmask_b32_e32 v2, v4, v3, vcc
	v_cmp_le_u32_e32 vcc, v101, v87
	s_nop 1
	v_cndmask_b32_e32 v182, 0, v2, vcc
	s_branch .Lidxp_w8
.Lidxp_e8:
	s_or_b64 exec, exec, s[82:83]
	v_max_f32_e32 v18, 0, v18
	v_max_f32_e32 v19, 0, v19
	v_fma_f32 v18, v174, v18, 0
	v_max_f32_e32 v20, 0, v20
	v_fmac_f32_e32 v18, v173, v19
	v_max_f32_e32 v21, 0, v21
	v_fmac_f32_e32 v18, v172, v20
	v_max_f32_e32 v22, 0, v22
	v_fmac_f32_e32 v18, v171, v21
	v_max_f32_e32 v23, 0, v23
	v_fmac_f32_e32 v18, v170, v22
	v_max_f32_e32 v24, 0, v24
	v_fmac_f32_e32 v18, v169, v23
	v_max_f32_e32 v25, 0, v25
	v_fmac_f32_e32 v18, v168, v24
	v_max_f32_e32 v26, 0, v26
	v_fmac_f32_e32 v18, v167, v25
	v_max_f32_e32 v27, 0, v27
	v_fmac_f32_e32 v18, v166, v26
	v_max_f32_e32 v28, 0, v28
	v_fmac_f32_e32 v18, v165, v27
	v_max_f32_e32 v29, 0, v29
	v_fmac_f32_e32 v18, v164, v28
	v_max_f32_e32 v30, 0, v30
	v_fmac_f32_e32 v18, v163, v29
	v_fmac_f32_e32 v18, v162, v30
	v_max_f32_e32 v19, 0, v31
	v_fmac_f32_e32 v18, v161, v19
	v_max_f32_e32 v19, 0, v32
	v_fmac_f32_e32 v18, v160, v19
	v_max_f32_e32 v19, 0, v33
	v_fmac_f32_e32 v18, v89, v19
	v_not_b32_e32 v19, v18
	v_or_b32_e32 v20, 0x80000000, v18
	v_cmp_gt_i32_e32 vcc, 0, v18
	s_nop 1
	v_cndmask_b32_e32 v18, v20, v19, vcc
	v_cmp_le_u32_e32 vcc, v102, v87
	s_nop 1
	v_cndmask_b32_e32 v183, 0, v18, vcc
	s_branch .Lidxp_w9
.Lidxp_e9:
	s_or_b64 exec, exec, s[82:83]
	v_max_f32_e32 v2, 0, v2
	v_max_f32_e32 v3, 0, v3
	v_fma_f32 v2, v174, v2, 0
	v_max_f32_e32 v4, 0, v4
	v_fmac_f32_e32 v2, v173, v3
	v_max_f32_e32 v5, 0, v5
	v_fmac_f32_e32 v2, v172, v4
	v_max_f32_e32 v6, 0, v6
	v_fmac_f32_e32 v2, v171, v5
	v_max_f32_e32 v7, 0, v7
	v_fmac_f32_e32 v2, v170, v6
	v_max_f32_e32 v8, 0, v8
	v_fmac_f32_e32 v2, v169, v7
	v_max_f32_e32 v9, 0, v9
	v_fmac_f32_e32 v2, v168, v8
	v_max_f32_e32 v10, 0, v10
	v_fmac_f32_e32 v2, v167, v9
	v_max_f32_e32 v11, 0, v11
	v_fmac_f32_e32 v2, v166, v10
	v_max_f32_e32 v12, 0, v12
	v_fmac_f32_e32 v2, v165, v11
	v_max_f32_e32 v13, 0, v13
	v_fmac_f32_e32 v2, v164, v12
	v_max_f32_e32 v14, 0, v14
	v_fmac_f32_e32 v2, v163, v13
	v_fmac_f32_e32 v2, v162, v14
	v_max_f32_e32 v3, 0, v15
	v_fmac_f32_e32 v2, v161, v3
	v_max_f32_e32 v3, 0, v16
	v_fmac_f32_e32 v2, v160, v3
	v_max_f32_e32 v3, 0, v17
	v_fmac_f32_e32 v2, v89, v3
	v_not_b32_e32 v3, v2
	v_or_b32_e32 v4, 0x80000000, v2
	v_cmp_gt_i32_e32 vcc, 0, v2
	s_nop 1
	v_cndmask_b32_e32 v2, v4, v3, vcc
	v_cmp_le_u32_e32 vcc, v103, v87
	s_nop 1
	v_cndmask_b32_e32 v184, 0, v2, vcc
	s_branch .Lidxp_w10
.Lidxp_e10:
	s_or_b64 exec, exec, s[82:83]
	v_max_f32_e32 v18, 0, v18
	v_max_f32_e32 v19, 0, v19
	v_fma_f32 v18, v174, v18, 0
	v_max_f32_e32 v20, 0, v20
	v_fmac_f32_e32 v18, v173, v19
	v_max_f32_e32 v21, 0, v21
	v_fmac_f32_e32 v18, v172, v20
	v_max_f32_e32 v22, 0, v22
	v_fmac_f32_e32 v18, v171, v21
	v_max_f32_e32 v23, 0, v23
	v_fmac_f32_e32 v18, v170, v22
	v_max_f32_e32 v24, 0, v24
	v_fmac_f32_e32 v18, v169, v23
	v_max_f32_e32 v25, 0, v25
	v_fmac_f32_e32 v18, v168, v24
	v_max_f32_e32 v26, 0, v26
	v_fmac_f32_e32 v18, v167, v25
	v_max_f32_e32 v27, 0, v27
	v_fmac_f32_e32 v18, v166, v26
	v_max_f32_e32 v28, 0, v28
	v_fmac_f32_e32 v18, v165, v27
	v_max_f32_e32 v29, 0, v29
	v_fmac_f32_e32 v18, v164, v28
	v_max_f32_e32 v30, 0, v30
	v_fmac_f32_e32 v18, v163, v29
	v_fmac_f32_e32 v18, v162, v30
	v_max_f32_e32 v19, 0, v31
	v_fmac_f32_e32 v18, v161, v19
	v_max_f32_e32 v19, 0, v32
	v_fmac_f32_e32 v18, v160, v19
	v_max_f32_e32 v19, 0, v33
	v_fmac_f32_e32 v18, v89, v19
	v_not_b32_e32 v19, v18
	v_or_b32_e32 v20, 0x80000000, v18
	v_cmp_gt_i32_e32 vcc, 0, v18
	s_nop 1
	v_cndmask_b32_e32 v18, v20, v19, vcc
	v_cmp_le_u32_e32 vcc, v104, v87
	s_nop 1
	v_cndmask_b32_e32 v185, 0, v18, vcc
	s_branch .Lidxp_w11
.Lidxp_e11:
	s_or_b64 exec, exec, s[82:83]
	v_max_f32_e32 v2, 0, v2
	v_max_f32_e32 v3, 0, v3
	v_fma_f32 v2, v174, v2, 0
	v_max_f32_e32 v4, 0, v4
	v_fmac_f32_e32 v2, v173, v3
	v_max_f32_e32 v5, 0, v5
	v_fmac_f32_e32 v2, v172, v4
	v_max_f32_e32 v6, 0, v6
	v_fmac_f32_e32 v2, v171, v5
	v_max_f32_e32 v7, 0, v7
	v_fmac_f32_e32 v2, v170, v6
	v_max_f32_e32 v8, 0, v8
	v_fmac_f32_e32 v2, v169, v7
	v_max_f32_e32 v9, 0, v9
	v_fmac_f32_e32 v2, v168, v8
	v_max_f32_e32 v10, 0, v10
	v_fmac_f32_e32 v2, v167, v9
	v_max_f32_e32 v11, 0, v11
	v_fmac_f32_e32 v2, v166, v10
	v_max_f32_e32 v12, 0, v12
	v_fmac_f32_e32 v2, v165, v11
	v_max_f32_e32 v13, 0, v13
	v_fmac_f32_e32 v2, v164, v12
	v_max_f32_e32 v14, 0, v14
	v_fmac_f32_e32 v2, v163, v13
	v_fmac_f32_e32 v2, v162, v14
	v_max_f32_e32 v3, 0, v15
	v_fmac_f32_e32 v2, v161, v3
	v_max_f32_e32 v3, 0, v16
	v_fmac_f32_e32 v2, v160, v3
	v_max_f32_e32 v3, 0, v17
	v_fmac_f32_e32 v2, v89, v3
	v_not_b32_e32 v3, v2
	v_or_b32_e32 v4, 0x80000000, v2
	v_cmp_gt_i32_e32 vcc, 0, v2
	s_nop 1
	v_cndmask_b32_e32 v2, v4, v3, vcc
	v_cmp_le_u32_e32 vcc, v105, v87
	s_nop 1
	v_cndmask_b32_e32 v186, 0, v2, vcc
	s_branch .Lidxp_w12
.Lidxp_e12:
	s_or_b64 exec, exec, s[82:83]
	v_max_f32_e32 v18, 0, v18
	v_max_f32_e32 v19, 0, v19
	v_fma_f32 v18, v174, v18, 0
	v_max_f32_e32 v20, 0, v20
	v_fmac_f32_e32 v18, v173, v19
	v_max_f32_e32 v21, 0, v21
	v_fmac_f32_e32 v18, v172, v20
	v_max_f32_e32 v22, 0, v22
	v_fmac_f32_e32 v18, v171, v21
	v_max_f32_e32 v23, 0, v23
	v_fmac_f32_e32 v18, v170, v22
	v_max_f32_e32 v24, 0, v24
	v_fmac_f32_e32 v18, v169, v23
	v_max_f32_e32 v25, 0, v25
	v_fmac_f32_e32 v18, v168, v24
	v_max_f32_e32 v26, 0, v26
	v_fmac_f32_e32 v18, v167, v25
	v_max_f32_e32 v27, 0, v27
	v_fmac_f32_e32 v18, v166, v26
	v_max_f32_e32 v28, 0, v28
	v_fmac_f32_e32 v18, v165, v27
	v_max_f32_e32 v29, 0, v29
	v_fmac_f32_e32 v18, v164, v28
	v_max_f32_e32 v30, 0, v30
	v_fmac_f32_e32 v18, v163, v29
	v_fmac_f32_e32 v18, v162, v30
	v_max_f32_e32 v19, 0, v31
	v_fmac_f32_e32 v18, v161, v19
	v_max_f32_e32 v19, 0, v32
	v_fmac_f32_e32 v18, v160, v19
	v_max_f32_e32 v19, 0, v33
	v_fmac_f32_e32 v18, v89, v19
	v_not_b32_e32 v19, v18
	v_or_b32_e32 v20, 0x80000000, v18
	v_cmp_gt_i32_e32 vcc, 0, v18
	s_nop 1
	v_cndmask_b32_e32 v18, v20, v19, vcc
	v_cmp_le_u32_e32 vcc, v106, v87
	s_nop 1
	v_cndmask_b32_e32 v187, 0, v18, vcc
	s_branch .Lidxp_w13
.Lidxp_e13:
	s_or_b64 exec, exec, s[82:83]
	v_max_f32_e32 v2, 0, v2
	v_max_f32_e32 v3, 0, v3
	v_fma_f32 v2, v174, v2, 0
	v_max_f32_e32 v4, 0, v4
	v_fmac_f32_e32 v2, v173, v3
	v_max_f32_e32 v5, 0, v5
	v_fmac_f32_e32 v2, v172, v4
	v_max_f32_e32 v6, 0, v6
	v_fmac_f32_e32 v2, v171, v5
	v_max_f32_e32 v7, 0, v7
	v_fmac_f32_e32 v2, v170, v6
	v_max_f32_e32 v8, 0, v8
	v_fmac_f32_e32 v2, v169, v7
	v_max_f32_e32 v9, 0, v9
	v_fmac_f32_e32 v2, v168, v8
	v_max_f32_e32 v10, 0, v10
	v_fmac_f32_e32 v2, v167, v9
	v_max_f32_e32 v11, 0, v11
	v_fmac_f32_e32 v2, v166, v10
	v_max_f32_e32 v12, 0, v12
	v_fmac_f32_e32 v2, v165, v11
	v_max_f32_e32 v13, 0, v13
	v_fmac_f32_e32 v2, v164, v12
	v_max_f32_e32 v14, 0, v14
	v_fmac_f32_e32 v2, v163, v13
	v_fmac_f32_e32 v2, v162, v14
	v_max_f32_e32 v3, 0, v15
	v_fmac_f32_e32 v2, v161, v3
	v_max_f32_e32 v3, 0, v16
	v_fmac_f32_e32 v2, v160, v3
	v_max_f32_e32 v3, 0, v17
	v_fmac_f32_e32 v2, v89, v3
	v_not_b32_e32 v3, v2
	v_or_b32_e32 v4, 0x80000000, v2
	v_cmp_gt_i32_e32 vcc, 0, v2
	s_nop 1
	v_cndmask_b32_e32 v2, v4, v3, vcc
	v_cmp_le_u32_e32 vcc, v107, v87
	s_nop 1
	v_cndmask_b32_e32 v188, 0, v2, vcc
	s_branch .Lidxp_w14
.Lidxp_e14:
	s_or_b64 exec, exec, s[82:83]
	v_max_f32_e32 v18, 0, v18
	v_max_f32_e32 v19, 0, v19
	v_fma_f32 v18, v174, v18, 0
	v_max_f32_e32 v20, 0, v20
	v_fmac_f32_e32 v18, v173, v19
	v_max_f32_e32 v21, 0, v21
	v_fmac_f32_e32 v18, v172, v20
	v_max_f32_e32 v22, 0, v22
	v_fmac_f32_e32 v18, v171, v21
	v_max_f32_e32 v23, 0, v23
	v_fmac_f32_e32 v18, v170, v22
	v_max_f32_e32 v24, 0, v24
	v_fmac_f32_e32 v18, v169, v23
	v_max_f32_e32 v25, 0, v25
	v_fmac_f32_e32 v18, v168, v24
	v_max_f32_e32 v26, 0, v26
	v_fmac_f32_e32 v18, v167, v25
	v_max_f32_e32 v27, 0, v27
	v_fmac_f32_e32 v18, v166, v26
	v_max_f32_e32 v28, 0, v28
	v_fmac_f32_e32 v18, v165, v27
	v_max_f32_e32 v29, 0, v29
	v_fmac_f32_e32 v18, v164, v28
	v_max_f32_e32 v30, 0, v30
	v_fmac_f32_e32 v18, v163, v29
	v_fmac_f32_e32 v18, v162, v30
	v_max_f32_e32 v19, 0, v31
	v_fmac_f32_e32 v18, v161, v19
	v_max_f32_e32 v19, 0, v32
	v_fmac_f32_e32 v18, v160, v19
	v_max_f32_e32 v19, 0, v33
	v_fmac_f32_e32 v18, v89, v19
	v_not_b32_e32 v19, v18
	v_or_b32_e32 v20, 0x80000000, v18
	v_cmp_gt_i32_e32 vcc, 0, v18
	s_nop 1
	v_cndmask_b32_e32 v18, v20, v19, vcc
	v_cmp_le_u32_e32 vcc, v108, v87
	s_nop 1
	v_cndmask_b32_e32 v189, 0, v18, vcc
	s_branch .Lidxp_w15
.Lidxp_e15:
	s_or_b64 exec, exec, s[82:83]
	v_max_f32_e32 v2, 0, v2
	v_max_f32_e32 v3, 0, v3
	v_fma_f32 v2, v174, v2, 0
	v_max_f32_e32 v4, 0, v4
	v_fmac_f32_e32 v2, v173, v3
	v_max_f32_e32 v5, 0, v5
	v_fmac_f32_e32 v2, v172, v4
	v_max_f32_e32 v6, 0, v6
	v_fmac_f32_e32 v2, v171, v5
	v_max_f32_e32 v7, 0, v7
	v_fmac_f32_e32 v2, v170, v6
	v_max_f32_e32 v8, 0, v8
	v_fmac_f32_e32 v2, v169, v7
	v_max_f32_e32 v9, 0, v9
	v_fmac_f32_e32 v2, v168, v8
	v_max_f32_e32 v10, 0, v10
	v_fmac_f32_e32 v2, v167, v9
	v_max_f32_e32 v11, 0, v11
	v_fmac_f32_e32 v2, v166, v10
	v_max_f32_e32 v12, 0, v12
	v_fmac_f32_e32 v2, v165, v11
	v_max_f32_e32 v13, 0, v13
	v_fmac_f32_e32 v2, v164, v12
	v_max_f32_e32 v14, 0, v14
	v_fmac_f32_e32 v2, v163, v13
	v_fmac_f32_e32 v2, v162, v14
	v_max_f32_e32 v3, 0, v15
	v_fmac_f32_e32 v2, v161, v3
	v_max_f32_e32 v3, 0, v16
	v_fmac_f32_e32 v2, v160, v3
	v_max_f32_e32 v3, 0, v17
	v_fmac_f32_e32 v2, v89, v3
	v_not_b32_e32 v3, v2
	v_or_b32_e32 v4, 0x80000000, v2
	v_cmp_gt_i32_e32 vcc, 0, v2
	s_nop 1
	v_cndmask_b32_e32 v2, v4, v3, vcc
	v_cmp_le_u32_e32 vcc, v109, v87
	s_nop 1
	v_cndmask_b32_e32 v190, 0, v2, vcc
	s_branch .Lidxp_w16
.Lidxp_e16:
	s_or_b64 exec, exec, s[82:83]
	v_max_f32_e32 v18, 0, v18
	v_max_f32_e32 v19, 0, v19
	v_fma_f32 v18, v174, v18, 0
	v_max_f32_e32 v20, 0, v20
	v_fmac_f32_e32 v18, v173, v19
	v_max_f32_e32 v21, 0, v21
	v_fmac_f32_e32 v18, v172, v20
	v_max_f32_e32 v22, 0, v22
	v_fmac_f32_e32 v18, v171, v21
	v_max_f32_e32 v23, 0, v23
	v_fmac_f32_e32 v18, v170, v22
	v_max_f32_e32 v24, 0, v24
	v_fmac_f32_e32 v18, v169, v23
	v_max_f32_e32 v25, 0, v25
	v_fmac_f32_e32 v18, v168, v24
	v_max_f32_e32 v26, 0, v26
	v_fmac_f32_e32 v18, v167, v25
	v_max_f32_e32 v27, 0, v27
	v_fmac_f32_e32 v18, v166, v26
	v_max_f32_e32 v28, 0, v28
	v_fmac_f32_e32 v18, v165, v27
	v_max_f32_e32 v29, 0, v29
	v_fmac_f32_e32 v18, v164, v28
	v_max_f32_e32 v30, 0, v30
	v_fmac_f32_e32 v18, v163, v29
	v_fmac_f32_e32 v18, v162, v30
	v_max_f32_e32 v19, 0, v31
	v_fmac_f32_e32 v18, v161, v19
	v_max_f32_e32 v19, 0, v32
	v_fmac_f32_e32 v18, v160, v19
	v_max_f32_e32 v19, 0, v33
	v_fmac_f32_e32 v18, v89, v19
	v_not_b32_e32 v19, v18
	v_or_b32_e32 v20, 0x80000000, v18
	v_cmp_gt_i32_e32 vcc, 0, v18
	s_nop 1
	v_cndmask_b32_e32 v18, v20, v19, vcc
	v_cmp_le_u32_e32 vcc, v110, v87
	s_nop 1
	v_cndmask_b32_e32 v191, 0, v18, vcc
	s_branch .Lidxp_w17
.Lidxp_e17:
	s_or_b64 exec, exec, s[82:83]
	v_max_f32_e32 v2, 0, v2
	v_max_f32_e32 v3, 0, v3
	v_fma_f32 v2, v174, v2, 0
	v_max_f32_e32 v4, 0, v4
	v_fmac_f32_e32 v2, v173, v3
	v_max_f32_e32 v5, 0, v5
	v_fmac_f32_e32 v2, v172, v4
	v_max_f32_e32 v6, 0, v6
	v_fmac_f32_e32 v2, v171, v5
	v_max_f32_e32 v7, 0, v7
	v_fmac_f32_e32 v2, v170, v6
	v_max_f32_e32 v8, 0, v8
	v_fmac_f32_e32 v2, v169, v7
	v_max_f32_e32 v9, 0, v9
	v_fmac_f32_e32 v2, v168, v8
	v_max_f32_e32 v10, 0, v10
	v_fmac_f32_e32 v2, v167, v9
	v_max_f32_e32 v11, 0, v11
	v_fmac_f32_e32 v2, v166, v10
	v_max_f32_e32 v12, 0, v12
	v_fmac_f32_e32 v2, v165, v11
	v_max_f32_e32 v13, 0, v13
	v_fmac_f32_e32 v2, v164, v12
	v_max_f32_e32 v14, 0, v14
	v_fmac_f32_e32 v2, v163, v13
	v_fmac_f32_e32 v2, v162, v14
	v_max_f32_e32 v3, 0, v15
	v_fmac_f32_e32 v2, v161, v3
	v_max_f32_e32 v3, 0, v16
	v_fmac_f32_e32 v2, v160, v3
	v_max_f32_e32 v3, 0, v17
	v_fmac_f32_e32 v2, v89, v3
	v_not_b32_e32 v3, v2
	v_or_b32_e32 v4, 0x80000000, v2
	v_cmp_gt_i32_e32 vcc, 0, v2
	s_nop 1
	v_cndmask_b32_e32 v2, v4, v3, vcc
	v_cmp_le_u32_e32 vcc, v111, v87
	s_nop 1
	v_cndmask_b32_e32 v192, 0, v2, vcc
	s_branch .Lidxp_w18
.Lidxp_e18:
	s_or_b64 exec, exec, s[82:83]
	v_max_f32_e32 v18, 0, v18
	v_max_f32_e32 v19, 0, v19
	v_fma_f32 v18, v174, v18, 0
	v_max_f32_e32 v20, 0, v20
	v_fmac_f32_e32 v18, v173, v19
	v_max_f32_e32 v21, 0, v21
	v_fmac_f32_e32 v18, v172, v20
	v_max_f32_e32 v22, 0, v22
	v_fmac_f32_e32 v18, v171, v21
	v_max_f32_e32 v23, 0, v23
	v_fmac_f32_e32 v18, v170, v22
	v_max_f32_e32 v24, 0, v24
	v_fmac_f32_e32 v18, v169, v23
	v_max_f32_e32 v25, 0, v25
	v_fmac_f32_e32 v18, v168, v24
	v_max_f32_e32 v26, 0, v26
	v_fmac_f32_e32 v18, v167, v25
	v_max_f32_e32 v27, 0, v27
	v_fmac_f32_e32 v18, v166, v26
	v_max_f32_e32 v28, 0, v28
	v_fmac_f32_e32 v18, v165, v27
	v_max_f32_e32 v29, 0, v29
	v_fmac_f32_e32 v18, v164, v28
	v_max_f32_e32 v30, 0, v30
	v_fmac_f32_e32 v18, v163, v29
	v_fmac_f32_e32 v18, v162, v30
	v_max_f32_e32 v19, 0, v31
	v_fmac_f32_e32 v18, v161, v19
	v_max_f32_e32 v19, 0, v32
	v_fmac_f32_e32 v18, v160, v19
	v_max_f32_e32 v19, 0, v33
	v_fmac_f32_e32 v18, v89, v19
	v_not_b32_e32 v19, v18
	v_or_b32_e32 v20, 0x80000000, v18
	v_cmp_gt_i32_e32 vcc, 0, v18
	s_nop 1
	v_cndmask_b32_e32 v18, v20, v19, vcc
	v_cmp_le_u32_e32 vcc, v112, v87
	s_nop 1
	v_cndmask_b32_e32 v193, 0, v18, vcc
	s_branch .Lidxp_w19
.Lidxp_e19:
	s_or_b64 exec, exec, s[82:83]
	v_max_f32_e32 v2, 0, v2
	v_max_f32_e32 v3, 0, v3
	v_fma_f32 v2, v174, v2, 0
	v_max_f32_e32 v4, 0, v4
	v_fmac_f32_e32 v2, v173, v3
	v_max_f32_e32 v5, 0, v5
	v_fmac_f32_e32 v2, v172, v4
	v_max_f32_e32 v6, 0, v6
	v_fmac_f32_e32 v2, v171, v5
	v_max_f32_e32 v7, 0, v7
	v_fmac_f32_e32 v2, v170, v6
	v_max_f32_e32 v8, 0, v8
	v_fmac_f32_e32 v2, v169, v7
	v_max_f32_e32 v9, 0, v9
	v_fmac_f32_e32 v2, v168, v8
	v_max_f32_e32 v10, 0, v10
	v_fmac_f32_e32 v2, v167, v9
	v_max_f32_e32 v11, 0, v11
	v_fmac_f32_e32 v2, v166, v10
	v_max_f32_e32 v12, 0, v12
	v_fmac_f32_e32 v2, v165, v11
	v_max_f32_e32 v13, 0, v13
	v_fmac_f32_e32 v2, v164, v12
	v_max_f32_e32 v14, 0, v14
	v_fmac_f32_e32 v2, v163, v13
	v_fmac_f32_e32 v2, v162, v14
	v_max_f32_e32 v3, 0, v15
	v_fmac_f32_e32 v2, v161, v3
	v_max_f32_e32 v3, 0, v16
	v_fmac_f32_e32 v2, v160, v3
	v_max_f32_e32 v3, 0, v17
	v_fmac_f32_e32 v2, v89, v3
	v_not_b32_e32 v3, v2
	v_or_b32_e32 v4, 0x80000000, v2
	v_cmp_gt_i32_e32 vcc, 0, v2
	s_nop 1
	v_cndmask_b32_e32 v2, v4, v3, vcc
	v_cmp_le_u32_e32 vcc, v113, v87
	s_nop 1
	v_cndmask_b32_e32 v194, 0, v2, vcc
	s_branch .Lidxp_w20
.Lidxp_e20:
	s_or_b64 exec, exec, s[82:83]
	v_max_f32_e32 v18, 0, v18
	v_max_f32_e32 v19, 0, v19
	v_fma_f32 v18, v174, v18, 0
	v_max_f32_e32 v20, 0, v20
	v_fmac_f32_e32 v18, v173, v19
	v_max_f32_e32 v21, 0, v21
	v_fmac_f32_e32 v18, v172, v20
	v_max_f32_e32 v22, 0, v22
	v_fmac_f32_e32 v18, v171, v21
	v_max_f32_e32 v23, 0, v23
	v_fmac_f32_e32 v18, v170, v22
	v_max_f32_e32 v24, 0, v24
	v_fmac_f32_e32 v18, v169, v23
	v_max_f32_e32 v25, 0, v25
	v_fmac_f32_e32 v18, v168, v24
	v_max_f32_e32 v26, 0, v26
	v_fmac_f32_e32 v18, v167, v25
	v_max_f32_e32 v27, 0, v27
	v_fmac_f32_e32 v18, v166, v26
	v_max_f32_e32 v28, 0, v28
	v_fmac_f32_e32 v18, v165, v27
	v_max_f32_e32 v29, 0, v29
	v_fmac_f32_e32 v18, v164, v28
	v_max_f32_e32 v30, 0, v30
	v_fmac_f32_e32 v18, v163, v29
	v_fmac_f32_e32 v18, v162, v30
	v_max_f32_e32 v19, 0, v31
	v_fmac_f32_e32 v18, v161, v19
	v_max_f32_e32 v19, 0, v32
	v_fmac_f32_e32 v18, v160, v19
	v_max_f32_e32 v19, 0, v33
	v_fmac_f32_e32 v18, v89, v19
	v_not_b32_e32 v19, v18
	v_or_b32_e32 v20, 0x80000000, v18
	v_cmp_gt_i32_e32 vcc, 0, v18
	s_nop 1
	v_cndmask_b32_e32 v18, v20, v19, vcc
	v_cmp_le_u32_e32 vcc, v114, v87
	s_nop 1
	v_cndmask_b32_e32 v195, 0, v18, vcc
	s_branch .Lidxp_w21
.Lidxp_e21:
	s_or_b64 exec, exec, s[82:83]
	v_max_f32_e32 v2, 0, v2
	v_max_f32_e32 v3, 0, v3
	v_fma_f32 v2, v174, v2, 0
	v_max_f32_e32 v4, 0, v4
	v_fmac_f32_e32 v2, v173, v3
	v_max_f32_e32 v5, 0, v5
	v_fmac_f32_e32 v2, v172, v4
	v_max_f32_e32 v6, 0, v6
	v_fmac_f32_e32 v2, v171, v5
	v_max_f32_e32 v7, 0, v7
	v_fmac_f32_e32 v2, v170, v6
	v_max_f32_e32 v8, 0, v8
	v_fmac_f32_e32 v2, v169, v7
	v_max_f32_e32 v9, 0, v9
	v_fmac_f32_e32 v2, v168, v8
	v_max_f32_e32 v10, 0, v10
	v_fmac_f32_e32 v2, v167, v9
	v_max_f32_e32 v11, 0, v11
	v_fmac_f32_e32 v2, v166, v10
	v_max_f32_e32 v12, 0, v12
	v_fmac_f32_e32 v2, v165, v11
	v_max_f32_e32 v13, 0, v13
	v_fmac_f32_e32 v2, v164, v12
	v_max_f32_e32 v14, 0, v14
	v_fmac_f32_e32 v2, v163, v13
	v_fmac_f32_e32 v2, v162, v14
	v_max_f32_e32 v3, 0, v15
	v_fmac_f32_e32 v2, v161, v3
	v_max_f32_e32 v3, 0, v16
	v_fmac_f32_e32 v2, v160, v3
	v_max_f32_e32 v3, 0, v17
	v_fmac_f32_e32 v2, v89, v3
	v_not_b32_e32 v3, v2
	v_or_b32_e32 v4, 0x80000000, v2
	v_cmp_gt_i32_e32 vcc, 0, v2
	s_nop 1
	v_cndmask_b32_e32 v2, v4, v3, vcc
	v_cmp_le_u32_e32 vcc, v115, v87
	s_nop 1
	v_cndmask_b32_e32 v196, 0, v2, vcc
	s_branch .Lidxp_w22
.Lidxp_e22:
	s_or_b64 exec, exec, s[82:83]
	v_max_f32_e32 v18, 0, v18
	v_max_f32_e32 v19, 0, v19
	v_fma_f32 v18, v174, v18, 0
	v_max_f32_e32 v20, 0, v20
	v_fmac_f32_e32 v18, v173, v19
	v_max_f32_e32 v21, 0, v21
	v_fmac_f32_e32 v18, v172, v20
	v_max_f32_e32 v22, 0, v22
	v_fmac_f32_e32 v18, v171, v21
	v_max_f32_e32 v23, 0, v23
	v_fmac_f32_e32 v18, v170, v22
	v_max_f32_e32 v24, 0, v24
	v_fmac_f32_e32 v18, v169, v23
	v_max_f32_e32 v25, 0, v25
	v_fmac_f32_e32 v18, v168, v24
	v_max_f32_e32 v26, 0, v26
	v_fmac_f32_e32 v18, v167, v25
	v_max_f32_e32 v27, 0, v27
	v_fmac_f32_e32 v18, v166, v26
	v_max_f32_e32 v28, 0, v28
	v_fmac_f32_e32 v18, v165, v27
	v_max_f32_e32 v29, 0, v29
	v_fmac_f32_e32 v18, v164, v28
	v_max_f32_e32 v30, 0, v30
	v_fmac_f32_e32 v18, v163, v29
	v_fmac_f32_e32 v18, v162, v30
	v_max_f32_e32 v19, 0, v31
	v_fmac_f32_e32 v18, v161, v19
	v_max_f32_e32 v19, 0, v32
	v_fmac_f32_e32 v18, v160, v19
	v_max_f32_e32 v19, 0, v33
	v_fmac_f32_e32 v18, v89, v19
	v_not_b32_e32 v19, v18
	v_or_b32_e32 v20, 0x80000000, v18
	v_cmp_gt_i32_e32 vcc, 0, v18
	s_nop 1
	v_cndmask_b32_e32 v18, v20, v19, vcc
	v_cmp_le_u32_e32 vcc, v116, v87
	s_nop 1
	v_cndmask_b32_e32 v197, 0, v18, vcc
	s_branch .Lidxp_w23
.Lidxp_e23:
	s_or_b64 exec, exec, s[82:83]
	v_max_f32_e32 v2, 0, v2
	v_max_f32_e32 v3, 0, v3
	v_fma_f32 v2, v174, v2, 0
	v_max_f32_e32 v4, 0, v4
	v_fmac_f32_e32 v2, v173, v3
	v_max_f32_e32 v5, 0, v5
	v_fmac_f32_e32 v2, v172, v4
	v_max_f32_e32 v6, 0, v6
	v_fmac_f32_e32 v2, v171, v5
	v_max_f32_e32 v7, 0, v7
	v_fmac_f32_e32 v2, v170, v6
	v_max_f32_e32 v8, 0, v8
	v_fmac_f32_e32 v2, v169, v7
	v_max_f32_e32 v9, 0, v9
	v_fmac_f32_e32 v2, v168, v8
	v_max_f32_e32 v10, 0, v10
	v_fmac_f32_e32 v2, v167, v9
	v_max_f32_e32 v11, 0, v11
	v_fmac_f32_e32 v2, v166, v10
	v_max_f32_e32 v12, 0, v12
	v_fmac_f32_e32 v2, v165, v11
	v_max_f32_e32 v13, 0, v13
	v_fmac_f32_e32 v2, v164, v12
	v_max_f32_e32 v14, 0, v14
	v_fmac_f32_e32 v2, v163, v13
	v_fmac_f32_e32 v2, v162, v14
	v_max_f32_e32 v3, 0, v15
	v_fmac_f32_e32 v2, v161, v3
	v_max_f32_e32 v3, 0, v16
	v_fmac_f32_e32 v2, v160, v3
	v_max_f32_e32 v3, 0, v17
	v_fmac_f32_e32 v2, v89, v3
	v_not_b32_e32 v3, v2
	v_or_b32_e32 v4, 0x80000000, v2
	v_cmp_gt_i32_e32 vcc, 0, v2
	s_nop 1
	v_cndmask_b32_e32 v2, v4, v3, vcc
	v_cmp_le_u32_e32 vcc, v117, v87
	s_nop 1
	v_cndmask_b32_e32 v216, 0, v2, vcc
	s_branch .Lidxp_w24
.Lidxp_e24:
	s_or_b64 exec, exec, s[82:83]
	v_max_f32_e32 v18, 0, v18
	v_max_f32_e32 v19, 0, v19
	v_fma_f32 v18, v174, v18, 0
	v_max_f32_e32 v20, 0, v20
	v_fmac_f32_e32 v18, v173, v19
	v_max_f32_e32 v21, 0, v21
	v_fmac_f32_e32 v18, v172, v20
	v_max_f32_e32 v22, 0, v22
	v_fmac_f32_e32 v18, v171, v21
	v_max_f32_e32 v23, 0, v23
	v_fmac_f32_e32 v18, v170, v22
	v_max_f32_e32 v24, 0, v24
	v_fmac_f32_e32 v18, v169, v23
	v_max_f32_e32 v25, 0, v25
	v_fmac_f32_e32 v18, v168, v24
	v_max_f32_e32 v26, 0, v26
	v_fmac_f32_e32 v18, v167, v25
	v_max_f32_e32 v27, 0, v27
	v_fmac_f32_e32 v18, v166, v26
	v_max_f32_e32 v28, 0, v28
	v_fmac_f32_e32 v18, v165, v27
	v_max_f32_e32 v29, 0, v29
	v_fmac_f32_e32 v18, v164, v28
	v_max_f32_e32 v30, 0, v30
	v_fmac_f32_e32 v18, v163, v29
	v_fmac_f32_e32 v18, v162, v30
	v_max_f32_e32 v19, 0, v31
	v_fmac_f32_e32 v18, v161, v19
	v_max_f32_e32 v19, 0, v32
	v_fmac_f32_e32 v18, v160, v19
	v_max_f32_e32 v19, 0, v33
	v_fmac_f32_e32 v18, v89, v19
	v_not_b32_e32 v19, v18
	v_or_b32_e32 v20, 0x80000000, v18
	v_cmp_gt_i32_e32 vcc, 0, v18
	s_nop 1
	v_cndmask_b32_e32 v18, v20, v19, vcc
	v_cmp_le_u32_e32 vcc, v118, v87
	s_nop 1
	v_cndmask_b32_e32 v217, 0, v18, vcc
	s_branch .Lidxp_w25
.Lidxp_e25:
	s_or_b64 exec, exec, s[82:83]
	v_max_f32_e32 v2, 0, v2
	v_max_f32_e32 v3, 0, v3
	v_fma_f32 v2, v174, v2, 0
	v_max_f32_e32 v4, 0, v4
	v_fmac_f32_e32 v2, v173, v3
	v_max_f32_e32 v5, 0, v5
	v_fmac_f32_e32 v2, v172, v4
	v_max_f32_e32 v6, 0, v6
	v_fmac_f32_e32 v2, v171, v5
	v_max_f32_e32 v7, 0, v7
	v_fmac_f32_e32 v2, v170, v6
	v_max_f32_e32 v8, 0, v8
	v_fmac_f32_e32 v2, v169, v7
	v_max_f32_e32 v9, 0, v9
	v_fmac_f32_e32 v2, v168, v8
	v_max_f32_e32 v10, 0, v10
	v_fmac_f32_e32 v2, v167, v9
	v_max_f32_e32 v11, 0, v11
	v_fmac_f32_e32 v2, v166, v10
	v_max_f32_e32 v12, 0, v12
	v_fmac_f32_e32 v2, v165, v11
	v_max_f32_e32 v13, 0, v13
	v_fmac_f32_e32 v2, v164, v12
	v_max_f32_e32 v14, 0, v14
	v_fmac_f32_e32 v2, v163, v13
	v_fmac_f32_e32 v2, v162, v14
	v_max_f32_e32 v3, 0, v15
	v_fmac_f32_e32 v2, v161, v3
	v_max_f32_e32 v3, 0, v16
	v_fmac_f32_e32 v2, v160, v3
	v_max_f32_e32 v3, 0, v17
	v_fmac_f32_e32 v2, v89, v3
	v_not_b32_e32 v3, v2
	v_or_b32_e32 v4, 0x80000000, v2
	v_cmp_gt_i32_e32 vcc, 0, v2
	s_nop 1
	v_cndmask_b32_e32 v2, v4, v3, vcc
	v_cmp_le_u32_e32 vcc, v119, v87
	s_nop 1
	v_cndmask_b32_e32 v218, 0, v2, vcc
	s_branch .Lidxp_w26
.Lidxp_e26:
	s_or_b64 exec, exec, s[82:83]
	v_max_f32_e32 v18, 0, v18
	v_max_f32_e32 v19, 0, v19
	v_fma_f32 v18, v174, v18, 0
	v_max_f32_e32 v20, 0, v20
	v_fmac_f32_e32 v18, v173, v19
	v_max_f32_e32 v21, 0, v21
	v_fmac_f32_e32 v18, v172, v20
	v_max_f32_e32 v22, 0, v22
	v_fmac_f32_e32 v18, v171, v21
	v_max_f32_e32 v23, 0, v23
	v_fmac_f32_e32 v18, v170, v22
	v_max_f32_e32 v24, 0, v24
	v_fmac_f32_e32 v18, v169, v23
	v_max_f32_e32 v25, 0, v25
	v_fmac_f32_e32 v18, v168, v24
	v_max_f32_e32 v26, 0, v26
	v_fmac_f32_e32 v18, v167, v25
	v_max_f32_e32 v27, 0, v27
	v_fmac_f32_e32 v18, v166, v26
	v_max_f32_e32 v28, 0, v28
	v_fmac_f32_e32 v18, v165, v27
	v_max_f32_e32 v29, 0, v29
	v_fmac_f32_e32 v18, v164, v28
	v_max_f32_e32 v30, 0, v30
	v_fmac_f32_e32 v18, v163, v29
	v_fmac_f32_e32 v18, v162, v30
	v_max_f32_e32 v19, 0, v31
	v_fmac_f32_e32 v18, v161, v19
	v_max_f32_e32 v19, 0, v32
	v_fmac_f32_e32 v18, v160, v19
	v_max_f32_e32 v19, 0, v33
	v_fmac_f32_e32 v18, v89, v19
	v_not_b32_e32 v19, v18
	v_or_b32_e32 v20, 0x80000000, v18
	v_cmp_gt_i32_e32 vcc, 0, v18
	s_nop 1
	v_cndmask_b32_e32 v18, v20, v19, vcc
	v_cmp_le_u32_e32 vcc, v120, v87
	s_nop 1
	v_cndmask_b32_e32 v219, 0, v18, vcc
	s_branch .Lidxp_w27
.Lidxp_e27:
	s_or_b64 exec, exec, s[82:83]
	v_max_f32_e32 v2, 0, v2
	v_max_f32_e32 v3, 0, v3
	v_fma_f32 v2, v174, v2, 0
	v_max_f32_e32 v4, 0, v4
	v_fmac_f32_e32 v2, v173, v3
	v_max_f32_e32 v5, 0, v5
	v_fmac_f32_e32 v2, v172, v4
	v_max_f32_e32 v6, 0, v6
	v_fmac_f32_e32 v2, v171, v5
	v_max_f32_e32 v7, 0, v7
	v_fmac_f32_e32 v2, v170, v6
	v_max_f32_e32 v8, 0, v8
	v_fmac_f32_e32 v2, v169, v7
	v_max_f32_e32 v9, 0, v9
	v_fmac_f32_e32 v2, v168, v8
	v_max_f32_e32 v10, 0, v10
	v_fmac_f32_e32 v2, v167, v9
	v_max_f32_e32 v11, 0, v11
	v_fmac_f32_e32 v2, v166, v10
	v_max_f32_e32 v12, 0, v12
	v_fmac_f32_e32 v2, v165, v11
	v_max_f32_e32 v13, 0, v13
	v_fmac_f32_e32 v2, v164, v12
	v_max_f32_e32 v14, 0, v14
	v_fmac_f32_e32 v2, v163, v13
	v_fmac_f32_e32 v2, v162, v14
	v_max_f32_e32 v3, 0, v15
	v_fmac_f32_e32 v2, v161, v3
	v_max_f32_e32 v3, 0, v16
	v_fmac_f32_e32 v2, v160, v3
	v_max_f32_e32 v3, 0, v17
	v_fmac_f32_e32 v2, v89, v3
	v_not_b32_e32 v3, v2
	v_or_b32_e32 v4, 0x80000000, v2
	v_cmp_gt_i32_e32 vcc, 0, v2
	s_nop 1
	v_cndmask_b32_e32 v2, v4, v3, vcc
	v_cmp_le_u32_e32 vcc, v121, v87
	s_nop 1
	v_cndmask_b32_e32 v220, 0, v2, vcc
	s_branch .Lidxp_w28
.Lidxp_e28:
	s_or_b64 exec, exec, s[82:83]
	v_max_f32_e32 v18, 0, v18
	v_max_f32_e32 v19, 0, v19
	v_fma_f32 v18, v174, v18, 0
	v_max_f32_e32 v20, 0, v20
	v_fmac_f32_e32 v18, v173, v19
	v_max_f32_e32 v21, 0, v21
	v_fmac_f32_e32 v18, v172, v20
	v_max_f32_e32 v22, 0, v22
	v_fmac_f32_e32 v18, v171, v21
	v_max_f32_e32 v23, 0, v23
	v_fmac_f32_e32 v18, v170, v22
	v_max_f32_e32 v24, 0, v24
	v_fmac_f32_e32 v18, v169, v23
	v_max_f32_e32 v25, 0, v25
	v_fmac_f32_e32 v18, v168, v24
	v_max_f32_e32 v26, 0, v26
	v_fmac_f32_e32 v18, v167, v25
	v_max_f32_e32 v27, 0, v27
	v_fmac_f32_e32 v18, v166, v26
	v_max_f32_e32 v28, 0, v28
	v_fmac_f32_e32 v18, v165, v27
	v_max_f32_e32 v29, 0, v29
	v_fmac_f32_e32 v18, v164, v28
	v_max_f32_e32 v30, 0, v30
	v_fmac_f32_e32 v18, v163, v29
	v_fmac_f32_e32 v18, v162, v30
	v_max_f32_e32 v19, 0, v31
	v_fmac_f32_e32 v18, v161, v19
	v_max_f32_e32 v19, 0, v32
	v_fmac_f32_e32 v18, v160, v19
	v_max_f32_e32 v19, 0, v33
	v_fmac_f32_e32 v18, v89, v19
	v_not_b32_e32 v19, v18
	v_or_b32_e32 v20, 0x80000000, v18
	v_cmp_gt_i32_e32 vcc, 0, v18
	s_nop 1
	v_cndmask_b32_e32 v18, v20, v19, vcc
	v_cmp_le_u32_e32 vcc, v122, v87
	s_nop 1
	v_cndmask_b32_e32 v221, 0, v18, vcc
	s_branch .Lidxp_w29
.Lidxp_e29:
	s_or_b64 exec, exec, s[82:83]
	v_max_f32_e32 v2, 0, v2
	v_max_f32_e32 v3, 0, v3
	v_fma_f32 v2, v174, v2, 0
	v_max_f32_e32 v4, 0, v4
	v_fmac_f32_e32 v2, v173, v3
	v_max_f32_e32 v5, 0, v5
	v_fmac_f32_e32 v2, v172, v4
	v_max_f32_e32 v6, 0, v6
	v_fmac_f32_e32 v2, v171, v5
	v_max_f32_e32 v7, 0, v7
	v_fmac_f32_e32 v2, v170, v6
	v_max_f32_e32 v8, 0, v8
	v_fmac_f32_e32 v2, v169, v7
	v_max_f32_e32 v9, 0, v9
	v_fmac_f32_e32 v2, v168, v8
	v_max_f32_e32 v10, 0, v10
	v_fmac_f32_e32 v2, v167, v9
	v_max_f32_e32 v11, 0, v11
	v_fmac_f32_e32 v2, v166, v10
	v_max_f32_e32 v12, 0, v12
	v_fmac_f32_e32 v2, v165, v11
	v_max_f32_e32 v13, 0, v13
	v_fmac_f32_e32 v2, v164, v12
	v_max_f32_e32 v14, 0, v14
	v_fmac_f32_e32 v2, v163, v13
	v_fmac_f32_e32 v2, v162, v14
	v_max_f32_e32 v3, 0, v15
	v_fmac_f32_e32 v2, v161, v3
	v_max_f32_e32 v3, 0, v16
	v_fmac_f32_e32 v2, v160, v3
	v_max_f32_e32 v3, 0, v17
	v_fmac_f32_e32 v2, v89, v3
	v_not_b32_e32 v3, v2
	v_or_b32_e32 v4, 0x80000000, v2
	v_cmp_gt_i32_e32 vcc, 0, v2
	s_nop 1
	v_cndmask_b32_e32 v2, v4, v3, vcc
	v_cmp_le_u32_e32 vcc, v123, v87
	s_nop 1
	v_cndmask_b32_e32 v222, 0, v2, vcc
	s_branch .Lidxp_w30
.Lidxp_e30:
	s_or_b64 exec, exec, s[82:83]
	v_max_f32_e32 v18, 0, v18
	v_max_f32_e32 v19, 0, v19
	v_fma_f32 v18, v174, v18, 0
	v_max_f32_e32 v20, 0, v20
	v_fmac_f32_e32 v18, v173, v19
	v_max_f32_e32 v21, 0, v21
	v_fmac_f32_e32 v18, v172, v20
	v_max_f32_e32 v22, 0, v22
	v_fmac_f32_e32 v18, v171, v21
	v_max_f32_e32 v23, 0, v23
	v_fmac_f32_e32 v18, v170, v22
	v_max_f32_e32 v24, 0, v24
	v_fmac_f32_e32 v18, v169, v23
	v_max_f32_e32 v25, 0, v25
	v_fmac_f32_e32 v18, v168, v24
	v_max_f32_e32 v26, 0, v26
	v_fmac_f32_e32 v18, v167, v25
	v_max_f32_e32 v27, 0, v27
	v_fmac_f32_e32 v18, v166, v26
	v_max_f32_e32 v28, 0, v28
	v_fmac_f32_e32 v18, v165, v27
	v_max_f32_e32 v29, 0, v29
	v_fmac_f32_e32 v18, v164, v28
	v_max_f32_e32 v30, 0, v30
	v_fmac_f32_e32 v18, v163, v29
	v_fmac_f32_e32 v18, v162, v30
	v_max_f32_e32 v19, 0, v31
	v_fmac_f32_e32 v18, v161, v19
	v_max_f32_e32 v19, 0, v32
	v_fmac_f32_e32 v18, v160, v19
	v_max_f32_e32 v19, 0, v33
	v_fmac_f32_e32 v18, v89, v19
	v_not_b32_e32 v19, v18
	v_or_b32_e32 v20, 0x80000000, v18
	v_cmp_gt_i32_e32 vcc, 0, v18
	s_nop 1
	v_cndmask_b32_e32 v18, v20, v19, vcc
	v_cmp_le_u32_e32 vcc, v124, v87
	s_nop 1
	v_cndmask_b32_e32 v223, 0, v18, vcc
	s_branch .Lidxp_w31
.Lidxp_e31:
	s_or_b64 exec, exec, s[82:83]
	v_max_f32_e32 v2, 0, v2
	v_max_f32_e32 v3, 0, v3
	v_fma_f32 v2, v174, v2, 0
	v_max_f32_e32 v4, 0, v4
	v_fmac_f32_e32 v2, v173, v3
	v_max_f32_e32 v5, 0, v5
	v_fmac_f32_e32 v2, v172, v4
	v_max_f32_e32 v6, 0, v6
	v_fmac_f32_e32 v2, v171, v5
	v_max_f32_e32 v7, 0, v7
	v_fmac_f32_e32 v2, v170, v6
	v_max_f32_e32 v8, 0, v8
	v_fmac_f32_e32 v2, v169, v7
	v_max_f32_e32 v9, 0, v9
	v_fmac_f32_e32 v2, v168, v8
	v_max_f32_e32 v10, 0, v10
	v_fmac_f32_e32 v2, v167, v9
	v_max_f32_e32 v11, 0, v11
	v_fmac_f32_e32 v2, v166, v10
	v_max_f32_e32 v12, 0, v12
	v_fmac_f32_e32 v2, v165, v11
	v_max_f32_e32 v13, 0, v13
	v_fmac_f32_e32 v2, v164, v12
	v_max_f32_e32 v14, 0, v14
	v_fmac_f32_e32 v2, v163, v13
	v_fmac_f32_e32 v2, v162, v14
	v_max_f32_e32 v3, 0, v15
	v_fmac_f32_e32 v2, v161, v3
	v_max_f32_e32 v3, 0, v16
	v_fmac_f32_e32 v2, v160, v3
	v_max_f32_e32 v3, 0, v17
	v_fmac_f32_e32 v2, v89, v3
	v_not_b32_e32 v3, v2
	v_or_b32_e32 v4, 0x80000000, v2
	v_cmp_gt_i32_e32 vcc, 0, v2
	s_nop 1
	v_cndmask_b32_e32 v2, v4, v3, vcc
	v_cmp_le_u32_e32 vcc, v125, v87
	s_nop 1
	v_cndmask_b32_e32 v224, 0, v2, vcc
	s_branch .Lidxp_w32
.Lidxp_e32:
	s_or_b64 exec, exec, s[82:83]
	v_max_f32_e32 v18, 0, v18
	v_max_f32_e32 v19, 0, v19
	v_fma_f32 v18, v174, v18, 0
	v_max_f32_e32 v20, 0, v20
	v_fmac_f32_e32 v18, v173, v19
	v_max_f32_e32 v21, 0, v21
	v_fmac_f32_e32 v18, v172, v20
	v_max_f32_e32 v22, 0, v22
	v_fmac_f32_e32 v18, v171, v21
	v_max_f32_e32 v23, 0, v23
	v_fmac_f32_e32 v18, v170, v22
	v_max_f32_e32 v24, 0, v24
	v_fmac_f32_e32 v18, v169, v23
	v_max_f32_e32 v25, 0, v25
	v_fmac_f32_e32 v18, v168, v24
	v_max_f32_e32 v26, 0, v26
	v_fmac_f32_e32 v18, v167, v25
	v_max_f32_e32 v27, 0, v27
	v_fmac_f32_e32 v18, v166, v26
	v_max_f32_e32 v28, 0, v28
	v_fmac_f32_e32 v18, v165, v27
	v_max_f32_e32 v29, 0, v29
	v_fmac_f32_e32 v18, v164, v28
	v_max_f32_e32 v30, 0, v30
	v_fmac_f32_e32 v18, v163, v29
	v_fmac_f32_e32 v18, v162, v30
	v_max_f32_e32 v19, 0, v31
	v_fmac_f32_e32 v18, v161, v19
	v_max_f32_e32 v19, 0, v32
	v_fmac_f32_e32 v18, v160, v19
	v_max_f32_e32 v19, 0, v33
	v_fmac_f32_e32 v18, v89, v19
	v_not_b32_e32 v19, v18
	v_or_b32_e32 v20, 0x80000000, v18
	v_cmp_gt_i32_e32 vcc, 0, v18
	s_nop 1
	v_cndmask_b32_e32 v18, v20, v19, vcc
	v_cmp_le_u32_e32 vcc, v126, v87
	s_nop 1
	v_cndmask_b32_e32 v225, 0, v18, vcc
	s_branch .Lidxp_w33
.Lidxp_e33:
	s_or_b64 exec, exec, s[82:83]
	v_max_f32_e32 v2, 0, v2
	v_max_f32_e32 v3, 0, v3
	v_fma_f32 v2, v174, v2, 0
	v_max_f32_e32 v4, 0, v4
	v_fmac_f32_e32 v2, v173, v3
	v_max_f32_e32 v5, 0, v5
	v_fmac_f32_e32 v2, v172, v4
	v_max_f32_e32 v6, 0, v6
	v_fmac_f32_e32 v2, v171, v5
	v_max_f32_e32 v7, 0, v7
	v_fmac_f32_e32 v2, v170, v6
	v_max_f32_e32 v8, 0, v8
	v_fmac_f32_e32 v2, v169, v7
	v_max_f32_e32 v9, 0, v9
	v_fmac_f32_e32 v2, v168, v8
	v_max_f32_e32 v10, 0, v10
	v_fmac_f32_e32 v2, v167, v9
	v_max_f32_e32 v11, 0, v11
	v_fmac_f32_e32 v2, v166, v10
	v_max_f32_e32 v12, 0, v12
	v_fmac_f32_e32 v2, v165, v11
	v_max_f32_e32 v13, 0, v13
	v_fmac_f32_e32 v2, v164, v12
	v_max_f32_e32 v14, 0, v14
	v_fmac_f32_e32 v2, v163, v13
	v_fmac_f32_e32 v2, v162, v14
	v_max_f32_e32 v3, 0, v15
	v_fmac_f32_e32 v2, v161, v3
	v_max_f32_e32 v3, 0, v16
	v_fmac_f32_e32 v2, v160, v3
	v_max_f32_e32 v3, 0, v17
	v_fmac_f32_e32 v2, v89, v3
	v_not_b32_e32 v3, v2
	v_or_b32_e32 v4, 0x80000000, v2
	v_cmp_gt_i32_e32 vcc, 0, v2
	s_nop 1
	v_cndmask_b32_e32 v2, v4, v3, vcc
	v_cmp_le_u32_e32 vcc, v127, v87
	s_nop 1
	v_cndmask_b32_e32 v226, 0, v2, vcc
	s_branch .Lidxp_w34
.Lidxp_e34:
	s_or_b64 exec, exec, s[82:83]
	v_max_f32_e32 v18, 0, v18
	v_max_f32_e32 v19, 0, v19
	v_fma_f32 v18, v174, v18, 0
	v_max_f32_e32 v20, 0, v20
	v_fmac_f32_e32 v18, v173, v19
	v_max_f32_e32 v21, 0, v21
	v_fmac_f32_e32 v18, v172, v20
	v_max_f32_e32 v22, 0, v22
	v_fmac_f32_e32 v18, v171, v21
	v_max_f32_e32 v23, 0, v23
	v_fmac_f32_e32 v18, v170, v22
	v_max_f32_e32 v24, 0, v24
	v_fmac_f32_e32 v18, v169, v23
	v_max_f32_e32 v25, 0, v25
	v_fmac_f32_e32 v18, v168, v24
	v_max_f32_e32 v26, 0, v26
	v_fmac_f32_e32 v18, v167, v25
	v_max_f32_e32 v27, 0, v27
	v_fmac_f32_e32 v18, v166, v26
	v_max_f32_e32 v28, 0, v28
	v_fmac_f32_e32 v18, v165, v27
	v_max_f32_e32 v29, 0, v29
	v_fmac_f32_e32 v18, v164, v28
	v_max_f32_e32 v30, 0, v30
	v_fmac_f32_e32 v18, v163, v29
	v_fmac_f32_e32 v18, v162, v30
	v_max_f32_e32 v19, 0, v31
	v_fmac_f32_e32 v18, v161, v19
	v_max_f32_e32 v19, 0, v32
	v_fmac_f32_e32 v18, v160, v19
	v_max_f32_e32 v19, 0, v33
	v_fmac_f32_e32 v18, v89, v19
	v_not_b32_e32 v19, v18
	v_or_b32_e32 v20, 0x80000000, v18
	v_cmp_gt_i32_e32 vcc, 0, v18
	s_nop 1
	v_cndmask_b32_e32 v18, v20, v19, vcc
	v_cmp_le_u32_e32 vcc, v128, v87
	s_nop 1
	v_cndmask_b32_e32 v227, 0, v18, vcc
	s_branch .Lidxp_w35
.Lidxp_e35:
	s_or_b64 exec, exec, s[82:83]
	v_max_f32_e32 v2, 0, v2
	v_max_f32_e32 v3, 0, v3
	v_fma_f32 v2, v174, v2, 0
	v_max_f32_e32 v4, 0, v4
	v_fmac_f32_e32 v2, v173, v3
	v_max_f32_e32 v5, 0, v5
	v_fmac_f32_e32 v2, v172, v4
	v_max_f32_e32 v6, 0, v6
	v_fmac_f32_e32 v2, v171, v5
	v_max_f32_e32 v7, 0, v7
	v_fmac_f32_e32 v2, v170, v6
	v_max_f32_e32 v8, 0, v8
	v_fmac_f32_e32 v2, v169, v7
	v_max_f32_e32 v9, 0, v9
	v_fmac_f32_e32 v2, v168, v8
	v_max_f32_e32 v10, 0, v10
	v_fmac_f32_e32 v2, v167, v9
	v_max_f32_e32 v11, 0, v11
	v_fmac_f32_e32 v2, v166, v10
	v_max_f32_e32 v12, 0, v12
	v_fmac_f32_e32 v2, v165, v11
	v_max_f32_e32 v13, 0, v13
	v_fmac_f32_e32 v2, v164, v12
	v_max_f32_e32 v14, 0, v14
	v_fmac_f32_e32 v2, v163, v13
	v_fmac_f32_e32 v2, v162, v14
	v_max_f32_e32 v3, 0, v15
	v_fmac_f32_e32 v2, v161, v3
	v_max_f32_e32 v3, 0, v16
	v_fmac_f32_e32 v2, v160, v3
	v_max_f32_e32 v3, 0, v17
	v_fmac_f32_e32 v2, v89, v3
	v_not_b32_e32 v3, v2
	v_or_b32_e32 v4, 0x80000000, v2
	v_cmp_gt_i32_e32 vcc, 0, v2
	s_nop 1
	v_cndmask_b32_e32 v2, v4, v3, vcc
	v_cmp_le_u32_e32 vcc, v129, v87
	s_nop 1
	v_cndmask_b32_e32 v228, 0, v2, vcc
	s_branch .Lidxp_w36
.Lidxp_e36:
	s_or_b64 exec, exec, s[82:83]
	v_max_f32_e32 v18, 0, v18
	v_max_f32_e32 v19, 0, v19
	v_fma_f32 v18, v174, v18, 0
	v_max_f32_e32 v20, 0, v20
	v_fmac_f32_e32 v18, v173, v19
	v_max_f32_e32 v21, 0, v21
	v_fmac_f32_e32 v18, v172, v20
	v_max_f32_e32 v22, 0, v22
	v_fmac_f32_e32 v18, v171, v21
	v_max_f32_e32 v23, 0, v23
	v_fmac_f32_e32 v18, v170, v22
	v_max_f32_e32 v24, 0, v24
	v_fmac_f32_e32 v18, v169, v23
	v_max_f32_e32 v25, 0, v25
	v_fmac_f32_e32 v18, v168, v24
	v_max_f32_e32 v26, 0, v26
	v_fmac_f32_e32 v18, v167, v25
	v_max_f32_e32 v27, 0, v27
	v_fmac_f32_e32 v18, v166, v26
	v_max_f32_e32 v28, 0, v28
	v_fmac_f32_e32 v18, v165, v27
	v_max_f32_e32 v29, 0, v29
	v_fmac_f32_e32 v18, v164, v28
	v_max_f32_e32 v30, 0, v30
	v_fmac_f32_e32 v18, v163, v29
	v_fmac_f32_e32 v18, v162, v30
	v_max_f32_e32 v19, 0, v31
	v_fmac_f32_e32 v18, v161, v19
	v_max_f32_e32 v19, 0, v32
	v_fmac_f32_e32 v18, v160, v19
	v_max_f32_e32 v19, 0, v33
	v_fmac_f32_e32 v18, v89, v19
	v_not_b32_e32 v19, v18
	v_or_b32_e32 v20, 0x80000000, v18
	v_cmp_gt_i32_e32 vcc, 0, v18
	s_nop 1
	v_cndmask_b32_e32 v18, v20, v19, vcc
	v_cmp_le_u32_e32 vcc, v130, v87
	s_nop 1
	v_cndmask_b32_e32 v229, 0, v18, vcc
	s_branch .Lidxp_w37
.Lidxp_e37:
	s_or_b64 exec, exec, s[82:83]
	v_max_f32_e32 v2, 0, v2
	v_max_f32_e32 v3, 0, v3
	v_fma_f32 v2, v174, v2, 0
	v_max_f32_e32 v4, 0, v4
	v_fmac_f32_e32 v2, v173, v3
	v_max_f32_e32 v5, 0, v5
	v_fmac_f32_e32 v2, v172, v4
	v_max_f32_e32 v6, 0, v6
	v_fmac_f32_e32 v2, v171, v5
	v_max_f32_e32 v7, 0, v7
	v_fmac_f32_e32 v2, v170, v6
	v_max_f32_e32 v8, 0, v8
	v_fmac_f32_e32 v2, v169, v7
	v_max_f32_e32 v9, 0, v9
	v_fmac_f32_e32 v2, v168, v8
	v_max_f32_e32 v10, 0, v10
	v_fmac_f32_e32 v2, v167, v9
	v_max_f32_e32 v11, 0, v11
	v_fmac_f32_e32 v2, v166, v10
	v_max_f32_e32 v12, 0, v12
	v_fmac_f32_e32 v2, v165, v11
	v_max_f32_e32 v13, 0, v13
	v_fmac_f32_e32 v2, v164, v12
	v_max_f32_e32 v14, 0, v14
	v_fmac_f32_e32 v2, v163, v13
	v_fmac_f32_e32 v2, v162, v14
	v_max_f32_e32 v3, 0, v15
	v_fmac_f32_e32 v2, v161, v3
	v_max_f32_e32 v3, 0, v16
	v_fmac_f32_e32 v2, v160, v3
	v_max_f32_e32 v3, 0, v17
	v_fmac_f32_e32 v2, v89, v3
	v_not_b32_e32 v3, v2
	v_or_b32_e32 v4, 0x80000000, v2
	v_cmp_gt_i32_e32 vcc, 0, v2
	s_nop 1
	v_cndmask_b32_e32 v2, v4, v3, vcc
	v_cmp_le_u32_e32 vcc, v131, v87
	s_nop 1
	v_cndmask_b32_e32 v230, 0, v2, vcc
	s_branch .Lidxp_w38
.Lidxp_e38:
	s_or_b64 exec, exec, s[82:83]
	v_max_f32_e32 v18, 0, v18
	v_max_f32_e32 v19, 0, v19
	v_fma_f32 v18, v174, v18, 0
	v_max_f32_e32 v20, 0, v20
	v_fmac_f32_e32 v18, v173, v19
	v_max_f32_e32 v21, 0, v21
	v_fmac_f32_e32 v18, v172, v20
	v_max_f32_e32 v22, 0, v22
	v_fmac_f32_e32 v18, v171, v21
	v_max_f32_e32 v23, 0, v23
	v_fmac_f32_e32 v18, v170, v22
	v_max_f32_e32 v24, 0, v24
	v_fmac_f32_e32 v18, v169, v23
	v_max_f32_e32 v25, 0, v25
	v_fmac_f32_e32 v18, v168, v24
	v_max_f32_e32 v26, 0, v26
	v_fmac_f32_e32 v18, v167, v25
	v_max_f32_e32 v27, 0, v27
	v_fmac_f32_e32 v18, v166, v26
	v_max_f32_e32 v28, 0, v28
	v_fmac_f32_e32 v18, v165, v27
	v_max_f32_e32 v29, 0, v29
	v_fmac_f32_e32 v18, v164, v28
	v_max_f32_e32 v30, 0, v30
	v_fmac_f32_e32 v18, v163, v29
	v_fmac_f32_e32 v18, v162, v30
	v_max_f32_e32 v19, 0, v31
	v_fmac_f32_e32 v18, v161, v19
	v_max_f32_e32 v19, 0, v32
	v_fmac_f32_e32 v18, v160, v19
	v_max_f32_e32 v19, 0, v33
	v_fmac_f32_e32 v18, v89, v19
	v_not_b32_e32 v19, v18
	v_or_b32_e32 v20, 0x80000000, v18
	v_cmp_gt_i32_e32 vcc, 0, v18
	s_nop 1
	v_cndmask_b32_e32 v18, v20, v19, vcc
	v_cmp_le_u32_e32 vcc, v132, v87
	s_nop 1
	v_cndmask_b32_e32 v231, 0, v18, vcc
	s_branch .Lidxp_w39
.Lidxp_e39:
	s_or_b64 exec, exec, s[82:83]
	v_max_f32_e32 v2, 0, v2
	v_max_f32_e32 v3, 0, v3
	v_fma_f32 v2, v174, v2, 0
	v_max_f32_e32 v4, 0, v4
	v_fmac_f32_e32 v2, v173, v3
	v_max_f32_e32 v5, 0, v5
	v_fmac_f32_e32 v2, v172, v4
	v_max_f32_e32 v6, 0, v6
	v_fmac_f32_e32 v2, v171, v5
	v_max_f32_e32 v7, 0, v7
	v_fmac_f32_e32 v2, v170, v6
	v_max_f32_e32 v8, 0, v8
	v_fmac_f32_e32 v2, v169, v7
	v_max_f32_e32 v9, 0, v9
	v_fmac_f32_e32 v2, v168, v8
	v_max_f32_e32 v10, 0, v10
	v_fmac_f32_e32 v2, v167, v9
	v_max_f32_e32 v11, 0, v11
	v_fmac_f32_e32 v2, v166, v10
	v_max_f32_e32 v12, 0, v12
	v_fmac_f32_e32 v2, v165, v11
	v_max_f32_e32 v13, 0, v13
	v_fmac_f32_e32 v2, v164, v12
	v_max_f32_e32 v14, 0, v14
	v_fmac_f32_e32 v2, v163, v13
	v_fmac_f32_e32 v2, v162, v14
	v_max_f32_e32 v3, 0, v15
	v_fmac_f32_e32 v2, v161, v3
	v_max_f32_e32 v3, 0, v16
	v_fmac_f32_e32 v2, v160, v3
	v_max_f32_e32 v3, 0, v17
	v_fmac_f32_e32 v2, v89, v3
	v_not_b32_e32 v3, v2
	v_or_b32_e32 v4, 0x80000000, v2
	v_cmp_gt_i32_e32 vcc, 0, v2
	s_nop 1
	v_cndmask_b32_e32 v2, v4, v3, vcc
	v_cmp_le_u32_e32 vcc, v133, v87
	s_nop 1
	v_cndmask_b32_e32 v232, 0, v2, vcc
	s_branch .Lidxp_w40
.Lidxp_e40:
	s_or_b64 exec, exec, s[82:83]
	v_max_f32_e32 v18, 0, v18
	v_max_f32_e32 v19, 0, v19
	v_fma_f32 v18, v174, v18, 0
	v_max_f32_e32 v20, 0, v20
	v_fmac_f32_e32 v18, v173, v19
	v_max_f32_e32 v21, 0, v21
	v_fmac_f32_e32 v18, v172, v20
	v_max_f32_e32 v22, 0, v22
	v_fmac_f32_e32 v18, v171, v21
	v_max_f32_e32 v23, 0, v23
	v_fmac_f32_e32 v18, v170, v22
	v_max_f32_e32 v24, 0, v24
	v_fmac_f32_e32 v18, v169, v23
	v_max_f32_e32 v25, 0, v25
	v_fmac_f32_e32 v18, v168, v24
	v_max_f32_e32 v26, 0, v26
	v_fmac_f32_e32 v18, v167, v25
	v_max_f32_e32 v27, 0, v27
	v_fmac_f32_e32 v18, v166, v26
	v_max_f32_e32 v28, 0, v28
	v_fmac_f32_e32 v18, v165, v27
	v_max_f32_e32 v29, 0, v29
	v_fmac_f32_e32 v18, v164, v28
	v_max_f32_e32 v30, 0, v30
	v_fmac_f32_e32 v18, v163, v29
	v_fmac_f32_e32 v18, v162, v30
	v_max_f32_e32 v19, 0, v31
	v_fmac_f32_e32 v18, v161, v19
	v_max_f32_e32 v19, 0, v32
	v_fmac_f32_e32 v18, v160, v19
	v_max_f32_e32 v19, 0, v33
	v_fmac_f32_e32 v18, v89, v19
	v_not_b32_e32 v19, v18
	v_or_b32_e32 v20, 0x80000000, v18
	v_cmp_gt_i32_e32 vcc, 0, v18
	s_nop 1
	v_cndmask_b32_e32 v18, v20, v19, vcc
	v_cmp_le_u32_e32 vcc, v134, v87
	s_nop 1
	v_cndmask_b32_e32 v233, 0, v18, vcc
	s_branch .Lidxp_w41
.Lidxp_e41:
	s_or_b64 exec, exec, s[82:83]
	v_max_f32_e32 v2, 0, v2
	v_max_f32_e32 v3, 0, v3
	v_fma_f32 v2, v174, v2, 0
	v_max_f32_e32 v4, 0, v4
	v_fmac_f32_e32 v2, v173, v3
	v_max_f32_e32 v5, 0, v5
	v_fmac_f32_e32 v2, v172, v4
	v_max_f32_e32 v6, 0, v6
	v_fmac_f32_e32 v2, v171, v5
	v_max_f32_e32 v7, 0, v7
	v_fmac_f32_e32 v2, v170, v6
	v_max_f32_e32 v8, 0, v8
	v_fmac_f32_e32 v2, v169, v7
	v_max_f32_e32 v9, 0, v9
	v_fmac_f32_e32 v2, v168, v8
	v_max_f32_e32 v10, 0, v10
	v_fmac_f32_e32 v2, v167, v9
	v_max_f32_e32 v11, 0, v11
	v_fmac_f32_e32 v2, v166, v10
	v_max_f32_e32 v12, 0, v12
	v_fmac_f32_e32 v2, v165, v11
	v_max_f32_e32 v13, 0, v13
	v_fmac_f32_e32 v2, v164, v12
	v_max_f32_e32 v14, 0, v14
	v_fmac_f32_e32 v2, v163, v13
	v_fmac_f32_e32 v2, v162, v14
	v_max_f32_e32 v3, 0, v15
	v_fmac_f32_e32 v2, v161, v3
	v_max_f32_e32 v3, 0, v16
	v_fmac_f32_e32 v2, v160, v3
	v_max_f32_e32 v3, 0, v17
	v_fmac_f32_e32 v2, v89, v3
	v_not_b32_e32 v3, v2
	v_or_b32_e32 v4, 0x80000000, v2
	v_cmp_gt_i32_e32 vcc, 0, v2
	s_nop 1
	v_cndmask_b32_e32 v2, v4, v3, vcc
	v_cmp_le_u32_e32 vcc, v135, v87
	s_nop 1
	v_cndmask_b32_e32 v234, 0, v2, vcc
	s_branch .Lidxp_w42
.Lidxp_e42:
	s_or_b64 exec, exec, s[82:83]
	v_max_f32_e32 v18, 0, v18
	v_max_f32_e32 v19, 0, v19
	v_fma_f32 v18, v174, v18, 0
	v_max_f32_e32 v20, 0, v20
	v_fmac_f32_e32 v18, v173, v19
	v_max_f32_e32 v21, 0, v21
	v_fmac_f32_e32 v18, v172, v20
	v_max_f32_e32 v22, 0, v22
	v_fmac_f32_e32 v18, v171, v21
	v_max_f32_e32 v23, 0, v23
	v_fmac_f32_e32 v18, v170, v22
	v_max_f32_e32 v24, 0, v24
	v_fmac_f32_e32 v18, v169, v23
	v_max_f32_e32 v25, 0, v25
	v_fmac_f32_e32 v18, v168, v24
	v_max_f32_e32 v26, 0, v26
	v_fmac_f32_e32 v18, v167, v25
	v_max_f32_e32 v27, 0, v27
	v_fmac_f32_e32 v18, v166, v26
	v_max_f32_e32 v28, 0, v28
	v_fmac_f32_e32 v18, v165, v27
	v_max_f32_e32 v29, 0, v29
	v_fmac_f32_e32 v18, v164, v28
	v_max_f32_e32 v30, 0, v30
	v_fmac_f32_e32 v18, v163, v29
	v_fmac_f32_e32 v18, v162, v30
	v_max_f32_e32 v19, 0, v31
	v_fmac_f32_e32 v18, v161, v19
	v_max_f32_e32 v19, 0, v32
	v_fmac_f32_e32 v18, v160, v19
	v_max_f32_e32 v19, 0, v33
	v_fmac_f32_e32 v18, v89, v19
	v_not_b32_e32 v19, v18
	v_or_b32_e32 v20, 0x80000000, v18
	v_cmp_gt_i32_e32 vcc, 0, v18
	s_nop 1
	v_cndmask_b32_e32 v18, v20, v19, vcc
	v_cmp_le_u32_e32 vcc, v136, v87
	s_nop 1
	v_cndmask_b32_e32 v235, 0, v18, vcc
	s_branch .Lidxp_w43
.Lidxp_e43:
	s_or_b64 exec, exec, s[82:83]
	v_max_f32_e32 v2, 0, v2
	v_max_f32_e32 v3, 0, v3
	v_fma_f32 v2, v174, v2, 0
	v_max_f32_e32 v4, 0, v4
	v_fmac_f32_e32 v2, v173, v3
	v_max_f32_e32 v5, 0, v5
	v_fmac_f32_e32 v2, v172, v4
	v_max_f32_e32 v6, 0, v6
	v_fmac_f32_e32 v2, v171, v5
	v_max_f32_e32 v7, 0, v7
	v_fmac_f32_e32 v2, v170, v6
	v_max_f32_e32 v8, 0, v8
	v_fmac_f32_e32 v2, v169, v7
	v_max_f32_e32 v9, 0, v9
	v_fmac_f32_e32 v2, v168, v8
	v_max_f32_e32 v10, 0, v10
	v_fmac_f32_e32 v2, v167, v9
	v_max_f32_e32 v11, 0, v11
	v_fmac_f32_e32 v2, v166, v10
	v_max_f32_e32 v12, 0, v12
	v_fmac_f32_e32 v2, v165, v11
	v_max_f32_e32 v13, 0, v13
	v_fmac_f32_e32 v2, v164, v12
	v_max_f32_e32 v14, 0, v14
	v_fmac_f32_e32 v2, v163, v13
	v_fmac_f32_e32 v2, v162, v14
	v_max_f32_e32 v3, 0, v15
	v_fmac_f32_e32 v2, v161, v3
	v_max_f32_e32 v3, 0, v16
	v_fmac_f32_e32 v2, v160, v3
	v_max_f32_e32 v3, 0, v17
	v_fmac_f32_e32 v2, v89, v3
	v_not_b32_e32 v3, v2
	v_or_b32_e32 v4, 0x80000000, v2
	v_cmp_gt_i32_e32 vcc, 0, v2
	s_nop 1
	v_cndmask_b32_e32 v2, v4, v3, vcc
	v_cmp_le_u32_e32 vcc, v137, v87
	s_nop 1
	v_cndmask_b32_e32 v236, 0, v2, vcc
	s_branch .Lidxp_w44
.Lidxp_e44:
	s_or_b64 exec, exec, s[82:83]
	v_max_f32_e32 v18, 0, v18
	v_max_f32_e32 v19, 0, v19
	v_fma_f32 v18, v174, v18, 0
	v_max_f32_e32 v20, 0, v20
	v_fmac_f32_e32 v18, v173, v19
	v_max_f32_e32 v21, 0, v21
	v_fmac_f32_e32 v18, v172, v20
	v_max_f32_e32 v22, 0, v22
	v_fmac_f32_e32 v18, v171, v21
	v_max_f32_e32 v23, 0, v23
	v_fmac_f32_e32 v18, v170, v22
	v_max_f32_e32 v24, 0, v24
	v_fmac_f32_e32 v18, v169, v23
	v_max_f32_e32 v25, 0, v25
	v_fmac_f32_e32 v18, v168, v24
	v_max_f32_e32 v26, 0, v26
	v_fmac_f32_e32 v18, v167, v25
	v_max_f32_e32 v27, 0, v27
	v_fmac_f32_e32 v18, v166, v26
	v_max_f32_e32 v28, 0, v28
	v_fmac_f32_e32 v18, v165, v27
	v_max_f32_e32 v29, 0, v29
	v_fmac_f32_e32 v18, v164, v28
	v_max_f32_e32 v30, 0, v30
	v_fmac_f32_e32 v18, v163, v29
	v_fmac_f32_e32 v18, v162, v30
	v_max_f32_e32 v19, 0, v31
	v_fmac_f32_e32 v18, v161, v19
	v_max_f32_e32 v19, 0, v32
	v_fmac_f32_e32 v18, v160, v19
	v_max_f32_e32 v19, 0, v33
	v_fmac_f32_e32 v18, v89, v19
	v_not_b32_e32 v19, v18
	v_or_b32_e32 v20, 0x80000000, v18
	v_cmp_gt_i32_e32 vcc, 0, v18
	s_nop 1
	v_cndmask_b32_e32 v18, v20, v19, vcc
	v_cmp_le_u32_e32 vcc, v138, v87
	s_nop 1
	v_cndmask_b32_e32 v237, 0, v18, vcc
	s_branch .Lidxp_w45
.Lidxp_e45:
	s_or_b64 exec, exec, s[82:83]
	v_max_f32_e32 v2, 0, v2
	v_max_f32_e32 v3, 0, v3
	v_fma_f32 v2, v174, v2, 0
	v_max_f32_e32 v4, 0, v4
	v_fmac_f32_e32 v2, v173, v3
	v_max_f32_e32 v5, 0, v5
	v_fmac_f32_e32 v2, v172, v4
	v_max_f32_e32 v6, 0, v6
	v_fmac_f32_e32 v2, v171, v5
	v_max_f32_e32 v7, 0, v7
	v_fmac_f32_e32 v2, v170, v6
	v_max_f32_e32 v8, 0, v8
	v_fmac_f32_e32 v2, v169, v7
	v_max_f32_e32 v9, 0, v9
	v_fmac_f32_e32 v2, v168, v8
	v_max_f32_e32 v10, 0, v10
	v_fmac_f32_e32 v2, v167, v9
	v_max_f32_e32 v11, 0, v11
	v_fmac_f32_e32 v2, v166, v10
	v_max_f32_e32 v12, 0, v12
	v_fmac_f32_e32 v2, v165, v11
	v_max_f32_e32 v13, 0, v13
	v_fmac_f32_e32 v2, v164, v12
	v_max_f32_e32 v14, 0, v14
	v_fmac_f32_e32 v2, v163, v13
	v_fmac_f32_e32 v2, v162, v14
	v_max_f32_e32 v3, 0, v15
	v_fmac_f32_e32 v2, v161, v3
	v_max_f32_e32 v3, 0, v16
	v_fmac_f32_e32 v2, v160, v3
	v_max_f32_e32 v3, 0, v17
	v_fmac_f32_e32 v2, v89, v3
	v_not_b32_e32 v3, v2
	v_or_b32_e32 v4, 0x80000000, v2
	v_cmp_gt_i32_e32 vcc, 0, v2
	s_nop 1
	v_cndmask_b32_e32 v2, v4, v3, vcc
	v_cmp_le_u32_e32 vcc, v139, v87
	s_nop 1
	v_cndmask_b32_e32 v238, 0, v2, vcc
	s_branch .Lidxp_w46
.Lidxp_e46:
	s_or_b64 exec, exec, s[82:83]
	v_max_f32_e32 v18, 0, v18
	v_max_f32_e32 v19, 0, v19
	v_fma_f32 v18, v174, v18, 0
	v_max_f32_e32 v20, 0, v20
	v_fmac_f32_e32 v18, v173, v19
	v_max_f32_e32 v21, 0, v21
	v_fmac_f32_e32 v18, v172, v20
	v_max_f32_e32 v22, 0, v22
	v_fmac_f32_e32 v18, v171, v21
	v_max_f32_e32 v23, 0, v23
	v_fmac_f32_e32 v18, v170, v22
	v_max_f32_e32 v24, 0, v24
	v_fmac_f32_e32 v18, v169, v23
	v_max_f32_e32 v25, 0, v25
	v_fmac_f32_e32 v18, v168, v24
	v_max_f32_e32 v26, 0, v26
	v_fmac_f32_e32 v18, v167, v25
	v_max_f32_e32 v27, 0, v27
	v_fmac_f32_e32 v18, v166, v26
	v_max_f32_e32 v28, 0, v28
	v_fmac_f32_e32 v18, v165, v27
	v_max_f32_e32 v29, 0, v29
	v_fmac_f32_e32 v18, v164, v28
	v_max_f32_e32 v30, 0, v30
	v_fmac_f32_e32 v18, v163, v29
	v_fmac_f32_e32 v18, v162, v30
	v_max_f32_e32 v19, 0, v31
	v_fmac_f32_e32 v18, v161, v19
	v_max_f32_e32 v19, 0, v32
	v_fmac_f32_e32 v18, v160, v19
	v_max_f32_e32 v19, 0, v33
	v_fmac_f32_e32 v18, v89, v19
	v_not_b32_e32 v19, v18
	v_or_b32_e32 v20, 0x80000000, v18
	v_cmp_gt_i32_e32 vcc, 0, v18
	s_nop 1
	v_cndmask_b32_e32 v18, v20, v19, vcc
	v_cmp_le_u32_e32 vcc, v140, v87
	s_nop 1
	v_cndmask_b32_e32 v239, 0, v18, vcc
	s_branch .Lidxp_w47
.Lidxp_e47:
	s_or_b64 exec, exec, s[82:83]
	v_max_f32_e32 v2, 0, v2
	v_max_f32_e32 v3, 0, v3
	v_fma_f32 v2, v174, v2, 0
	v_max_f32_e32 v4, 0, v4
	v_fmac_f32_e32 v2, v173, v3
	v_max_f32_e32 v5, 0, v5
	v_fmac_f32_e32 v2, v172, v4
	v_max_f32_e32 v6, 0, v6
	v_fmac_f32_e32 v2, v171, v5
	v_max_f32_e32 v7, 0, v7
	v_fmac_f32_e32 v2, v170, v6
	v_max_f32_e32 v8, 0, v8
	v_fmac_f32_e32 v2, v169, v7
	v_max_f32_e32 v9, 0, v9
	v_fmac_f32_e32 v2, v168, v8
	v_max_f32_e32 v10, 0, v10
	v_fmac_f32_e32 v2, v167, v9
	v_max_f32_e32 v11, 0, v11
	v_fmac_f32_e32 v2, v166, v10
	v_max_f32_e32 v12, 0, v12
	v_fmac_f32_e32 v2, v165, v11
	v_max_f32_e32 v13, 0, v13
	v_fmac_f32_e32 v2, v164, v12
	v_max_f32_e32 v14, 0, v14
	v_fmac_f32_e32 v2, v163, v13
	v_fmac_f32_e32 v2, v162, v14
	v_max_f32_e32 v3, 0, v15
	v_fmac_f32_e32 v2, v161, v3
	v_max_f32_e32 v3, 0, v16
	v_fmac_f32_e32 v2, v160, v3
	v_max_f32_e32 v3, 0, v17
	v_fmac_f32_e32 v2, v89, v3
	v_not_b32_e32 v3, v2
	v_or_b32_e32 v4, 0x80000000, v2
	v_cmp_gt_i32_e32 vcc, 0, v2
	s_nop 1
	v_cndmask_b32_e32 v2, v4, v3, vcc
	v_cmp_le_u32_e32 vcc, v141, v87
	s_nop 1
	v_cndmask_b32_e32 v240, 0, v2, vcc
	s_branch .Lidxp_w48
.Lidxp_e48:
	s_or_b64 exec, exec, s[82:83]
	v_max_f32_e32 v18, 0, v18
	v_max_f32_e32 v19, 0, v19
	v_fma_f32 v18, v174, v18, 0
	v_max_f32_e32 v20, 0, v20
	v_fmac_f32_e32 v18, v173, v19
	v_max_f32_e32 v21, 0, v21
	v_fmac_f32_e32 v18, v172, v20
	v_max_f32_e32 v22, 0, v22
	v_fmac_f32_e32 v18, v171, v21
	v_max_f32_e32 v23, 0, v23
	v_fmac_f32_e32 v18, v170, v22
	v_max_f32_e32 v24, 0, v24
	v_fmac_f32_e32 v18, v169, v23
	v_max_f32_e32 v25, 0, v25
	v_fmac_f32_e32 v18, v168, v24
	v_max_f32_e32 v26, 0, v26
	v_fmac_f32_e32 v18, v167, v25
	v_max_f32_e32 v27, 0, v27
	v_fmac_f32_e32 v18, v166, v26
	v_max_f32_e32 v28, 0, v28
	v_fmac_f32_e32 v18, v165, v27
	v_max_f32_e32 v29, 0, v29
	v_fmac_f32_e32 v18, v164, v28
	v_max_f32_e32 v30, 0, v30
	v_fmac_f32_e32 v18, v163, v29
	v_fmac_f32_e32 v18, v162, v30
	v_max_f32_e32 v19, 0, v31
	v_fmac_f32_e32 v18, v161, v19
	v_max_f32_e32 v19, 0, v32
	v_fmac_f32_e32 v18, v160, v19
	v_max_f32_e32 v19, 0, v33
	v_fmac_f32_e32 v18, v89, v19
	v_not_b32_e32 v19, v18
	v_or_b32_e32 v20, 0x80000000, v18
	v_cmp_gt_i32_e32 vcc, 0, v18
	s_nop 1
	v_cndmask_b32_e32 v18, v20, v19, vcc
	v_cmp_le_u32_e32 vcc, v142, v87
	s_nop 1
	v_cndmask_b32_e32 v241, 0, v18, vcc
	s_branch .Lidxp_w49
.Lidxp_e49:
	s_or_b64 exec, exec, s[82:83]
	v_max_f32_e32 v2, 0, v2
	v_max_f32_e32 v3, 0, v3
	v_fma_f32 v2, v174, v2, 0
	v_max_f32_e32 v4, 0, v4
	v_fmac_f32_e32 v2, v173, v3
	v_max_f32_e32 v5, 0, v5
	v_fmac_f32_e32 v2, v172, v4
	v_max_f32_e32 v6, 0, v6
	v_fmac_f32_e32 v2, v171, v5
	v_max_f32_e32 v7, 0, v7
	v_fmac_f32_e32 v2, v170, v6
	v_max_f32_e32 v8, 0, v8
	v_fmac_f32_e32 v2, v169, v7
	v_max_f32_e32 v9, 0, v9
	v_fmac_f32_e32 v2, v168, v8
	v_max_f32_e32 v10, 0, v10
	v_fmac_f32_e32 v2, v167, v9
	v_max_f32_e32 v11, 0, v11
	v_fmac_f32_e32 v2, v166, v10
	v_max_f32_e32 v12, 0, v12
	v_fmac_f32_e32 v2, v165, v11
	v_max_f32_e32 v13, 0, v13
	v_fmac_f32_e32 v2, v164, v12
	v_max_f32_e32 v14, 0, v14
	v_fmac_f32_e32 v2, v163, v13
	v_fmac_f32_e32 v2, v162, v14
	v_max_f32_e32 v3, 0, v15
	v_fmac_f32_e32 v2, v161, v3
	v_max_f32_e32 v3, 0, v16
	v_fmac_f32_e32 v2, v160, v3
	v_max_f32_e32 v3, 0, v17
	v_fmac_f32_e32 v2, v89, v3
	v_not_b32_e32 v3, v2
	v_or_b32_e32 v4, 0x80000000, v2
	v_cmp_gt_i32_e32 vcc, 0, v2
	s_nop 1
	v_cndmask_b32_e32 v2, v4, v3, vcc
	v_cmp_le_u32_e32 vcc, v143, v87
	s_nop 1
	v_cndmask_b32_e32 v242, 0, v2, vcc
	s_branch .Lidxp_w50
.Lidxp_e50:
	s_or_b64 exec, exec, s[82:83]
	v_max_f32_e32 v18, 0, v18
	v_max_f32_e32 v19, 0, v19
	v_fma_f32 v18, v174, v18, 0
	v_max_f32_e32 v20, 0, v20
	v_fmac_f32_e32 v18, v173, v19
	v_max_f32_e32 v21, 0, v21
	v_fmac_f32_e32 v18, v172, v20
	v_max_f32_e32 v22, 0, v22
	v_fmac_f32_e32 v18, v171, v21
	v_max_f32_e32 v23, 0, v23
	v_fmac_f32_e32 v18, v170, v22
	v_max_f32_e32 v24, 0, v24
	v_fmac_f32_e32 v18, v169, v23
	v_max_f32_e32 v25, 0, v25
	v_fmac_f32_e32 v18, v168, v24
	v_max_f32_e32 v26, 0, v26
	v_fmac_f32_e32 v18, v167, v25
	v_max_f32_e32 v27, 0, v27
	v_fmac_f32_e32 v18, v166, v26
	v_max_f32_e32 v28, 0, v28
	v_fmac_f32_e32 v18, v165, v27
	v_max_f32_e32 v29, 0, v29
	v_fmac_f32_e32 v18, v164, v28
	v_max_f32_e32 v30, 0, v30
	v_fmac_f32_e32 v18, v163, v29
	v_fmac_f32_e32 v18, v162, v30
	v_max_f32_e32 v19, 0, v31
	v_fmac_f32_e32 v18, v161, v19
	v_max_f32_e32 v19, 0, v32
	v_fmac_f32_e32 v18, v160, v19
	v_max_f32_e32 v19, 0, v33
	v_fmac_f32_e32 v18, v89, v19
	v_not_b32_e32 v19, v18
	v_or_b32_e32 v20, 0x80000000, v18
	v_cmp_gt_i32_e32 vcc, 0, v18
	s_nop 1
	v_cndmask_b32_e32 v18, v20, v19, vcc
	v_cmp_le_u32_e32 vcc, v144, v87
	s_nop 1
	v_cndmask_b32_e32 v243, 0, v18, vcc
	s_branch .Lidxp_w51
.Lidxp_e51:
	s_or_b64 exec, exec, s[82:83]
	v_max_f32_e32 v2, 0, v2
	v_max_f32_e32 v3, 0, v3
	v_fma_f32 v2, v174, v2, 0
	v_max_f32_e32 v4, 0, v4
	v_fmac_f32_e32 v2, v173, v3
	v_max_f32_e32 v5, 0, v5
	v_fmac_f32_e32 v2, v172, v4
	v_max_f32_e32 v6, 0, v6
	v_fmac_f32_e32 v2, v171, v5
	v_max_f32_e32 v7, 0, v7
	v_fmac_f32_e32 v2, v170, v6
	v_max_f32_e32 v8, 0, v8
	v_fmac_f32_e32 v2, v169, v7
	v_max_f32_e32 v9, 0, v9
	v_fmac_f32_e32 v2, v168, v8
	v_max_f32_e32 v10, 0, v10
	v_fmac_f32_e32 v2, v167, v9
	v_max_f32_e32 v11, 0, v11
	v_fmac_f32_e32 v2, v166, v10
	v_max_f32_e32 v12, 0, v12
	v_fmac_f32_e32 v2, v165, v11
	v_max_f32_e32 v13, 0, v13
	v_fmac_f32_e32 v2, v164, v12
	v_max_f32_e32 v14, 0, v14
	v_fmac_f32_e32 v2, v163, v13
	v_fmac_f32_e32 v2, v162, v14
	v_max_f32_e32 v3, 0, v15
	v_fmac_f32_e32 v2, v161, v3
	v_max_f32_e32 v3, 0, v16
	v_fmac_f32_e32 v2, v160, v3
	v_max_f32_e32 v3, 0, v17
	v_fmac_f32_e32 v2, v89, v3
	v_not_b32_e32 v3, v2
	v_or_b32_e32 v4, 0x80000000, v2
	v_cmp_gt_i32_e32 vcc, 0, v2
	s_nop 1
	v_cndmask_b32_e32 v2, v4, v3, vcc
	v_cmp_le_u32_e32 vcc, v145, v87
	s_nop 1
	v_cndmask_b32_e32 v244, 0, v2, vcc
	s_branch .Lidxp_w52
.Lidxp_e52:
	s_or_b64 exec, exec, s[82:83]
	v_max_f32_e32 v18, 0, v18
	v_max_f32_e32 v19, 0, v19
	v_fma_f32 v18, v174, v18, 0
	v_max_f32_e32 v20, 0, v20
	v_fmac_f32_e32 v18, v173, v19
	v_max_f32_e32 v21, 0, v21
	v_fmac_f32_e32 v18, v172, v20
	v_max_f32_e32 v22, 0, v22
	v_fmac_f32_e32 v18, v171, v21
	v_max_f32_e32 v23, 0, v23
	v_fmac_f32_e32 v18, v170, v22
	v_max_f32_e32 v24, 0, v24
	v_fmac_f32_e32 v18, v169, v23
	v_max_f32_e32 v25, 0, v25
	v_fmac_f32_e32 v18, v168, v24
	v_max_f32_e32 v26, 0, v26
	v_fmac_f32_e32 v18, v167, v25
	v_max_f32_e32 v27, 0, v27
	v_fmac_f32_e32 v18, v166, v26
	v_max_f32_e32 v28, 0, v28
	v_fmac_f32_e32 v18, v165, v27
	v_max_f32_e32 v29, 0, v29
	v_fmac_f32_e32 v18, v164, v28
	v_max_f32_e32 v30, 0, v30
	v_fmac_f32_e32 v18, v163, v29
	v_fmac_f32_e32 v18, v162, v30
	v_max_f32_e32 v19, 0, v31
	v_fmac_f32_e32 v18, v161, v19
	v_max_f32_e32 v19, 0, v32
	v_fmac_f32_e32 v18, v160, v19
	v_max_f32_e32 v19, 0, v33
	v_fmac_f32_e32 v18, v89, v19
	v_not_b32_e32 v19, v18
	v_or_b32_e32 v20, 0x80000000, v18
	v_cmp_gt_i32_e32 vcc, 0, v18
	s_nop 1
	v_cndmask_b32_e32 v18, v20, v19, vcc
	v_cmp_le_u32_e32 vcc, v146, v87
	s_nop 1
	v_cndmask_b32_e32 v245, 0, v18, vcc
	s_branch .Lidxp_w53
.Lidxp_e53:
	s_or_b64 exec, exec, s[82:83]
	v_max_f32_e32 v2, 0, v2
	v_max_f32_e32 v3, 0, v3
	v_fma_f32 v2, v174, v2, 0
	v_max_f32_e32 v4, 0, v4
	v_fmac_f32_e32 v2, v173, v3
	v_max_f32_e32 v5, 0, v5
	v_fmac_f32_e32 v2, v172, v4
	v_max_f32_e32 v6, 0, v6
	v_fmac_f32_e32 v2, v171, v5
	v_max_f32_e32 v7, 0, v7
	v_fmac_f32_e32 v2, v170, v6
	v_max_f32_e32 v8, 0, v8
	v_fmac_f32_e32 v2, v169, v7
	v_max_f32_e32 v9, 0, v9
	v_fmac_f32_e32 v2, v168, v8
	v_max_f32_e32 v10, 0, v10
	v_fmac_f32_e32 v2, v167, v9
	v_max_f32_e32 v11, 0, v11
	v_fmac_f32_e32 v2, v166, v10
	v_max_f32_e32 v12, 0, v12
	v_fmac_f32_e32 v2, v165, v11
	v_max_f32_e32 v13, 0, v13
	v_fmac_f32_e32 v2, v164, v12
	v_max_f32_e32 v14, 0, v14
	v_fmac_f32_e32 v2, v163, v13
	v_fmac_f32_e32 v2, v162, v14
	v_max_f32_e32 v3, 0, v15
	v_fmac_f32_e32 v2, v161, v3
	v_max_f32_e32 v3, 0, v16
	v_fmac_f32_e32 v2, v160, v3
	v_max_f32_e32 v3, 0, v17
	v_fmac_f32_e32 v2, v89, v3
	v_not_b32_e32 v3, v2
	v_or_b32_e32 v4, 0x80000000, v2
	v_cmp_gt_i32_e32 vcc, 0, v2
	s_nop 1
	v_cndmask_b32_e32 v2, v4, v3, vcc
	v_cmp_le_u32_e32 vcc, v147, v87
	s_nop 1
	v_cndmask_b32_e32 v246, 0, v2, vcc
	s_branch .Lidxp_w54
.Lidxp_e54:
	s_or_b64 exec, exec, s[82:83]
	v_max_f32_e32 v18, 0, v18
	v_max_f32_e32 v19, 0, v19
	v_fma_f32 v18, v174, v18, 0
	v_max_f32_e32 v20, 0, v20
	v_fmac_f32_e32 v18, v173, v19
	v_max_f32_e32 v21, 0, v21
	v_fmac_f32_e32 v18, v172, v20
	v_max_f32_e32 v22, 0, v22
	v_fmac_f32_e32 v18, v171, v21
	v_max_f32_e32 v23, 0, v23
	v_fmac_f32_e32 v18, v170, v22
	v_max_f32_e32 v24, 0, v24
	v_fmac_f32_e32 v18, v169, v23
	v_max_f32_e32 v25, 0, v25
	v_fmac_f32_e32 v18, v168, v24
	v_max_f32_e32 v26, 0, v26
	v_fmac_f32_e32 v18, v167, v25
	v_max_f32_e32 v27, 0, v27
	v_fmac_f32_e32 v18, v166, v26
	v_max_f32_e32 v28, 0, v28
	v_fmac_f32_e32 v18, v165, v27
	v_max_f32_e32 v29, 0, v29
	v_fmac_f32_e32 v18, v164, v28
	v_max_f32_e32 v30, 0, v30
	v_fmac_f32_e32 v18, v163, v29
	v_fmac_f32_e32 v18, v162, v30
	v_max_f32_e32 v19, 0, v31
	v_fmac_f32_e32 v18, v161, v19
	v_max_f32_e32 v19, 0, v32
	v_fmac_f32_e32 v18, v160, v19
	v_max_f32_e32 v19, 0, v33
	v_fmac_f32_e32 v18, v89, v19
	v_not_b32_e32 v19, v18
	v_or_b32_e32 v20, 0x80000000, v18
	v_cmp_gt_i32_e32 vcc, 0, v18
	s_nop 1
	v_cndmask_b32_e32 v18, v20, v19, vcc
	v_cmp_le_u32_e32 vcc, v148, v87
	s_nop 1
	v_cndmask_b32_e32 v247, 0, v18, vcc
	s_branch .Lidxp_w55
.Lidxp_e55:
	s_or_b64 exec, exec, s[82:83]
	v_max_f32_e32 v2, 0, v2
	v_max_f32_e32 v3, 0, v3
	v_fma_f32 v2, v174, v2, 0
	v_max_f32_e32 v4, 0, v4
	v_fmac_f32_e32 v2, v173, v3
	v_max_f32_e32 v5, 0, v5
	v_fmac_f32_e32 v2, v172, v4
	v_max_f32_e32 v6, 0, v6
	v_fmac_f32_e32 v2, v171, v5
	v_max_f32_e32 v7, 0, v7
	v_fmac_f32_e32 v2, v170, v6
	v_max_f32_e32 v8, 0, v8
	v_fmac_f32_e32 v2, v169, v7
	v_max_f32_e32 v9, 0, v9
	v_fmac_f32_e32 v2, v168, v8
	v_max_f32_e32 v10, 0, v10
	v_fmac_f32_e32 v2, v167, v9
	v_max_f32_e32 v11, 0, v11
	v_fmac_f32_e32 v2, v166, v10
	v_max_f32_e32 v12, 0, v12
	v_fmac_f32_e32 v2, v165, v11
	v_max_f32_e32 v13, 0, v13
	v_fmac_f32_e32 v2, v164, v12
	v_max_f32_e32 v14, 0, v14
	v_fmac_f32_e32 v2, v163, v13
	v_fmac_f32_e32 v2, v162, v14
	v_max_f32_e32 v3, 0, v15
	v_fmac_f32_e32 v2, v161, v3
	v_max_f32_e32 v3, 0, v16
	v_fmac_f32_e32 v2, v160, v3
	v_max_f32_e32 v3, 0, v17
	v_fmac_f32_e32 v2, v89, v3
	v_not_b32_e32 v3, v2
	v_or_b32_e32 v4, 0x80000000, v2
	v_cmp_gt_i32_e32 vcc, 0, v2
	s_nop 1
	v_cndmask_b32_e32 v2, v4, v3, vcc
	v_cmp_le_u32_e32 vcc, v149, v87
	s_nop 1
	v_cndmask_b32_e32 v248, 0, v2, vcc
	s_branch .Lidxp_w56
.Lidxp_e56:
	s_or_b64 exec, exec, s[82:83]
	v_max_f32_e32 v18, 0, v18
	v_max_f32_e32 v19, 0, v19
	v_fma_f32 v18, v174, v18, 0
	v_max_f32_e32 v20, 0, v20
	v_fmac_f32_e32 v18, v173, v19
	v_max_f32_e32 v21, 0, v21
	v_fmac_f32_e32 v18, v172, v20
	v_max_f32_e32 v22, 0, v22
	v_fmac_f32_e32 v18, v171, v21
	v_max_f32_e32 v23, 0, v23
	v_fmac_f32_e32 v18, v170, v22
	v_max_f32_e32 v24, 0, v24
	v_fmac_f32_e32 v18, v169, v23
	v_max_f32_e32 v25, 0, v25
	v_fmac_f32_e32 v18, v168, v24
	v_max_f32_e32 v26, 0, v26
	v_fmac_f32_e32 v18, v167, v25
	v_max_f32_e32 v27, 0, v27
	v_fmac_f32_e32 v18, v166, v26
	v_max_f32_e32 v28, 0, v28
	v_fmac_f32_e32 v18, v165, v27
	v_max_f32_e32 v29, 0, v29
	v_fmac_f32_e32 v18, v164, v28
	v_max_f32_e32 v30, 0, v30
	v_fmac_f32_e32 v18, v163, v29
	v_fmac_f32_e32 v18, v162, v30
	v_max_f32_e32 v19, 0, v31
	v_fmac_f32_e32 v18, v161, v19
	v_max_f32_e32 v19, 0, v32
	v_fmac_f32_e32 v18, v160, v19
	v_max_f32_e32 v19, 0, v33
	v_fmac_f32_e32 v18, v89, v19
	v_not_b32_e32 v19, v18
	v_or_b32_e32 v20, 0x80000000, v18
	v_cmp_gt_i32_e32 vcc, 0, v18
	s_nop 1
	v_cndmask_b32_e32 v18, v20, v19, vcc
	v_cmp_le_u32_e32 vcc, v150, v87
	s_nop 1
	v_cndmask_b32_e32 v249, 0, v18, vcc
	s_branch .Lidxp_w57
.Lidxp_e57:
	s_or_b64 exec, exec, s[82:83]
	v_max_f32_e32 v2, 0, v2
	v_max_f32_e32 v3, 0, v3
	v_fma_f32 v2, v174, v2, 0
	v_max_f32_e32 v4, 0, v4
	v_fmac_f32_e32 v2, v173, v3
	v_max_f32_e32 v5, 0, v5
	v_fmac_f32_e32 v2, v172, v4
	v_max_f32_e32 v6, 0, v6
	v_fmac_f32_e32 v2, v171, v5
	v_max_f32_e32 v7, 0, v7
	v_fmac_f32_e32 v2, v170, v6
	v_max_f32_e32 v8, 0, v8
	v_fmac_f32_e32 v2, v169, v7
	v_max_f32_e32 v9, 0, v9
	v_fmac_f32_e32 v2, v168, v8
	v_max_f32_e32 v10, 0, v10
	v_fmac_f32_e32 v2, v167, v9
	v_max_f32_e32 v11, 0, v11
	v_fmac_f32_e32 v2, v166, v10
	v_max_f32_e32 v12, 0, v12
	v_fmac_f32_e32 v2, v165, v11
	v_max_f32_e32 v13, 0, v13
	v_fmac_f32_e32 v2, v164, v12
	v_max_f32_e32 v14, 0, v14
	v_fmac_f32_e32 v2, v163, v13
	v_fmac_f32_e32 v2, v162, v14
	v_max_f32_e32 v3, 0, v15
	v_fmac_f32_e32 v2, v161, v3
	v_max_f32_e32 v3, 0, v16
	v_fmac_f32_e32 v2, v160, v3
	v_max_f32_e32 v3, 0, v17
	v_fmac_f32_e32 v2, v89, v3
	v_not_b32_e32 v3, v2
	v_or_b32_e32 v4, 0x80000000, v2
	v_cmp_gt_i32_e32 vcc, 0, v2
	s_nop 1
	v_cndmask_b32_e32 v2, v4, v3, vcc
	v_cmp_le_u32_e32 vcc, v151, v87
	s_nop 1
	v_cndmask_b32_e32 v250, 0, v2, vcc
	s_branch .Lidxp_w58
.Lidxp_e58:
	s_or_b64 exec, exec, s[82:83]
	v_max_f32_e32 v18, 0, v18
	v_max_f32_e32 v19, 0, v19
	v_fma_f32 v18, v174, v18, 0
	v_max_f32_e32 v20, 0, v20
	v_fmac_f32_e32 v18, v173, v19
	v_max_f32_e32 v21, 0, v21
	v_fmac_f32_e32 v18, v172, v20
	v_max_f32_e32 v22, 0, v22
	v_fmac_f32_e32 v18, v171, v21
	v_max_f32_e32 v23, 0, v23
	v_fmac_f32_e32 v18, v170, v22
	v_max_f32_e32 v24, 0, v24
	v_fmac_f32_e32 v18, v169, v23
	v_max_f32_e32 v25, 0, v25
	v_fmac_f32_e32 v18, v168, v24
	v_max_f32_e32 v26, 0, v26
	v_fmac_f32_e32 v18, v167, v25
	v_max_f32_e32 v27, 0, v27
	v_fmac_f32_e32 v18, v166, v26
	v_max_f32_e32 v28, 0, v28
	v_fmac_f32_e32 v18, v165, v27
	v_max_f32_e32 v29, 0, v29
	v_fmac_f32_e32 v18, v164, v28
	v_max_f32_e32 v30, 0, v30
	v_fmac_f32_e32 v18, v163, v29
	v_fmac_f32_e32 v18, v162, v30
	v_max_f32_e32 v19, 0, v31
	v_fmac_f32_e32 v18, v161, v19
	v_max_f32_e32 v19, 0, v32
	v_fmac_f32_e32 v18, v160, v19
	v_max_f32_e32 v19, 0, v33
	v_fmac_f32_e32 v18, v89, v19
	v_not_b32_e32 v19, v18
	v_or_b32_e32 v20, 0x80000000, v18
	v_cmp_gt_i32_e32 vcc, 0, v18
	s_nop 1
	v_cndmask_b32_e32 v18, v20, v19, vcc
	v_cmp_le_u32_e32 vcc, v152, v87
	s_nop 1
	v_cndmask_b32_e32 v199, 0, v18, vcc
	s_branch .Lidxp_w59
.Lidxp_e59:
	s_or_b64 exec, exec, s[82:83]
	v_max_f32_e32 v2, 0, v2
	v_max_f32_e32 v3, 0, v3
	v_fma_f32 v2, v174, v2, 0
	v_max_f32_e32 v4, 0, v4
	v_fmac_f32_e32 v2, v173, v3
	v_max_f32_e32 v5, 0, v5
	v_fmac_f32_e32 v2, v172, v4
	v_max_f32_e32 v6, 0, v6
	v_fmac_f32_e32 v2, v171, v5
	v_max_f32_e32 v7, 0, v7
	v_fmac_f32_e32 v2, v170, v6
	v_max_f32_e32 v8, 0, v8
	v_fmac_f32_e32 v2, v169, v7
	v_max_f32_e32 v9, 0, v9
	v_fmac_f32_e32 v2, v168, v8
	v_max_f32_e32 v10, 0, v10
	v_fmac_f32_e32 v2, v167, v9
	v_max_f32_e32 v11, 0, v11
	v_fmac_f32_e32 v2, v166, v10
	v_max_f32_e32 v12, 0, v12
	v_fmac_f32_e32 v2, v165, v11
	v_max_f32_e32 v13, 0, v13
	v_fmac_f32_e32 v2, v164, v12
	v_max_f32_e32 v14, 0, v14
	v_fmac_f32_e32 v2, v163, v13
	v_fmac_f32_e32 v2, v162, v14
	v_max_f32_e32 v3, 0, v15
	v_fmac_f32_e32 v2, v161, v3
	v_max_f32_e32 v3, 0, v16
	v_fmac_f32_e32 v2, v160, v3
	v_max_f32_e32 v3, 0, v17
	v_fmac_f32_e32 v2, v89, v3
	v_not_b32_e32 v3, v2
	v_or_b32_e32 v4, 0x80000000, v2
	v_cmp_gt_i32_e32 vcc, 0, v2
	s_nop 1
	v_cndmask_b32_e32 v2, v4, v3, vcc
	v_cmp_le_u32_e32 vcc, v153, v87
	s_nop 1
	v_cndmask_b32_e32 v200, 0, v2, vcc
	s_branch .Lidxp_w60
.Lidxp_e60:
	s_or_b64 exec, exec, s[82:83]
	v_max_f32_e32 v18, 0, v18
	v_max_f32_e32 v19, 0, v19
	v_fma_f32 v18, v174, v18, 0
	v_max_f32_e32 v20, 0, v20
	v_fmac_f32_e32 v18, v173, v19
	v_max_f32_e32 v21, 0, v21
	v_fmac_f32_e32 v18, v172, v20
	v_max_f32_e32 v22, 0, v22
	v_fmac_f32_e32 v18, v171, v21
	v_max_f32_e32 v23, 0, v23
	v_fmac_f32_e32 v18, v170, v22
	v_max_f32_e32 v24, 0, v24
	v_fmac_f32_e32 v18, v169, v23
	v_max_f32_e32 v25, 0, v25
	v_fmac_f32_e32 v18, v168, v24
	v_max_f32_e32 v26, 0, v26
	v_fmac_f32_e32 v18, v167, v25
	v_max_f32_e32 v27, 0, v27
	v_fmac_f32_e32 v18, v166, v26
	v_max_f32_e32 v28, 0, v28
	v_fmac_f32_e32 v18, v165, v27
	v_max_f32_e32 v29, 0, v29
	v_fmac_f32_e32 v18, v164, v28
	v_max_f32_e32 v30, 0, v30
	v_fmac_f32_e32 v18, v163, v29
	v_fmac_f32_e32 v18, v162, v30
	v_max_f32_e32 v19, 0, v31
	v_fmac_f32_e32 v18, v161, v19
	v_max_f32_e32 v19, 0, v32
	v_fmac_f32_e32 v18, v160, v19
	v_max_f32_e32 v19, 0, v33
	v_fmac_f32_e32 v18, v89, v19
	v_not_b32_e32 v19, v18
	v_or_b32_e32 v20, 0x80000000, v18
	v_cmp_gt_i32_e32 vcc, 0, v18
	s_nop 1
	v_cndmask_b32_e32 v18, v20, v19, vcc
	v_cmp_le_u32_e32 vcc, v154, v87
	s_nop 1
	v_cndmask_b32_e32 v207, 0, v18, vcc
	s_branch .Lidxp_w61
.Lidxp_e61:
	s_or_b64 exec, exec, s[82:83]
	v_max_f32_e32 v2, 0, v2
	v_max_f32_e32 v3, 0, v3
	v_fma_f32 v2, v174, v2, 0
	v_max_f32_e32 v4, 0, v4
	v_fmac_f32_e32 v2, v173, v3
	v_max_f32_e32 v5, 0, v5
	v_fmac_f32_e32 v2, v172, v4
	v_max_f32_e32 v6, 0, v6
	v_fmac_f32_e32 v2, v171, v5
	v_max_f32_e32 v7, 0, v7
	v_fmac_f32_e32 v2, v170, v6
	v_max_f32_e32 v8, 0, v8
	v_fmac_f32_e32 v2, v169, v7
	v_max_f32_e32 v9, 0, v9
	v_fmac_f32_e32 v2, v168, v8
	v_max_f32_e32 v10, 0, v10
	v_fmac_f32_e32 v2, v167, v9
	v_max_f32_e32 v11, 0, v11
	v_fmac_f32_e32 v2, v166, v10
	v_max_f32_e32 v12, 0, v12
	v_fmac_f32_e32 v2, v165, v11
	v_max_f32_e32 v13, 0, v13
	v_fmac_f32_e32 v2, v164, v12
	v_max_f32_e32 v14, 0, v14
	v_fmac_f32_e32 v2, v163, v13
	v_fmac_f32_e32 v2, v162, v14
	v_max_f32_e32 v3, 0, v15
	v_fmac_f32_e32 v2, v161, v3
	v_max_f32_e32 v3, 0, v16
	v_fmac_f32_e32 v2, v160, v3
	v_max_f32_e32 v3, 0, v17
	v_fmac_f32_e32 v2, v89, v3
	v_not_b32_e32 v3, v2
	v_or_b32_e32 v4, 0x80000000, v2
	v_cmp_gt_i32_e32 vcc, 0, v2
	s_nop 1
	v_cndmask_b32_e32 v2, v4, v3, vcc
	v_cmp_le_u32_e32 vcc, v155, v87
	s_nop 1
	v_cndmask_b32_e32 v208, 0, v2, vcc
	s_branch .Lidxp_w62
.Lidxp_e62:
	s_or_b64 exec, exec, s[82:83]
	v_max_f32_e32 v18, 0, v18
	v_max_f32_e32 v19, 0, v19
	v_fma_f32 v18, v174, v18, 0
	v_max_f32_e32 v20, 0, v20
	v_fmac_f32_e32 v18, v173, v19
	v_max_f32_e32 v21, 0, v21
	v_fmac_f32_e32 v18, v172, v20
	v_max_f32_e32 v22, 0, v22
	v_fmac_f32_e32 v18, v171, v21
	v_max_f32_e32 v23, 0, v23
	v_fmac_f32_e32 v18, v170, v22
	v_max_f32_e32 v24, 0, v24
	v_fmac_f32_e32 v18, v169, v23
	v_max_f32_e32 v25, 0, v25
	v_fmac_f32_e32 v18, v168, v24
	v_max_f32_e32 v26, 0, v26
	v_fmac_f32_e32 v18, v167, v25
	v_max_f32_e32 v27, 0, v27
	v_fmac_f32_e32 v18, v166, v26
	v_max_f32_e32 v28, 0, v28
	v_fmac_f32_e32 v18, v165, v27
	v_max_f32_e32 v29, 0, v29
	v_fmac_f32_e32 v18, v164, v28
	v_max_f32_e32 v30, 0, v30
	v_fmac_f32_e32 v18, v163, v29
	v_fmac_f32_e32 v18, v162, v30
	v_max_f32_e32 v19, 0, v31
	v_fmac_f32_e32 v18, v161, v19
	v_max_f32_e32 v19, 0, v32
	v_fmac_f32_e32 v18, v160, v19
	v_max_f32_e32 v19, 0, v33
	v_fmac_f32_e32 v18, v89, v19
	v_not_b32_e32 v19, v18
	v_or_b32_e32 v20, 0x80000000, v18
	v_cmp_gt_i32_e32 vcc, 0, v18
	s_nop 1
	v_cndmask_b32_e32 v18, v20, v19, vcc
	v_cmp_le_u32_e32 vcc, v156, v87
	s_nop 1
	v_cndmask_b32_e32 v210, 0, v18, vcc
	s_branch .Lidxp_w63
.Lidxp_e63:
	s_or_b64 exec, exec, s[82:83]
	v_max_f32_e32 v2, 0, v2
	v_max_f32_e32 v3, 0, v3
	v_fma_f32 v2, v174, v2, 0
	v_max_f32_e32 v4, 0, v4
	v_fmac_f32_e32 v2, v173, v3
	v_max_f32_e32 v5, 0, v5
	v_fmac_f32_e32 v2, v172, v4
	v_max_f32_e32 v6, 0, v6
	v_fmac_f32_e32 v2, v171, v5
	v_max_f32_e32 v7, 0, v7
	v_fmac_f32_e32 v2, v170, v6
	v_max_f32_e32 v8, 0, v8
	v_fmac_f32_e32 v2, v169, v7
	v_max_f32_e32 v9, 0, v9
	v_fmac_f32_e32 v2, v168, v8
	v_max_f32_e32 v10, 0, v10
	v_fmac_f32_e32 v2, v167, v9
	v_max_f32_e32 v11, 0, v11
	v_fmac_f32_e32 v2, v166, v10
	v_max_f32_e32 v12, 0, v12
	v_fmac_f32_e32 v2, v165, v11
	v_max_f32_e32 v13, 0, v13
	v_fmac_f32_e32 v2, v164, v12
	v_max_f32_e32 v14, 0, v14
	v_fmac_f32_e32 v2, v163, v13
	v_fmac_f32_e32 v2, v162, v14
	v_max_f32_e32 v3, 0, v15
	v_fmac_f32_e32 v2, v161, v3
	v_max_f32_e32 v3, 0, v16
	v_fmac_f32_e32 v2, v160, v3
	v_max_f32_e32 v3, 0, v17
	v_fmac_f32_e32 v2, v89, v3
	v_not_b32_e32 v3, v2
	v_or_b32_e32 v4, 0x80000000, v2
	v_cmp_gt_i32_e32 vcc, 0, v2
	s_nop 1
	v_cndmask_b32_e32 v2, v4, v3, vcc
	v_cmp_le_u32_e32 vcc, v157, v87
	s_nop 1
	v_cndmask_b32_e32 v70, 0, v2, vcc
	s_branch .Lidxp_end
.Lidxp_w2:
	s_xor_b64 s[80:81], s[82:83], -1
	v_mov_b32_e32 v176, 0
.Lidxp_w3:
	v_mov_b32_e32 v179, 0
.Lidxp_w4:
	v_mov_b32_e32 v180, 0
.Lidxp_w5:
	v_mov_b32_e32 v181, 0
.Lidxp_w6:
	v_mov_b32_e32 v182, 0
.Lidxp_w7:
	v_mov_b32_e32 v183, 0
.Lidxp_w8:
	v_cmp_gt_u32_e64 s[74:75], s33, v177
	v_mov_b32_e32 v184, 0
.Lidxp_w9:
	v_mov_b32_e32 v185, 0
.Lidxp_w10:
	v_mov_b32_e32 v186, 0
.Lidxp_w11:
	v_mov_b32_e32 v187, 0
.Lidxp_w12:
	v_mov_b32_e32 v188, 0
.Lidxp_w13:
	v_mov_b32_e32 v189, 0
.Lidxp_w14:
	v_mov_b32_e32 v190, 0
.Lidxp_w15:
	v_mov_b32_e32 v191, 0
.Lidxp_w16:
	v_mov_b32_e32 v192, 0
.Lidxp_w17:
	v_mov_b32_e32 v193, 0
.Lidxp_w18:
	v_mov_b32_e32 v194, 0
.Lidxp_w19:
	v_mov_b32_e32 v195, 0
.Lidxp_w20:
	v_mov_b32_e32 v196, 0
.Lidxp_w21:
	v_mov_b32_e32 v197, 0
.Lidxp_w22:
	v_mov_b32_e32 v216, 0
.Lidxp_w23:
	v_mov_b32_e32 v217, 0
.Lidxp_w24:
	v_mov_b32_e32 v218, 0
.Lidxp_w25:
	v_mov_b32_e32 v219, 0
.Lidxp_w26:
	v_mov_b32_e32 v220, 0
.Lidxp_w27:
	v_mov_b32_e32 v221, 0
.Lidxp_w28:
	v_mov_b32_e32 v222, 0
.Lidxp_w29:
	v_mov_b32_e32 v223, 0
.Lidxp_w30:
	v_mov_b32_e32 v224, 0
.Lidxp_w31:
	v_mov_b32_e32 v225, 0
.Lidxp_w32:
	v_mov_b32_e32 v226, 0
.Lidxp_w33:
	v_mov_b32_e32 v227, 0
.Lidxp_w34:
	v_mov_b32_e32 v228, 0
.Lidxp_w35:
	v_mov_b32_e32 v229, 0
.Lidxp_w36:
	v_mov_b32_e32 v230, 0
.Lidxp_w37:
	v_mov_b32_e32 v231, 0
.Lidxp_w38:
	v_mov_b32_e32 v232, 0
.Lidxp_w39:
	v_mov_b32_e32 v233, 0
.Lidxp_w40:
	v_mov_b32_e32 v234, 0
.Lidxp_w41:
	v_mov_b32_e32 v235, 0
.Lidxp_w42:
	v_mov_b32_e32 v236, 0
.Lidxp_w43:
	v_mov_b32_e32 v237, 0
.Lidxp_w44:
	v_mov_b32_e32 v238, 0
.Lidxp_w45:
	v_mov_b32_e32 v239, 0
.Lidxp_w46:
	v_mov_b32_e32 v240, 0
.Lidxp_w47:
	v_mov_b32_e32 v241, 0
.Lidxp_w48:
	v_mov_b32_e32 v242, 0
.Lidxp_w49:
	v_mov_b32_e32 v243, 0
.Lidxp_w50:
	v_mov_b32_e32 v244, 0
.Lidxp_w51:
	v_mov_b32_e32 v245, 0
.Lidxp_w52:
	v_mov_b32_e32 v246, 0
.Lidxp_w53:
	v_mov_b32_e32 v247, 0
.Lidxp_w54:
	v_mov_b32_e32 v248, 0
.Lidxp_w55:
	v_mov_b32_e32 v249, 0
.Lidxp_w56:
	v_mov_b32_e32 v250, 0
.Lidxp_w57:
	v_mov_b32_e32 v199, 0
.Lidxp_w58:
	v_mov_b32_e32 v200, 0
.Lidxp_w59:
	v_mov_b32_e32 v207, 0
.Lidxp_w60:
	v_mov_b32_e32 v208, 0
.Lidxp_w61:
	v_mov_b32_e32 v210, 0
.Lidxp_w62:
	v_lshrrev_b32_e32 v201, 5, v177
	v_mov_b32_e32 v70, 0
.Lidxp_w63:
	v_mov_b32_e32 v66, 0
	v_mov_b32_e32 v18, 0
.Lidxp_end:
	v_mov_b32_e32 v3, v81
	v_mov_b32_e32 v2, 31
	v_readfirstlane_b32 s100, v177
	s_nop 1
	s_add_i32 s100, s100, 1
	s_lshr_b32 m0, s100, 5
	s_branch .LBB0_654
